# GEMM K-loop: uniform counted vmcnt(10) per load phase (5-phase DMA flight) + tail waits; removed conservative vmcnt(0) in tile prologue/ssx/attention item top; rope+qk-norm tables staged in LDS
# speedup vs baseline: 1.0069x; 1.0069x over previous
.LBB0_62:
	v_and_b32_e32 v1, 15, v0
	v_and_b32_e32 v2, 48, v0
	v_lshlrev_b32_e32 v1, 6, v1
	v_lshlrev_b32_e32 v0, 2, v0
	v_or_b32_e32 v3, v1, v2
	v_and_b32_e32 v0, 32, v0
	s_lshl_b32 s7, s37, 13
	v_bitop3_b32 v148, v3, s7, v0 bitop3:0xde
	s_lshl_b32 s7, s9, 6
	v_bitop3_b32 v1, v1, v0, v2 bitop3:0x36
	s_and_b32 s7, s7, 0x3000
	v_or_b32_e32 v0, s7, v1
	s_add_u32 s7, s94, s14
	s_addc_u32 s20, s95, s15
	s_add_u32 s21, s31, s38
	s_addc_u32 s26, s34, s55
	s_add_u32 s2, s94, s2
	s_addc_u32 s3, s95, s3
	s_add_u32 s18, s31, s18
	s_addc_u32 s19, s34, s19
	v_or_b32_e32 v149, 0x10000, v0
	v_or_b32_e32 v147, 0x14000, v0
	v_or_b32_e32 v145, 0x18000, v0
	v_or_b32_e32 v143, 0x1c000, v0
	s_add_u32 s27, s7, 0x100
	v_mov_b32_e32 v0, 0
	v_add_u32_e32 v146, 0x4000, v148
	v_add_u32_e32 v144, 0x8000, v148
	v_add_u32_e32 v142, 0xc000, v148
	s_addc_u32 s28, s20, 0
	s_mov_b32 s29, -2
	s_mov_b64 s[14:15], 0
	v_mov_b32_e32 v1, v0
	v_mov_b32_e32 v2, v0
	v_mov_b32_e32 v3, v0
	v_mov_b32_e32 v4, v0
	v_mov_b32_e32 v5, v0
	v_mov_b32_e32 v6, v0
	v_mov_b32_e32 v7, v0
	v_mov_b32_e32 v8, v0
	v_mov_b32_e32 v9, v0
	v_mov_b32_e32 v10, v0
	v_mov_b32_e32 v11, v0
	v_mov_b32_e32 v12, v0
	v_mov_b32_e32 v13, v0
	v_mov_b32_e32 v14, v0
	v_mov_b32_e32 v15, v0
	v_mov_b32_e32 v16, v0
	v_mov_b32_e32 v17, v0
	v_mov_b32_e32 v18, v0
	v_mov_b32_e32 v19, v0
	v_mov_b32_e32 v20, v0
	v_mov_b32_e32 v21, v0
	v_mov_b32_e32 v22, v0
	v_mov_b32_e32 v23, v0
	v_mov_b32_e32 v24, v0
	v_mov_b32_e32 v25, v0
	v_mov_b32_e32 v26, v0
	v_mov_b32_e32 v27, v0
	v_mov_b32_e32 v28, v0
	v_mov_b32_e32 v29, v0
	v_mov_b32_e32 v30, v0
	v_mov_b32_e32 v31, v0
	v_mov_b32_e32 v32, v0
	v_mov_b32_e32 v33, v0
	v_mov_b32_e32 v34, v0
	v_mov_b32_e32 v35, v0
	v_mov_b32_e32 v36, v0
	v_mov_b32_e32 v37, v0
	v_mov_b32_e32 v38, v0
	v_mov_b32_e32 v39, v0
	v_mov_b32_e32 v40, v0
	v_mov_b32_e32 v41, v0
	v_mov_b32_e32 v42, v0
	v_mov_b32_e32 v43, v0
	v_mov_b32_e32 v44, v0
	v_mov_b32_e32 v45, v0
	v_mov_b32_e32 v46, v0
	v_mov_b32_e32 v47, v0
	v_mov_b32_e32 v48, v0
	v_mov_b32_e32 v49, v0
	v_mov_b32_e32 v50, v0
	v_mov_b32_e32 v51, v0
	v_mov_b32_e32 v52, v0
	v_mov_b32_e32 v53, v0
	v_mov_b32_e32 v54, v0
	v_mov_b32_e32 v55, v0
	v_mov_b32_e32 v56, v0
	v_mov_b32_e32 v57, v0
	v_mov_b32_e32 v58, v0
	v_mov_b32_e32 v59, v0
	v_mov_b32_e32 v60, v0
	v_mov_b32_e32 v61, v0
	v_mov_b32_e32 v62, v0
	v_mov_b32_e32 v63, v0
	s_nop 0
	v_mov_b32_e32 v64, v0
	v_mov_b32_e32 v65, v0
	v_mov_b32_e32 v66, v0
	v_mov_b32_e32 v67, v0
	v_mov_b32_e32 v68, v0
	v_mov_b32_e32 v69, v0
	v_mov_b32_e32 v70, v0
	v_mov_b32_e32 v71, v0
	v_mov_b32_e32 v72, v0
	v_mov_b32_e32 v73, v0
	v_mov_b32_e32 v74, v0
	v_mov_b32_e32 v75, v0
	v_mov_b32_e32 v76, v0
	v_mov_b32_e32 v77, v0
	v_mov_b32_e32 v78, v0
	v_mov_b32_e32 v79, v0
	v_mov_b32_e32 v80, v0
	v_mov_b32_e32 v81, v0
	v_mov_b32_e32 v82, v0
	v_mov_b32_e32 v83, v0
	v_mov_b32_e32 v84, v0
	v_mov_b32_e32 v85, v0
	v_mov_b32_e32 v86, v0
	v_mov_b32_e32 v87, v0
	v_mov_b32_e32 v88, v0
	v_mov_b32_e32 v89, v0
	v_mov_b32_e32 v90, v0
	v_mov_b32_e32 v91, v0
	v_mov_b32_e32 v92, v0
	v_mov_b32_e32 v93, v0
	v_mov_b32_e32 v94, v0
	v_mov_b32_e32 v95, v0
	v_mov_b32_e32 v96, v0
	v_mov_b32_e32 v97, v0
	v_mov_b32_e32 v98, v0
	v_mov_b32_e32 v99, v0
	v_mov_b32_e32 v100, v0
	v_mov_b32_e32 v101, v0
	v_mov_b32_e32 v102, v0
	v_mov_b32_e32 v103, v0
	v_mov_b32_e32 v104, v0
	v_mov_b32_e32 v105, v0
	v_mov_b32_e32 v106, v0
	v_mov_b32_e32 v107, v0
	v_mov_b32_e32 v108, v0
	v_mov_b32_e32 v109, v0
	v_mov_b32_e32 v110, v0
	v_mov_b32_e32 v111, v0
	v_mov_b32_e32 v112, v0
	v_mov_b32_e32 v113, v0
	v_mov_b32_e32 v114, v0
	v_mov_b32_e32 v115, v0
	v_mov_b32_e32 v116, v0
	v_mov_b32_e32 v117, v0
	v_mov_b32_e32 v118, v0
	v_mov_b32_e32 v119, v0
	v_mov_b32_e32 v120, v0
	v_mov_b32_e32 v121, v0
	v_mov_b32_e32 v122, v0
	v_mov_b32_e32 v123, v0
	v_mov_b32_e32 v124, v0
	v_mov_b32_e32 v125, v0
	v_mov_b32_e32 v126, v0
	v_mov_b32_e32 v127, v0
.LBB0_63:
	ds_read_b128 v[150:153], v149 offset:0
	ds_read_b128 v[158:161], v149 offset:1024
	ds_read_b128 v[162:165], v149 offset:2048
	ds_read_b128 v[166:169], v149 offset:3072
	s_add_u32 s37, s7, s14
	s_addc_u32 s39, s20, s15
	s_add_u32 s38, s37, 0x80
	v_add_u32_e32 v156, 0xc000, v135
	s_addc_u32 s39, s39, 0
	v_readfirstlane_b32 s37, v156
	v_add_u32_e32 v157, 0xe000, v135
	v_lshl_add_u64 v[154:155], s[38:39], 0, v[130:131]
	s_mov_b32 m0, s37
	v_readfirstlane_b32 s37, v157
	ds_read_b128 v[170:173], v148 offset:0
	ds_read_b128 v[178:181], v148 offset:1024
	ds_read_b128 v[182:185], v148 offset:2048
	ds_read_b128 v[186:189], v148 offset:3072
	ds_read_b128 v[190:193], v148 offset:4096
	ds_read_b128 v[194:197], v148 offset:5120
	ds_read_b128 v[198:201], v148 offset:6144
	ds_read_b128 v[202:205], v148 offset:7168
	global_load_lds_dwordx4 v[154:155], off
	v_lshl_add_u64 v[154:155], s[38:39], 0, v[128:129]
	s_mov_b32 m0, s37
	s_nop 0
	global_load_lds_dwordx4 v[154:155], off
	s_waitcnt vmcnt(10)
	s_waitcnt lgkmcnt(8)
	s_barrier
	s_waitcnt lgkmcnt(0)
	s_waitcnt lgkmcnt(0)
	s_setprio 1
	v_mfma_f32_16x16x32_bf16 v[124:127], v[150:153], v[170:173], v[124:127]
	v_mfma_f32_16x16x32_bf16 v[120:123], v[162:165], v[170:173], v[120:123]
	v_mfma_f32_16x16x32_bf16 v[116:119], v[150:153], v[182:185], v[116:119]
	v_mfma_f32_16x16x32_bf16 v[112:115], v[162:165], v[182:185], v[112:115]
	v_mfma_f32_16x16x32_bf16 v[108:111], v[150:153], v[190:193], v[108:111]
	v_mfma_f32_16x16x32_bf16 v[104:107], v[162:165], v[190:193], v[104:107]
	v_mfma_f32_16x16x32_bf16 v[100:103], v[150:153], v[198:201], v[100:103]
	v_mfma_f32_16x16x32_bf16 v[96:99], v[162:165], v[198:201], v[96:99]
	v_mfma_f32_16x16x32_bf16 v[124:127], v[158:161], v[178:181], v[124:127]
	v_mfma_f32_16x16x32_bf16 v[120:123], v[166:169], v[178:181], v[120:123]
	v_mfma_f32_16x16x32_bf16 v[116:119], v[158:161], v[186:189], v[116:119]
	v_mfma_f32_16x16x32_bf16 v[112:115], v[166:169], v[186:189], v[112:115]
	v_mfma_f32_16x16x32_bf16 v[108:111], v[158:161], v[194:197], v[108:111]
	v_mfma_f32_16x16x32_bf16 v[104:107], v[166:169], v[194:197], v[104:107]
	v_mfma_f32_16x16x32_bf16 v[100:103], v[158:161], v[202:205], v[100:103]
	v_mfma_f32_16x16x32_bf16 v[96:99], v[166:169], v[202:205], v[96:99]
	s_setprio 0
	s_barrier
	s_add_u32 s37, s21, s14
	s_addc_u32 s40, s26, s15
	s_add_u32 s38, s37, 0x100
	s_addc_u32 s39, s40, 0
	v_readfirstlane_b32 s41, v141
	v_lshl_add_u64 v[154:155], s[38:39], 0, v[176:177]
	s_mov_b32 m0, s41
	ds_read_b128 v[206:209], v147 offset:0
	ds_read_b128 v[210:213], v147 offset:1024
	ds_read_b128 v[214:217], v147 offset:2048
	ds_read_b128 v[218:221], v147 offset:3072
	s_nop 0
	global_load_lds_dwordx4 v[154:155], off
	v_lshl_add_u64 v[154:155], s[38:39], 0, v[132:133]
	v_readfirstlane_b32 s38, v140
	s_mov_b32 m0, s38
	s_nop 0
	global_load_lds_dwordx4 v[154:155], off
	s_waitcnt vmcnt(10)
	s_barrier
	s_waitcnt lgkmcnt(0)
	s_setprio 1
	v_mfma_f32_16x16x32_bf16 v[92:95], v[206:209], v[170:173], v[92:95]
	v_mfma_f32_16x16x32_bf16 v[88:91], v[214:217], v[170:173], v[88:91]
	v_mfma_f32_16x16x32_bf16 v[84:87], v[206:209], v[182:185], v[84:87]
	v_mfma_f32_16x16x32_bf16 v[80:83], v[214:217], v[182:185], v[80:83]
	v_mfma_f32_16x16x32_bf16 v[76:79], v[206:209], v[190:193], v[76:79]
	v_mfma_f32_16x16x32_bf16 v[72:75], v[214:217], v[190:193], v[72:75]
	v_mfma_f32_16x16x32_bf16 v[68:71], v[206:209], v[198:201], v[68:71]
	v_mfma_f32_16x16x32_bf16 v[64:67], v[214:217], v[198:201], v[64:67]
	v_mfma_f32_16x16x32_bf16 v[92:95], v[210:213], v[178:181], v[92:95]
	v_mfma_f32_16x16x32_bf16 v[88:91], v[218:221], v[178:181], v[88:91]
	v_mfma_f32_16x16x32_bf16 v[84:87], v[210:213], v[186:189], v[84:87]
	v_mfma_f32_16x16x32_bf16 v[80:83], v[218:221], v[186:189], v[80:83]
	v_mfma_f32_16x16x32_bf16 v[76:79], v[210:213], v[194:197], v[76:79]
	v_mfma_f32_16x16x32_bf16 v[72:75], v[218:221], v[194:197], v[72:75]
	v_mfma_f32_16x16x32_bf16 v[68:71], v[210:213], v[202:205], v[68:71]
	v_mfma_f32_16x16x32_bf16 v[64:67], v[218:221], v[202:205], v[64:67]
	s_setprio 0
	s_add_u32 s41, s2, s14
	s_addc_u32 s42, s3, s15
	s_add_u32 s38, s41, 0x100
	s_addc_u32 s39, s42, 0
	v_readfirstlane_b32 s43, v135
	v_lshl_add_u64 v[154:155], s[38:39], 0, v[130:131]
	s_mov_b32 m0, s43
	s_barrier
	ds_read_b128 v[170:173], v146 offset:0
	ds_read_b128 v[178:181], v146 offset:1024
	ds_read_b128 v[182:185], v146 offset:2048
	ds_read_b128 v[186:189], v146 offset:3072
	ds_read_b128 v[190:193], v146 offset:4096
	ds_read_b128 v[194:197], v146 offset:5120
	ds_read_b128 v[198:201], v146 offset:6144
	ds_read_b128 v[202:205], v146 offset:7168
	global_load_lds_dwordx4 v[154:155], off
	v_lshl_add_u64 v[154:155], s[38:39], 0, v[128:129]
	v_readfirstlane_b32 s38, v136
	s_mov_b32 m0, s38
	s_nop 0
	global_load_lds_dwordx4 v[154:155], off
	s_waitcnt vmcnt(10)
	s_barrier
	s_waitcnt lgkmcnt(0)
	s_setprio 1
	v_mfma_f32_16x16x32_bf16 v[60:63], v[150:153], v[170:173], v[60:63]
	v_mfma_f32_16x16x32_bf16 v[56:59], v[162:165], v[170:173], v[56:59]
	v_mfma_f32_16x16x32_bf16 v[52:55], v[150:153], v[182:185], v[52:55]
	v_mfma_f32_16x16x32_bf16 v[48:51], v[162:165], v[182:185], v[48:51]
	v_mfma_f32_16x16x32_bf16 v[44:47], v[150:153], v[190:193], v[44:47]
	v_mfma_f32_16x16x32_bf16 v[40:43], v[162:165], v[190:193], v[40:43]
	v_mfma_f32_16x16x32_bf16 v[36:39], v[150:153], v[198:201], v[36:39]
	v_mfma_f32_16x16x32_bf16 v[32:35], v[162:165], v[198:201], v[32:35]
	v_mfma_f32_16x16x32_bf16 v[60:63], v[158:161], v[178:181], v[60:63]
	v_mfma_f32_16x16x32_bf16 v[56:59], v[166:169], v[178:181], v[56:59]
	v_mfma_f32_16x16x32_bf16 v[52:55], v[158:161], v[186:189], v[52:55]
	v_mfma_f32_16x16x32_bf16 v[48:51], v[166:169], v[186:189], v[48:51]
	v_mfma_f32_16x16x32_bf16 v[44:47], v[158:161], v[194:197], v[44:47]
	v_mfma_f32_16x16x32_bf16 v[40:43], v[166:169], v[194:197], v[40:43]
	v_mfma_f32_16x16x32_bf16 v[36:39], v[158:161], v[202:205], v[36:39]
	v_mfma_f32_16x16x32_bf16 v[32:35], v[166:169], v[202:205], v[32:35]
	s_setprio 0
	s_barrier
	s_add_u32 s43, s18, s14
	s_addc_u32 s44, s19, s15
	s_add_u32 s38, s43, 0x100
	s_addc_u32 s39, s44, 0
	v_readfirstlane_b32 s45, v139
	v_lshl_add_u64 v[150:151], s[38:39], 0, v[176:177]
	s_mov_b32 m0, s45
	s_nop 0
	global_load_lds_dwordx4 v[150:151], off
	v_lshl_add_u64 v[150:151], s[38:39], 0, v[132:133]
	v_readfirstlane_b32 s38, v138
	s_mov_b32 m0, s38
	s_nop 0
	global_load_lds_dwordx4 v[150:151], off
	s_waitcnt vmcnt(10)
	s_barrier
	s_setprio 1
	v_mfma_f32_16x16x32_bf16 v[28:31], v[206:209], v[170:173], v[28:31]
	v_mfma_f32_16x16x32_bf16 v[24:27], v[214:217], v[170:173], v[24:27]
	v_mfma_f32_16x16x32_bf16 v[20:23], v[206:209], v[182:185], v[20:23]
	v_mfma_f32_16x16x32_bf16 v[16:19], v[214:217], v[182:185], v[16:19]
	v_mfma_f32_16x16x32_bf16 v[12:15], v[206:209], v[190:193], v[12:15]
	v_mfma_f32_16x16x32_bf16 v[8:11], v[214:217], v[190:193], v[8:11]
	v_mfma_f32_16x16x32_bf16 v[4:7], v[206:209], v[198:201], v[4:7]
	v_mfma_f32_16x16x32_bf16 v[0:3], v[214:217], v[198:201], v[0:3]
	v_mfma_f32_16x16x32_bf16 v[28:31], v[210:213], v[178:181], v[28:31]
	v_mfma_f32_16x16x32_bf16 v[24:27], v[218:221], v[178:181], v[24:27]
	v_mfma_f32_16x16x32_bf16 v[20:23], v[210:213], v[186:189], v[20:23]
	v_mfma_f32_16x16x32_bf16 v[16:19], v[218:221], v[186:189], v[16:19]
	v_mfma_f32_16x16x32_bf16 v[12:15], v[210:213], v[194:197], v[12:15]
	v_mfma_f32_16x16x32_bf16 v[8:11], v[218:221], v[194:197], v[8:11]
	v_mfma_f32_16x16x32_bf16 v[4:7], v[210:213], v[202:205], v[4:7]
	v_mfma_f32_16x16x32_bf16 v[0:3], v[218:221], v[202:205], v[0:3]
	s_setprio 0
	s_barrier
	ds_read_b128 v[158:161], v145 offset:0
	ds_read_b128 v[162:165], v145 offset:1024
	ds_read_b128 v[166:169], v145 offset:2048
	ds_read_b128 v[170:173], v145 offset:3072
	s_add_u32 s38, s27, s14
	s_addc_u32 s39, s28, s15
	v_readfirstlane_b32 s45, v137
	v_lshl_add_u64 v[150:151], s[38:39], 0, v[130:131]
	s_mov_b32 m0, s45
	ds_read_b128 v[152:155], v144 offset:0
	ds_read_b128 v[178:181], v144 offset:1024
	ds_read_b128 v[182:185], v144 offset:2048
	ds_read_b128 v[186:189], v144 offset:3072
	ds_read_b128 v[190:193], v144 offset:4096
	ds_read_b128 v[194:197], v144 offset:5120
	ds_read_b128 v[198:201], v144 offset:6144
	ds_read_b128 v[202:205], v144 offset:7168
	s_nop 0
	global_load_lds_dwordx4 v[150:151], off
	v_lshl_add_u64 v[150:151], s[38:39], 0, v[128:129]
	v_readfirstlane_b32 s38, v134
	s_mov_b32 m0, s38
	s_nop 0
	global_load_lds_dwordx4 v[150:151], off
	s_waitcnt vmcnt(10)
	s_waitcnt lgkmcnt(8)
	s_barrier
	s_waitcnt lgkmcnt(0)
	s_waitcnt lgkmcnt(0)
	s_setprio 1
	v_mfma_f32_16x16x32_bf16 v[124:127], v[158:161], v[152:155], v[124:127]
	v_mfma_f32_16x16x32_bf16 v[120:123], v[166:169], v[152:155], v[120:123]
	v_mfma_f32_16x16x32_bf16 v[116:119], v[158:161], v[182:185], v[116:119]
	v_mfma_f32_16x16x32_bf16 v[112:115], v[166:169], v[182:185], v[112:115]
	v_mfma_f32_16x16x32_bf16 v[108:111], v[158:161], v[190:193], v[108:111]
	v_mfma_f32_16x16x32_bf16 v[104:107], v[166:169], v[190:193], v[104:107]
	v_mfma_f32_16x16x32_bf16 v[100:103], v[158:161], v[198:201], v[100:103]
	v_mfma_f32_16x16x32_bf16 v[96:99], v[166:169], v[198:201], v[96:99]
	v_mfma_f32_16x16x32_bf16 v[124:127], v[162:165], v[178:181], v[124:127]
	v_mfma_f32_16x16x32_bf16 v[120:123], v[170:173], v[178:181], v[120:123]
	v_mfma_f32_16x16x32_bf16 v[116:119], v[162:165], v[186:189], v[116:119]
	v_mfma_f32_16x16x32_bf16 v[112:115], v[170:173], v[186:189], v[112:115]
	v_mfma_f32_16x16x32_bf16 v[108:111], v[162:165], v[194:197], v[108:111]
	v_mfma_f32_16x16x32_bf16 v[104:107], v[170:173], v[194:197], v[104:107]
	v_mfma_f32_16x16x32_bf16 v[100:103], v[162:165], v[202:205], v[100:103]
	v_mfma_f32_16x16x32_bf16 v[96:99], v[170:173], v[202:205], v[96:99]
	s_setprio 0
	s_barrier
	s_add_u32 s38, s37, 0x180
	v_add_u32_e32 v150, 0x18000, v135
	s_addc_u32 s39, s40, 0
	v_readfirstlane_b32 s37, v150
	v_add_u32_e32 v151, 0x1a000, v135
	v_lshl_add_u64 v[174:175], s[38:39], 0, v[176:177]
	s_mov_b32 m0, s37
	v_readfirstlane_b32 s37, v151
	ds_read_b128 v[206:209], v143 offset:0
	ds_read_b128 v[210:213], v143 offset:1024
	ds_read_b128 v[214:217], v143 offset:2048
	ds_read_b128 v[218:221], v143 offset:3072
	global_load_lds_dwordx4 v[174:175], off
	v_lshl_add_u64 v[174:175], s[38:39], 0, v[132:133]
	s_mov_b32 m0, s37
	s_nop 0
	global_load_lds_dwordx4 v[174:175], off
	s_waitcnt vmcnt(10)
	s_barrier
	s_waitcnt lgkmcnt(0)
	s_setprio 1
	v_mfma_f32_16x16x32_bf16 v[92:95], v[206:209], v[152:155], v[92:95]
	v_mfma_f32_16x16x32_bf16 v[88:91], v[214:217], v[152:155], v[88:91]
	v_mfma_f32_16x16x32_bf16 v[84:87], v[206:209], v[182:185], v[84:87]
	v_mfma_f32_16x16x32_bf16 v[80:83], v[214:217], v[182:185], v[80:83]
	v_mfma_f32_16x16x32_bf16 v[76:79], v[206:209], v[190:193], v[76:79]
	v_mfma_f32_16x16x32_bf16 v[72:75], v[214:217], v[190:193], v[72:75]
	v_mfma_f32_16x16x32_bf16 v[68:71], v[206:209], v[198:201], v[68:71]
	v_mfma_f32_16x16x32_bf16 v[64:67], v[214:217], v[198:201], v[64:67]
	v_mfma_f32_16x16x32_bf16 v[92:95], v[210:213], v[178:181], v[92:95]
	v_mfma_f32_16x16x32_bf16 v[88:91], v[218:221], v[178:181], v[88:91]
	v_mfma_f32_16x16x32_bf16 v[84:87], v[210:213], v[186:189], v[84:87]
	v_mfma_f32_16x16x32_bf16 v[80:83], v[218:221], v[186:189], v[80:83]
	v_mfma_f32_16x16x32_bf16 v[76:79], v[210:213], v[194:197], v[76:79]
	v_mfma_f32_16x16x32_bf16 v[72:75], v[218:221], v[194:197], v[72:75]
	v_mfma_f32_16x16x32_bf16 v[68:71], v[210:213], v[202:205], v[68:71]
	v_mfma_f32_16x16x32_bf16 v[64:67], v[218:221], v[202:205], v[64:67]
	s_setprio 0
	s_add_u32 s38, s41, 0x180
	v_add_u32_e32 v152, 0x8000, v135
	s_addc_u32 s39, s42, 0
	v_readfirstlane_b32 s37, v152
	v_add_u32_e32 v153, 0xa000, v135
	v_lshl_add_u64 v[154:155], s[38:39], 0, v[130:131]
	s_mov_b32 m0, s37
	v_readfirstlane_b32 s37, v153
	s_barrier
	ds_read_b128 v[178:181], v142 offset:0
	ds_read_b128 v[182:185], v142 offset:1024
	ds_read_b128 v[186:189], v142 offset:2048
	ds_read_b128 v[190:193], v142 offset:3072
	ds_read_b128 v[194:197], v142 offset:4096
	ds_read_b128 v[198:201], v142 offset:5120
	ds_read_b128 v[202:205], v142 offset:6144
	ds_read_b128 v[222:225], v142 offset:7168
	global_load_lds_dwordx4 v[154:155], off
	v_lshl_add_u64 v[154:155], s[38:39], 0, v[128:129]
	s_mov_b32 m0, s37
	s_nop 0
	global_load_lds_dwordx4 v[154:155], off
	s_waitcnt vmcnt(10)
	s_barrier
	s_waitcnt lgkmcnt(0)
	s_setprio 1
	v_mfma_f32_16x16x32_bf16 v[60:63], v[158:161], v[178:181], v[60:63]
	v_mfma_f32_16x16x32_bf16 v[56:59], v[166:169], v[178:181], v[56:59]
	v_mfma_f32_16x16x32_bf16 v[52:55], v[158:161], v[186:189], v[52:55]
	v_mfma_f32_16x16x32_bf16 v[48:51], v[166:169], v[186:189], v[48:51]
	v_mfma_f32_16x16x32_bf16 v[44:47], v[158:161], v[194:197], v[44:47]
	v_mfma_f32_16x16x32_bf16 v[40:43], v[166:169], v[194:197], v[40:43]
	v_mfma_f32_16x16x32_bf16 v[36:39], v[158:161], v[202:205], v[36:39]
	v_mfma_f32_16x16x32_bf16 v[32:35], v[166:169], v[202:205], v[32:35]
	v_mfma_f32_16x16x32_bf16 v[60:63], v[162:165], v[182:185], v[60:63]
	v_mfma_f32_16x16x32_bf16 v[56:59], v[170:173], v[182:185], v[56:59]
	v_mfma_f32_16x16x32_bf16 v[52:55], v[162:165], v[190:193], v[52:55]
	v_mfma_f32_16x16x32_bf16 v[48:51], v[170:173], v[190:193], v[48:51]
	v_mfma_f32_16x16x32_bf16 v[44:47], v[162:165], v[198:201], v[44:47]
	v_mfma_f32_16x16x32_bf16 v[40:43], v[170:173], v[198:201], v[40:43]
	v_mfma_f32_16x16x32_bf16 v[36:39], v[162:165], v[222:225], v[36:39]
	v_mfma_f32_16x16x32_bf16 v[32:35], v[170:173], v[222:225], v[32:35]
	s_setprio 0
	s_barrier
	s_add_u32 s38, s43, 0x180
	v_add_u32_e32 v154, 0x1c000, v135
	s_addc_u32 s39, s44, 0
	v_readfirstlane_b32 s37, v154
	v_add_u32_e32 v155, 0x1e000, v135
	v_lshl_add_u64 v[158:159], s[38:39], 0, v[176:177]
	s_mov_b32 m0, s37
	v_readfirstlane_b32 s37, v155
	global_load_lds_dwordx4 v[158:159], off
	v_lshl_add_u64 v[158:159], s[38:39], 0, v[132:133]
	s_mov_b32 m0, s37
	s_nop 0
	global_load_lds_dwordx4 v[158:159], off
	s_waitcnt vmcnt(10)
	s_barrier
	s_setprio 1
	v_mfma_f32_16x16x32_bf16 v[28:31], v[206:209], v[178:181], v[28:31]
	v_mfma_f32_16x16x32_bf16 v[24:27], v[214:217], v[178:181], v[24:27]
	v_mfma_f32_16x16x32_bf16 v[20:23], v[206:209], v[186:189], v[20:23]
	v_mfma_f32_16x16x32_bf16 v[16:19], v[214:217], v[186:189], v[16:19]
	v_mfma_f32_16x16x32_bf16 v[12:15], v[206:209], v[194:197], v[12:15]
	v_mfma_f32_16x16x32_bf16 v[8:11], v[214:217], v[194:197], v[8:11]
	v_mfma_f32_16x16x32_bf16 v[4:7], v[206:209], v[202:205], v[4:7]
	v_mfma_f32_16x16x32_bf16 v[0:3], v[214:217], v[202:205], v[0:3]
	v_mfma_f32_16x16x32_bf16 v[28:31], v[210:213], v[182:185], v[28:31]
	v_mfma_f32_16x16x32_bf16 v[24:27], v[218:221], v[182:185], v[24:27]
	v_mfma_f32_16x16x32_bf16 v[20:23], v[210:213], v[190:193], v[20:23]
	v_mfma_f32_16x16x32_bf16 v[16:19], v[218:221], v[190:193], v[16:19]
	v_mfma_f32_16x16x32_bf16 v[12:15], v[210:213], v[198:201], v[12:15]
	v_mfma_f32_16x16x32_bf16 v[8:11], v[218:221], v[198:201], v[8:11]
	v_mfma_f32_16x16x32_bf16 v[4:7], v[210:213], v[222:225], v[4:7]
	v_mfma_f32_16x16x32_bf16 v[0:3], v[218:221], v[222:225], v[0:3]
	s_setprio 0
	s_add_i32 s29, s29, 2
	s_add_u32 s14, s14, 0x100
	s_addc_u32 s15, s15, 0
	s_cmp_gt_u32 s29, 11
	s_barrier
	s_cbranch_scc0 .LBB0_63
	s_add_u32 s2, s7, 0x780
	s_addc_u32 s3, s20, 0
	v_readfirstlane_b32 s7, v156
	ds_read_b128 v[158:161], v149 offset:0
	ds_read_b128 v[162:165], v149 offset:1024
	ds_read_b128 v[166:169], v149 offset:2048
	ds_read_b128 v[170:173], v149 offset:3072
	ds_read_b128 v[178:181], v148 offset:0
	ds_read_b128 v[182:185], v148 offset:1024
	ds_read_b128 v[186:189], v148 offset:2048
	ds_read_b128 v[190:193], v148 offset:3072
	ds_read_b128 v[194:197], v148 offset:4096
	ds_read_b128 v[198:201], v148 offset:5120
	ds_read_b128 v[202:205], v148 offset:6144
	ds_read_b128 v[206:209], v148 offset:7168
	v_lshl_add_u64 v[148:149], s[2:3], 0, v[130:131]
	s_mov_b32 m0, s7
	s_nop 0
	global_load_lds_dwordx4 v[148:149], off
	v_lshl_add_u64 v[148:149], s[2:3], 0, v[128:129]
	v_readfirstlane_b32 s2, v157
	s_mov_b32 m0, s2
	s_nop 0
	global_load_lds_dwordx4 v[148:149], off
	s_waitcnt vmcnt(10)
	s_barrier
	s_waitcnt lgkmcnt(0)
	s_waitcnt lgkmcnt(0)
	s_setprio 1
	v_mfma_f32_16x16x32_bf16 v[124:127], v[158:161], v[178:181], v[124:127]
	v_mfma_f32_16x16x32_bf16 v[120:123], v[166:169], v[178:181], v[120:123]
	v_mfma_f32_16x16x32_bf16 v[116:119], v[158:161], v[186:189], v[116:119]
	v_mfma_f32_16x16x32_bf16 v[112:115], v[166:169], v[186:189], v[112:115]
	v_mfma_f32_16x16x32_bf16 v[100:103], v[158:161], v[202:205], v[100:103]
	v_mfma_f32_16x16x32_bf16 v[96:99], v[166:169], v[202:205], v[96:99]
	v_mfma_f32_16x16x32_bf16 v[124:127], v[162:165], v[182:185], v[124:127]
	v_mfma_f32_16x16x32_bf16 v[120:123], v[170:173], v[182:185], v[120:123]
	v_mfma_f32_16x16x32_bf16 v[116:119], v[162:165], v[190:193], v[116:119]
	v_mfma_f32_16x16x32_bf16 v[112:115], v[170:173], v[190:193], v[112:115]
	v_mfma_f32_16x16x32_bf16 v[108:111], v[158:161], v[194:197], v[108:111]
	v_mfma_f32_16x16x32_bf16 v[104:107], v[166:169], v[194:197], v[104:107]
	v_mfma_f32_16x16x32_bf16 v[100:103], v[162:165], v[206:209], v[100:103]
	v_mfma_f32_16x16x32_bf16 v[96:99], v[170:173], v[206:209], v[96:99]
	v_mfma_f32_16x16x32_bf16 v[210:213], v[162:165], v[198:201], v[108:111]
	v_mfma_f32_16x16x32_bf16 v[214:217], v[170:173], v[198:201], v[104:107]
	s_setprio 0
	s_barrier
	ds_read_b128 v[104:107], v147 offset:0
	ds_read_b128 v[108:111], v147 offset:1024
	ds_read_b128 v[218:221], v147 offset:2048
	ds_read_b128 v[222:225], v147 offset:3072
	s_waitcnt vmcnt(8)
	s_barrier
	s_waitcnt lgkmcnt(0)
	s_setprio 1
	v_mfma_f32_16x16x32_bf16 v[92:95], v[104:107], v[178:181], v[92:95]
	v_mfma_f32_16x16x32_bf16 v[88:91], v[218:221], v[178:181], v[88:91]
	v_mfma_f32_16x16x32_bf16 v[76:79], v[104:107], v[194:197], v[76:79]
	v_mfma_f32_16x16x32_bf16 v[72:75], v[218:221], v[194:197], v[72:75]
	v_mfma_f32_16x16x32_bf16 v[68:71], v[104:107], v[202:205], v[68:71]
	v_mfma_f32_16x16x32_bf16 v[92:95], v[108:111], v[182:185], v[92:95]
	v_mfma_f32_16x16x32_bf16 v[88:91], v[222:225], v[182:185], v[88:91]
	v_mfma_f32_16x16x32_bf16 v[84:87], v[104:107], v[186:189], v[84:87]
	v_mfma_f32_16x16x32_bf16 v[80:83], v[218:221], v[186:189], v[80:83]
	v_mfma_f32_16x16x32_bf16 v[76:79], v[108:111], v[198:201], v[76:79]
	v_mfma_f32_16x16x32_bf16 v[72:75], v[222:225], v[198:201], v[72:75]
	v_mfma_f32_16x16x32_bf16 v[68:71], v[108:111], v[206:209], v[68:71]
	v_mfma_f32_16x16x32_bf16 v[64:67], v[218:221], v[202:205], v[64:67]
	v_mfma_f32_16x16x32_bf16 v[178:181], v[108:111], v[190:193], v[84:87]
	v_mfma_f32_16x16x32_bf16 v[182:185], v[222:225], v[190:193], v[80:83]
	v_mfma_f32_16x16x32_bf16 v[186:189], v[222:225], v[206:209], v[64:67]
	s_setprio 0
	s_barrier
	ds_read_b128 v[64:67], v146 offset:0
	ds_read_b128 v[80:83], v146 offset:1024
	ds_read_b128 v[84:87], v146 offset:2048
	ds_read_b128 v[190:193], v146 offset:3072
	ds_read_b128 v[194:197], v146 offset:4096
	ds_read_b128 v[198:201], v146 offset:5120
	ds_read_b128 v[202:205], v146 offset:6144
	ds_read_b128 v[146:149], v146 offset:7168
	s_waitcnt vmcnt(4)
	s_barrier
	s_waitcnt lgkmcnt(0)
	s_setprio 1
	s_nop 0
	v_mfma_f32_16x16x32_bf16 v[60:63], v[158:161], v[64:67], v[60:63]
	v_mfma_f32_16x16x32_bf16 v[56:59], v[166:169], v[64:67], v[56:59]
	v_mfma_f32_16x16x32_bf16 v[60:63], v[162:165], v[80:83], v[60:63]
	v_mfma_f32_16x16x32_bf16 v[56:59], v[170:173], v[80:83], v[56:59]
	v_mfma_f32_16x16x32_bf16 v[52:55], v[158:161], v[84:87], v[52:55]
	v_mfma_f32_16x16x32_bf16 v[48:51], v[166:169], v[84:87], v[48:51]
	v_mfma_f32_16x16x32_bf16 v[44:47], v[158:161], v[194:197], v[44:47]
	v_mfma_f32_16x16x32_bf16 v[40:43], v[166:169], v[194:197], v[40:43]
	v_mfma_f32_16x16x32_bf16 v[36:39], v[158:161], v[202:205], v[36:39]
	v_mfma_f32_16x16x32_bf16 v[32:35], v[166:169], v[202:205], v[32:35]
	v_mfma_f32_16x16x32_bf16 v[206:209], v[162:165], v[190:193], v[52:55]
	v_mfma_f32_16x16x32_bf16 v[226:229], v[170:173], v[190:193], v[48:51]
	v_mfma_f32_16x16x32_bf16 v[232:235], v[162:165], v[198:201], v[44:47]
	v_mfma_f32_16x16x32_bf16 v[238:241], v[170:173], v[198:201], v[40:43]
	v_mfma_f32_16x16x32_bf16 v[156:159], v[162:165], v[146:149], v[36:39]
	v_mfma_f32_16x16x32_bf16 v[160:163], v[170:173], v[146:149], v[32:35]
	s_setprio 0
	s_setprio 1
	v_mfma_f32_16x16x32_bf16 v[28:31], v[104:107], v[64:67], v[28:31]
	v_mfma_f32_16x16x32_bf16 v[24:27], v[218:221], v[64:67], v[24:27]
	v_mfma_f32_16x16x32_bf16 v[12:15], v[104:107], v[194:197], v[12:15]
	v_mfma_f32_16x16x32_bf16 v[8:11], v[218:221], v[194:197], v[8:11]
	v_mfma_f32_16x16x32_bf16 v[28:31], v[108:111], v[80:83], v[28:31]
	v_mfma_f32_16x16x32_bf16 v[24:27], v[222:225], v[80:83], v[24:27]
	v_mfma_f32_16x16x32_bf16 v[20:23], v[104:107], v[84:87], v[20:23]
	v_mfma_f32_16x16x32_bf16 v[16:19], v[218:221], v[84:87], v[16:19]
	v_mfma_f32_16x16x32_bf16 v[12:15], v[108:111], v[198:201], v[12:15]
	v_mfma_f32_16x16x32_bf16 v[8:11], v[222:225], v[198:201], v[8:11]
	v_mfma_f32_16x16x32_bf16 v[4:7], v[104:107], v[202:205], v[4:7]
	v_mfma_f32_16x16x32_bf16 v[0:3], v[218:221], v[202:205], v[0:3]
	v_mfma_f32_16x16x32_bf16 v[164:167], v[108:111], v[190:193], v[20:23]
	v_mfma_f32_16x16x32_bf16 v[168:171], v[222:225], v[190:193], v[16:19]
	v_mfma_f32_16x16x32_bf16 v[172:175], v[108:111], v[146:149], v[4:7]
	v_mfma_f32_16x16x32_bf16 v[146:149], v[222:225], v[146:149], v[0:3]
	s_setprio 0
	s_barrier
	ds_read_b128 v[0:3], v145 offset:0
	ds_read_b128 v[4:7], v145 offset:1024
	ds_read_b128 v[190:193], v145 offset:2048
	ds_read_b128 v[194:197], v145 offset:3072
	ds_read_b128 v[16:19], v144 offset:0
	ds_read_b128 v[20:23], v144 offset:1024
	ds_read_b128 v[40:43], v144 offset:2048
	ds_read_b128 v[44:47], v144 offset:3072
	ds_read_b128 v[64:67], v144 offset:4096
	ds_read_b128 v[198:201], v144 offset:5120
	ds_read_b128 v[202:205], v144 offset:6144
	ds_read_b128 v[218:221], v144 offset:7168
	s_waitcnt vmcnt(2)
	s_barrier
	s_waitcnt lgkmcnt(0)
	s_waitcnt lgkmcnt(0)
	s_setprio 1
	v_mfma_f32_16x16x32_bf16 v[32:35], v[0:3], v[16:19], v[124:127]
	v_mfma_f32_16x16x32_bf16 v[104:107], v[4:7], v[20:23], v[32:35]
	v_mfma_f32_16x16x32_bf16 v[32:35], v[190:193], v[16:19], v[120:123]
	v_mfma_f32_16x16x32_bf16 v[108:111], v[194:197], v[20:23], v[32:35]
	v_mfma_f32_16x16x32_bf16 v[32:35], v[0:3], v[40:43], v[116:119]
	v_mfma_f32_16x16x32_bf16 v[80:83], v[4:7], v[44:47], v[32:35]
	v_mfma_f32_16x16x32_bf16 v[32:35], v[190:193], v[40:43], v[112:115]
	v_mfma_f32_16x16x32_bf16 v[84:87], v[194:197], v[44:47], v[32:35]
	v_mfma_f32_16x16x32_bf16 v[32:35], v[0:3], v[64:67], v[210:213]
	v_mfma_f32_16x16x32_bf16 v[48:51], v[4:7], v[198:201], v[32:35]
	v_mfma_f32_16x16x32_bf16 v[32:35], v[190:193], v[64:67], v[214:217]
	v_mfma_f32_16x16x32_bf16 v[52:55], v[194:197], v[198:201], v[32:35]
	v_mfma_f32_16x16x32_bf16 v[32:35], v[0:3], v[202:205], v[100:103]
	v_mfma_f32_16x16x32_bf16 v[36:39], v[190:193], v[202:205], v[96:99]
	v_mfma_f32_16x16x32_bf16 v[32:35], v[4:7], v[218:221], v[32:35]
	v_mfma_f32_16x16x32_bf16 v[36:39], v[194:197], v[218:221], v[36:39]
	s_setprio 0
	s_barrier
	ds_read_b128 v[210:213], v143 offset:0
	ds_read_b128 v[214:217], v143 offset:1024
	ds_read_b128 v[222:225], v143 offset:2048
	ds_read_b128 v[242:245], v143 offset:3072
	s_waitcnt vmcnt(0)
	s_barrier
	s_waitcnt lgkmcnt(0)
	s_setprio 1
	v_mfma_f32_16x16x32_bf16 v[92:95], v[210:213], v[16:19], v[92:95]
	v_mfma_f32_16x16x32_bf16 v[16:19], v[222:225], v[16:19], v[88:91]
	v_mfma_f32_16x16x32_bf16 v[124:127], v[242:245], v[20:23], v[16:19]
	v_mfma_f32_16x16x32_bf16 v[16:19], v[210:213], v[40:43], v[178:181]
	v_mfma_f32_16x16x32_bf16 v[112:115], v[214:217], v[44:47], v[16:19]
	v_mfma_f32_16x16x32_bf16 v[16:19], v[222:225], v[40:43], v[182:185]
	v_mfma_f32_16x16x32_bf16 v[116:119], v[242:245], v[44:47], v[16:19]
	v_mfma_f32_16x16x32_bf16 v[16:19], v[210:213], v[64:67], v[76:79]
	v_mfma_f32_16x16x32_bf16 v[96:99], v[214:217], v[198:201], v[16:19]
	v_mfma_f32_16x16x32_bf16 v[16:19], v[222:225], v[64:67], v[72:75]
	v_mfma_f32_16x16x32_bf16 v[100:103], v[242:245], v[198:201], v[16:19]
	v_mfma_f32_16x16x32_bf16 v[16:19], v[210:213], v[202:205], v[68:71]
	v_mfma_f32_16x16x32_bf16 v[64:67], v[214:217], v[218:221], v[16:19]
	v_mfma_f32_16x16x32_bf16 v[16:19], v[222:225], v[202:205], v[186:189]
	v_mfma_f32_16x16x32_bf16 v[120:123], v[214:217], v[20:23], v[92:95]
	v_mfma_f32_16x16x32_bf16 v[68:71], v[242:245], v[218:221], v[16:19]
	s_setprio 0
	s_barrier
	ds_read_b128 v[92:95], v142 offset:0
	ds_read_b128 v[178:181], v142 offset:1024
	ds_read_b128 v[182:185], v142 offset:2048
	ds_read_b128 v[186:189], v142 offset:3072
	ds_read_b128 v[198:201], v142 offset:4096
	ds_read_b128 v[202:205], v142 offset:5120
	ds_read_b128 v[218:221], v142 offset:6144
	ds_read_b128 v[142:145], v142 offset:7168
	s_barrier
	s_waitcnt lgkmcnt(0)
	s_setprio 1
	v_mfma_f32_16x16x32_bf16 v[16:19], v[0:3], v[92:95], v[60:63]
	v_mfma_f32_16x16x32_bf16 v[72:75], v[4:7], v[178:181], v[16:19]
	v_mfma_f32_16x16x32_bf16 v[16:19], v[190:193], v[92:95], v[56:59]
	v_mfma_f32_16x16x32_bf16 v[76:79], v[194:197], v[178:181], v[16:19]
	v_mfma_f32_16x16x32_bf16 v[16:19], v[0:3], v[182:185], v[206:209]
	v_mfma_f32_16x16x32_bf16 v[40:43], v[4:7], v[186:189], v[16:19]
	v_mfma_f32_16x16x32_bf16 v[16:19], v[190:193], v[182:185], v[226:229]
	v_mfma_f32_16x16x32_bf16 v[44:47], v[194:197], v[186:189], v[16:19]
	v_mfma_f32_16x16x32_bf16 v[16:19], v[0:3], v[198:201], v[232:235]
	v_mfma_f32_16x16x32_bf16 v[0:3], v[0:3], v[218:221], v[156:159]
	v_mfma_f32_16x16x32_bf16 v[16:19], v[4:7], v[202:205], v[16:19]
	v_mfma_f32_16x16x32_bf16 v[20:23], v[190:193], v[198:201], v[238:241]
	v_mfma_f32_16x16x32_bf16 v[0:3], v[4:7], v[142:145], v[0:3]
	v_mfma_f32_16x16x32_bf16 v[4:7], v[190:193], v[218:221], v[160:163]
	v_mfma_f32_16x16x32_bf16 v[20:23], v[194:197], v[202:205], v[20:23]
	v_mfma_f32_16x16x32_bf16 v[4:7], v[194:197], v[142:145], v[4:7]
	s_setprio 0
	s_setprio 1
	v_mfma_f32_16x16x32_bf16 v[24:27], v[222:225], v[92:95], v[24:27]
	v_mfma_f32_16x16x32_bf16 v[28:31], v[210:213], v[92:95], v[28:31]
	v_mfma_f32_16x16x32_bf16 v[92:95], v[242:245], v[178:181], v[24:27]
	v_mfma_f32_16x16x32_bf16 v[24:27], v[210:213], v[182:185], v[164:167]
	v_mfma_f32_16x16x32_bf16 v[56:59], v[214:217], v[186:189], v[24:27]
	v_mfma_f32_16x16x32_bf16 v[24:27], v[222:225], v[182:185], v[168:171]
	v_mfma_f32_16x16x32_bf16 v[12:15], v[210:213], v[198:201], v[12:15]
	v_mfma_f32_16x16x32_bf16 v[8:11], v[222:225], v[198:201], v[8:11]
	v_mfma_f32_16x16x32_bf16 v[88:91], v[214:217], v[178:181], v[28:31]
	v_mfma_f32_16x16x32_bf16 v[60:63], v[242:245], v[186:189], v[24:27]
	v_mfma_f32_16x16x32_bf16 v[24:27], v[214:217], v[202:205], v[12:15]
	v_mfma_f32_16x16x32_bf16 v[28:31], v[242:245], v[202:205], v[8:11]
	v_mfma_f32_16x16x32_bf16 v[8:11], v[210:213], v[218:221], v[172:175]
	v_mfma_f32_16x16x32_bf16 v[12:15], v[222:225], v[218:221], v[146:149]
	v_mfma_f32_16x16x32_bf16 v[8:11], v[214:217], v[142:145], v[8:11]
	v_mfma_f32_16x16x32_bf16 v[12:15], v[242:245], v[142:145], v[12:15]
	s_setprio 0
	s_cmpk_lt_u32 s9, 0x100
	s_barrier
	s_cbranch_scc0 .LBB0_66
	s_barrier

.LBB0_70:
	s_andn2_b64 vcc, exec, s[0:1]
	s_cbranch_vccnz .LBB0_939
	s_cmp_eq_u32 s30, 1
	s_mov_b64 s[0:1], -1
	s_cbranch_scc1 .LBB0_873
	v_readlane_b32 s0, v253, 20
	v_writelane_b32 v255, s48, 2
	v_readlane_b32 s1, v253, 21
	s_andn2_b64 vcc, exec, s[0:1]
	v_writelane_b32 v255, s49, 3
	s_cbranch_vccnz .LBB0_872
	v_readlane_b32 s0, v255, 0
	v_readlane_b32 s1, v255, 1
	s_mov_b32 s6, s0
	s_lshl_b32 s0, s0, 6
	s_ashr_i32 s1, s0, 31
	s_lshl_b64 s[0:1], s[0:1], 2
	s_add_u32 s2, s58, s0
	v_writelane_b32 v255, s2, 4
	s_addc_u32 s2, s59, s1
	v_writelane_b32 v255, s2, 5
	s_add_u32 s0, s60, s0
	v_writelane_b32 v255, s0, 6
	s_addc_u32 s0, s61, s1
	s_ashr_i32 s7, s6, 31
	s_mul_i32 s1, s6, 0x480000
	v_readlane_b32 s2, v254, 62
	v_writelane_b32 v255, s0, 7
	s_mul_hi_i32 s0, s6, 0x480000
	s_add_u32 s2, s2, s1
	s_addc_u32 s3, s97, s0
	v_writelane_b32 v255, s2, 8
	s_mul_i32 s1, s6, 0x280000
	s_mul_hi_i32 s0, s6, 0x280000
	v_writelane_b32 v255, s3, 9
	v_readlane_b32 s2, v253, 7
	s_add_u32 s8, s2, s1
	v_readlane_b32 s2, v253, 8
	s_addc_u32 s9, s2, s0
	v_writelane_b32 v255, s8, 10
	v_readlane_b32 s2, v253, 9
	s_add_u32 s1, s2, s1
	v_writelane_b32 v255, s9, 11
	v_writelane_b32 v255, s1, 12
	v_readlane_b32 s1, v253, 10
	s_addc_u32 s0, s1, s0
	v_writelane_b32 v255, s0, 13
	s_lshl_b64 s[0:1], s[6:7], 20
	v_readlane_b32 s2, v253, 1
	s_add_u32 s8, s2, s0
	s_mov_b32 s2, s6
	v_readlane_b32 s0, v253, 2
	v_writelane_b32 v255, s2, 0
	s_addc_u32 s9, s0, s1
	s_mul_i32 s1, s6, 0xa00000
	v_writelane_b32 v255, s3, 1
	v_readlane_b32 s2, v253, 5
	s_mul_hi_i32 s0, s6, 0xa00000
	v_readlane_b32 s3, v253, 6
	s_add_u32 s14, s2, s1
	s_addc_u32 s15, s3, s0
	v_lshlrev_b32_e32 v0, 4, v250
	global_load_dwordx4 v[2:5], v0, s[98:99]
	v_and_b32_e32 v1, 0xf0, v0
	v_readlane_b32 s0, v255, 4
	v_readlane_b32 s1, v255, 5
	v_readlane_b32 s2, v255, 6
	v_readlane_b32 s3, v255, 7
	s_nop 4
	global_load_dwordx4 v[6:9], v1, s[0:1]
	global_load_dwordx4 v[10:13], v1, s[2:3]
	v_add_u32_e32 v0, 0x20010, v0
	v_add_u32_e32 v1, 0x22010, v1
	s_waitcnt vmcnt(2)
	ds_write_b128 v0, v[2:5]
	s_waitcnt vmcnt(1)
	ds_write_b128 v1, v[6:9]
	s_waitcnt vmcnt(0)
	ds_write_b128 v1, v[10:13] offset:256
	s_waitcnt lgkmcnt(0)
	s_mov_b64 s[2:3], 0
	v_readlane_b32 s34, v254, 57
	s_branch .LBB0_75

.LBB0_104:
	v_and_b32_e32 v0, 15, v7
	v_and_b32_e32 v1, 48, v7
	v_lshlrev_b32_e32 v0, 6, v0
	v_lshlrev_b32_e32 v7, 2, v7
	v_or_b32_e32 v8, v0, v1
	v_and_b32_e32 v7, 32, v7
	s_lshl_b32 s1, s35, 13
	v_bitop3_b32 v144, v8, s1, v7 bitop3:0xde
	s_lshl_b32 s1, s11, 6
	v_bitop3_b32 v0, v0, v7, v1 bitop3:0x36
	s_and_b32 s1, s1, 0x3000
	v_or_b32_e32 v0, s1, v0
	s_add_u32 s1, s48, s26
	v_bfe_u32 v8, v134, 6, 2
	s_addc_u32 s26, s49, s27
	v_and_b32_e32 v1, 31, v5
	v_lshlrev_b32_e32 v7, 1, v5
	v_lshrrev_b32_e32 v6, 13, v6
	v_add_u32_e32 v5, v5, v8
	s_add_u32 s2, s52, s2
	v_and_b32_e32 v7, 24, v7
	v_and_b32_e32 v6, 4, v6
	v_sub_u32_e32 v1, v5, v1
	s_addc_u32 s3, s53, s3
	v_add3_u32 v1, v1, v7, v6
	v_lshl_or_b32 v136, v1, 11, v2
	v_and_b32_e32 v1, 31, v3
	v_lshlrev_b32_e32 v5, 1, v3
	v_lshrrev_b32_e32 v4, 13, v4
	v_add_u32_e32 v3, v3, v8
	s_add_u32 s20, s48, s20
	v_and_b32_e32 v5, 24, v5
	v_and_b32_e32 v4, 4, v4
	v_sub_u32_e32 v1, v3, v1
	s_addc_u32 s21, s49, s21
	v_add3_u32 v1, v1, v5, v4
	s_add_u32 s27, s52, s30
	v_or_b32_e32 v145, 0x10000, v0
	v_or_b32_e32 v143, 0x14000, v0
	v_lshl_or_b32 v137, v1, 11, v2
	s_addc_u32 s28, s53, s31
	v_or_b32_e32 v141, 0x18000, v0
	v_or_b32_e32 v139, 0x1c000, v0
	v_cndmask_b32_e64 v0, v128, v136, s[40:41]
	v_cndmask_b32_e64 v132, v176, v137, s[40:41]
	v_mov_b32_e32 v176, v0
	s_add_u32 s29, s1, 0x100
	v_mov_b32_e32 v0, 0
	v_add_u32_e32 v142, 0x4000, v144
	v_add_u32_e32 v140, 0x8000, v144
	v_add_u32_e32 v138, 0xc000, v144
	v_mov_b32_e32 v133, v177
	s_addc_u32 s30, s26, 0
	s_mov_b32 s31, -2
	s_mov_b64 s[40:41], 0
	v_mov_b32_e32 v1, v0
	v_mov_b32_e32 v2, v0
	v_mov_b32_e32 v3, v0
	v_mov_b32_e32 v4, v0
	v_mov_b32_e32 v5, v0
	v_mov_b32_e32 v6, v0
	v_mov_b32_e32 v7, v0
	v_mov_b32_e32 v8, v0
	v_mov_b32_e32 v9, v0
	v_mov_b32_e32 v10, v0
	v_mov_b32_e32 v11, v0
	v_mov_b32_e32 v12, v0
	v_mov_b32_e32 v13, v0
	v_mov_b32_e32 v14, v0
	v_mov_b32_e32 v15, v0
	v_mov_b32_e32 v16, v0
	v_mov_b32_e32 v17, v0
	v_mov_b32_e32 v18, v0
	v_mov_b32_e32 v19, v0
	v_mov_b32_e32 v20, v0
	v_mov_b32_e32 v21, v0
	v_mov_b32_e32 v22, v0
	v_mov_b32_e32 v23, v0
	v_mov_b32_e32 v24, v0
	v_mov_b32_e32 v25, v0
	v_mov_b32_e32 v26, v0
	v_mov_b32_e32 v27, v0
	v_mov_b32_e32 v28, v0
	v_mov_b32_e32 v29, v0
	v_mov_b32_e32 v30, v0
	v_mov_b32_e32 v31, v0
	v_mov_b32_e32 v32, v0
	v_mov_b32_e32 v33, v0
	v_mov_b32_e32 v34, v0
	v_mov_b32_e32 v35, v0
	v_mov_b32_e32 v36, v0
	v_mov_b32_e32 v37, v0
	v_mov_b32_e32 v38, v0
	v_mov_b32_e32 v39, v0
	v_mov_b32_e32 v40, v0
	v_mov_b32_e32 v41, v0
	v_mov_b32_e32 v42, v0
	v_mov_b32_e32 v43, v0
	v_mov_b32_e32 v44, v0
	v_mov_b32_e32 v45, v0
	v_mov_b32_e32 v46, v0
	v_mov_b32_e32 v47, v0
	v_mov_b32_e32 v48, v0
	v_mov_b32_e32 v49, v0
	v_mov_b32_e32 v50, v0
	v_mov_b32_e32 v51, v0
	v_mov_b32_e32 v52, v0
	v_mov_b32_e32 v53, v0
	v_mov_b32_e32 v54, v0
	v_mov_b32_e32 v55, v0
	v_mov_b32_e32 v56, v0
	v_mov_b32_e32 v57, v0
	v_mov_b32_e32 v58, v0
	v_mov_b32_e32 v59, v0
	v_mov_b32_e32 v60, v0
	v_mov_b32_e32 v61, v0
	v_mov_b32_e32 v62, v0
	v_mov_b32_e32 v63, v0
	s_nop 0
	v_mov_b32_e32 v64, v0
	v_mov_b32_e32 v65, v0
	v_mov_b32_e32 v66, v0
	v_mov_b32_e32 v67, v0
	v_mov_b32_e32 v68, v0
	v_mov_b32_e32 v69, v0
	v_mov_b32_e32 v70, v0
	v_mov_b32_e32 v71, v0
	v_mov_b32_e32 v72, v0
	v_mov_b32_e32 v73, v0
	v_mov_b32_e32 v74, v0
	v_mov_b32_e32 v75, v0
	v_mov_b32_e32 v76, v0
	v_mov_b32_e32 v77, v0
	v_mov_b32_e32 v78, v0
	v_mov_b32_e32 v79, v0
	v_mov_b32_e32 v80, v0
	v_mov_b32_e32 v81, v0
	v_mov_b32_e32 v82, v0
	v_mov_b32_e32 v83, v0
	v_mov_b32_e32 v84, v0
	v_mov_b32_e32 v85, v0
	v_mov_b32_e32 v86, v0
	v_mov_b32_e32 v87, v0
	v_mov_b32_e32 v88, v0
	v_mov_b32_e32 v89, v0
	v_mov_b32_e32 v90, v0
	v_mov_b32_e32 v91, v0
	v_mov_b32_e32 v92, v0
	v_mov_b32_e32 v93, v0
	v_mov_b32_e32 v94, v0
	v_mov_b32_e32 v95, v0
	v_mov_b32_e32 v96, v0
	v_mov_b32_e32 v97, v0
	v_mov_b32_e32 v98, v0
	v_mov_b32_e32 v99, v0
	v_mov_b32_e32 v100, v0
	v_mov_b32_e32 v101, v0
	v_mov_b32_e32 v102, v0
	v_mov_b32_e32 v103, v0
	v_mov_b32_e32 v104, v0
	v_mov_b32_e32 v105, v0
	v_mov_b32_e32 v106, v0
	v_mov_b32_e32 v107, v0
	v_mov_b32_e32 v108, v0
	v_mov_b32_e32 v109, v0
	v_mov_b32_e32 v110, v0
	v_mov_b32_e32 v111, v0
	v_mov_b32_e32 v112, v0
	v_mov_b32_e32 v113, v0
	v_mov_b32_e32 v114, v0
	v_mov_b32_e32 v115, v0
	v_mov_b32_e32 v116, v0
	v_mov_b32_e32 v117, v0
	v_mov_b32_e32 v118, v0
	v_mov_b32_e32 v119, v0
	v_mov_b32_e32 v120, v0
	v_mov_b32_e32 v121, v0
	v_mov_b32_e32 v122, v0
	v_mov_b32_e32 v123, v0
	v_mov_b32_e32 v124, v0
	v_mov_b32_e32 v125, v0
	v_mov_b32_e32 v126, v0
	v_mov_b32_e32 v127, v0
.LBB0_105:
	ds_read_b128 v[148:151], v145 offset:0
	ds_read_b128 v[152:155], v145 offset:1024
	ds_read_b128 v[160:163], v145 offset:2048
	ds_read_b128 v[164:167], v145 offset:3072
	s_add_u32 s35, s1, s40
	s_addc_u32 s43, s26, s41
	s_add_u32 s42, s35, 0x80
	v_add_u32_e32 v158, 0xc000, v134
	s_addc_u32 s43, s43, 0
	v_readfirstlane_b32 s35, v158
	v_add_u32_e32 v159, 0xe000, v134
	v_lshl_add_u64 v[146:147], s[42:43], 0, v[128:129]
	s_mov_b32 m0, s35
	v_readfirstlane_b32 s35, v159
	ds_read_b128 v[168:171], v144 offset:0
	ds_read_b128 v[172:175], v144 offset:1024
	ds_read_b128 v[178:181], v144 offset:2048
	ds_read_b128 v[182:185], v144 offset:3072
	ds_read_b128 v[186:189], v144 offset:4096
	ds_read_b128 v[190:193], v144 offset:5120
	ds_read_b128 v[194:197], v144 offset:6144
	ds_read_b128 v[198:201], v144 offset:7168
	global_load_lds_dwordx4 v[146:147], off
	v_lshl_add_u64 v[146:147], s[42:43], 0, v[130:131]
	s_mov_b32 m0, s35
	s_nop 0
	global_load_lds_dwordx4 v[146:147], off
	s_waitcnt vmcnt(10)
	s_waitcnt lgkmcnt(8)
	s_barrier
	s_waitcnt lgkmcnt(0)
	s_waitcnt lgkmcnt(0)
	s_setprio 1
	v_mfma_f32_16x16x32_bf16 v[124:127], v[148:151], v[168:171], v[124:127]
	v_mfma_f32_16x16x32_bf16 v[120:123], v[160:163], v[168:171], v[120:123]
	v_mfma_f32_16x16x32_bf16 v[116:119], v[148:151], v[178:181], v[116:119]
	v_mfma_f32_16x16x32_bf16 v[112:115], v[160:163], v[178:181], v[112:115]
	v_mfma_f32_16x16x32_bf16 v[108:111], v[148:151], v[186:189], v[108:111]
	v_mfma_f32_16x16x32_bf16 v[104:107], v[160:163], v[186:189], v[104:107]
	v_mfma_f32_16x16x32_bf16 v[100:103], v[148:151], v[194:197], v[100:103]
	v_mfma_f32_16x16x32_bf16 v[96:99], v[160:163], v[194:197], v[96:99]
	v_mfma_f32_16x16x32_bf16 v[124:127], v[152:155], v[172:175], v[124:127]
	v_mfma_f32_16x16x32_bf16 v[120:123], v[164:167], v[172:175], v[120:123]
	v_mfma_f32_16x16x32_bf16 v[116:119], v[152:155], v[182:185], v[116:119]
	v_mfma_f32_16x16x32_bf16 v[112:115], v[164:167], v[182:185], v[112:115]
	v_mfma_f32_16x16x32_bf16 v[108:111], v[152:155], v[190:193], v[108:111]
	v_mfma_f32_16x16x32_bf16 v[104:107], v[164:167], v[190:193], v[104:107]
	v_mfma_f32_16x16x32_bf16 v[100:103], v[152:155], v[198:201], v[100:103]
	v_mfma_f32_16x16x32_bf16 v[96:99], v[164:167], v[198:201], v[96:99]
	s_setprio 0
	s_barrier
	s_add_u32 s35, s2, s40
	s_addc_u32 s45, s3, s41
	s_add_u32 s42, s35, 0x100
	v_add_u32_e32 v146, 0x10000, v134
	s_addc_u32 s43, s45, 0
	v_readfirstlane_b32 s51, v146
	v_lshl_add_u64 v[156:157], s[42:43], 0, v[176:177]
	s_mov_b32 m0, s51
	v_add_u32_e32 v147, 0x12000, v134
	ds_read_b128 v[202:205], v143 offset:0
	ds_read_b128 v[206:209], v143 offset:1024
	ds_read_b128 v[210:213], v143 offset:2048
	ds_read_b128 v[214:217], v143 offset:3072
	global_load_lds_dwordx4 v[156:157], off
	v_lshl_add_u64 v[156:157], s[42:43], 0, v[132:133]
	v_readfirstlane_b32 s42, v147
	s_mov_b32 m0, s42
	s_nop 0
	global_load_lds_dwordx4 v[156:157], off
	s_waitcnt vmcnt(10)
	s_barrier
	s_waitcnt lgkmcnt(0)
	s_setprio 1
	v_mfma_f32_16x16x32_bf16 v[92:95], v[202:205], v[168:171], v[92:95]
	v_mfma_f32_16x16x32_bf16 v[88:91], v[210:213], v[168:171], v[88:91]
	v_mfma_f32_16x16x32_bf16 v[84:87], v[202:205], v[178:181], v[84:87]
	v_mfma_f32_16x16x32_bf16 v[80:83], v[210:213], v[178:181], v[80:83]
	v_mfma_f32_16x16x32_bf16 v[76:79], v[202:205], v[186:189], v[76:79]
	v_mfma_f32_16x16x32_bf16 v[72:75], v[210:213], v[186:189], v[72:75]
	v_mfma_f32_16x16x32_bf16 v[68:71], v[202:205], v[194:197], v[68:71]
	v_mfma_f32_16x16x32_bf16 v[64:67], v[210:213], v[194:197], v[64:67]
	v_mfma_f32_16x16x32_bf16 v[92:95], v[206:209], v[172:175], v[92:95]
	v_mfma_f32_16x16x32_bf16 v[88:91], v[214:217], v[172:175], v[88:91]
	v_mfma_f32_16x16x32_bf16 v[84:87], v[206:209], v[182:185], v[84:87]
	v_mfma_f32_16x16x32_bf16 v[80:83], v[214:217], v[182:185], v[80:83]
	v_mfma_f32_16x16x32_bf16 v[76:79], v[206:209], v[190:193], v[76:79]
	v_mfma_f32_16x16x32_bf16 v[72:75], v[214:217], v[190:193], v[72:75]
	v_mfma_f32_16x16x32_bf16 v[68:71], v[206:209], v[198:201], v[68:71]
	v_mfma_f32_16x16x32_bf16 v[64:67], v[214:217], v[198:201], v[64:67]
	s_setprio 0
	s_add_u32 s51, s20, s40
	s_addc_u32 s54, s21, s41
	s_add_u32 s42, s51, 0x100
	s_addc_u32 s43, s54, 0
	v_readfirstlane_b32 s88, v134
	v_lshl_add_u64 v[156:157], s[42:43], 0, v[128:129]
	s_mov_b32 m0, s88
	s_barrier
	ds_read_b128 v[168:171], v142 offset:0
	ds_read_b128 v[172:175], v142 offset:1024
	ds_read_b128 v[178:181], v142 offset:2048
	ds_read_b128 v[182:185], v142 offset:3072
	ds_read_b128 v[186:189], v142 offset:4096
	ds_read_b128 v[190:193], v142 offset:5120
	ds_read_b128 v[194:197], v142 offset:6144
	ds_read_b128 v[198:201], v142 offset:7168
	global_load_lds_dwordx4 v[156:157], off
	v_lshl_add_u64 v[156:157], s[42:43], 0, v[130:131]
	v_readfirstlane_b32 s42, v135
	s_mov_b32 m0, s42
	s_nop 0
	global_load_lds_dwordx4 v[156:157], off
	s_waitcnt vmcnt(10)
	s_barrier
	s_waitcnt lgkmcnt(0)
	s_setprio 1
	v_mfma_f32_16x16x32_bf16 v[60:63], v[148:151], v[168:171], v[60:63]
	v_mfma_f32_16x16x32_bf16 v[56:59], v[160:163], v[168:171], v[56:59]
	v_mfma_f32_16x16x32_bf16 v[52:55], v[148:151], v[178:181], v[52:55]
	v_mfma_f32_16x16x32_bf16 v[48:51], v[160:163], v[178:181], v[48:51]
	v_mfma_f32_16x16x32_bf16 v[44:47], v[148:151], v[186:189], v[44:47]
	v_mfma_f32_16x16x32_bf16 v[40:43], v[160:163], v[186:189], v[40:43]
	v_mfma_f32_16x16x32_bf16 v[36:39], v[148:151], v[194:197], v[36:39]
	v_mfma_f32_16x16x32_bf16 v[32:35], v[160:163], v[194:197], v[32:35]
	v_mfma_f32_16x16x32_bf16 v[60:63], v[152:155], v[172:175], v[60:63]
	v_mfma_f32_16x16x32_bf16 v[56:59], v[164:167], v[172:175], v[56:59]
	v_mfma_f32_16x16x32_bf16 v[52:55], v[152:155], v[182:185], v[52:55]
	v_mfma_f32_16x16x32_bf16 v[48:51], v[164:167], v[182:185], v[48:51]
	v_mfma_f32_16x16x32_bf16 v[44:47], v[152:155], v[190:193], v[44:47]
	v_mfma_f32_16x16x32_bf16 v[40:43], v[164:167], v[190:193], v[40:43]
	v_mfma_f32_16x16x32_bf16 v[36:39], v[152:155], v[198:201], v[36:39]
	v_mfma_f32_16x16x32_bf16 v[32:35], v[164:167], v[198:201], v[32:35]
	s_setprio 0
	s_barrier
	s_add_u32 s88, s27, s40
	s_addc_u32 s89, s28, s41
	s_add_u32 s42, s88, 0x100
	v_add_u32_e32 v148, 0x14000, v134
	s_addc_u32 s43, s89, 0
	v_readfirstlane_b32 s96, v148
	v_lshl_add_u64 v[150:151], s[42:43], 0, v[176:177]
	s_mov_b32 m0, s96
	v_add_u32_e32 v149, 0x16000, v134
	global_load_lds_dwordx4 v[150:151], off
	v_lshl_add_u64 v[150:151], s[42:43], 0, v[132:133]
	v_readfirstlane_b32 s42, v149
	s_mov_b32 m0, s42
	s_nop 0
	global_load_lds_dwordx4 v[150:151], off
	s_waitcnt vmcnt(10)
	s_barrier
	s_setprio 1
	v_mfma_f32_16x16x32_bf16 v[28:31], v[202:205], v[168:171], v[28:31]
	v_mfma_f32_16x16x32_bf16 v[24:27], v[210:213], v[168:171], v[24:27]
	v_mfma_f32_16x16x32_bf16 v[20:23], v[202:205], v[178:181], v[20:23]
	v_mfma_f32_16x16x32_bf16 v[16:19], v[210:213], v[178:181], v[16:19]
	v_mfma_f32_16x16x32_bf16 v[12:15], v[202:205], v[186:189], v[12:15]
	v_mfma_f32_16x16x32_bf16 v[8:11], v[210:213], v[186:189], v[8:11]
	v_mfma_f32_16x16x32_bf16 v[4:7], v[202:205], v[194:197], v[4:7]
	v_mfma_f32_16x16x32_bf16 v[0:3], v[210:213], v[194:197], v[0:3]
	v_mfma_f32_16x16x32_bf16 v[28:31], v[206:209], v[172:175], v[28:31]
	v_mfma_f32_16x16x32_bf16 v[24:27], v[214:217], v[172:175], v[24:27]
	v_mfma_f32_16x16x32_bf16 v[20:23], v[206:209], v[182:185], v[20:23]
	v_mfma_f32_16x16x32_bf16 v[16:19], v[214:217], v[182:185], v[16:19]
	v_mfma_f32_16x16x32_bf16 v[12:15], v[206:209], v[190:193], v[12:15]
	v_mfma_f32_16x16x32_bf16 v[8:11], v[214:217], v[190:193], v[8:11]
	v_mfma_f32_16x16x32_bf16 v[4:7], v[206:209], v[198:201], v[4:7]
	v_mfma_f32_16x16x32_bf16 v[0:3], v[214:217], v[198:201], v[0:3]
	s_setprio 0
	s_barrier
	ds_read_b128 v[160:163], v141 offset:0
	ds_read_b128 v[164:167], v141 offset:1024
	ds_read_b128 v[168:171], v141 offset:2048
	ds_read_b128 v[172:175], v141 offset:3072
	s_add_u32 s42, s29, s40
	v_add_u32_e32 v150, 0x4000, v134
	s_addc_u32 s43, s30, s41
	v_readfirstlane_b32 s96, v150
	v_lshl_add_u64 v[152:153], s[42:43], 0, v[128:129]
	s_mov_b32 m0, s96
	v_add_u32_e32 v151, 0x6000, v134
	ds_read_b128 v[154:157], v140 offset:0
	ds_read_b128 v[178:181], v140 offset:1024
	ds_read_b128 v[182:185], v140 offset:2048
	ds_read_b128 v[186:189], v140 offset:3072
	ds_read_b128 v[190:193], v140 offset:4096
	ds_read_b128 v[194:197], v140 offset:5120
	ds_read_b128 v[198:201], v140 offset:6144
	ds_read_b128 v[202:205], v140 offset:7168
	global_load_lds_dwordx4 v[152:153], off
	v_lshl_add_u64 v[152:153], s[42:43], 0, v[130:131]
	v_readfirstlane_b32 s42, v151
	s_mov_b32 m0, s42
	s_nop 0
	global_load_lds_dwordx4 v[152:153], off
	s_waitcnt vmcnt(10)
	s_waitcnt lgkmcnt(8)
	s_barrier
	s_waitcnt lgkmcnt(0)
	s_waitcnt lgkmcnt(0)
	s_setprio 1
	v_mfma_f32_16x16x32_bf16 v[124:127], v[160:163], v[154:157], v[124:127]
	v_mfma_f32_16x16x32_bf16 v[120:123], v[168:171], v[154:157], v[120:123]
	v_mfma_f32_16x16x32_bf16 v[116:119], v[160:163], v[182:185], v[116:119]
	v_mfma_f32_16x16x32_bf16 v[112:115], v[168:171], v[182:185], v[112:115]
	v_mfma_f32_16x16x32_bf16 v[108:111], v[160:163], v[190:193], v[108:111]
	v_mfma_f32_16x16x32_bf16 v[104:107], v[168:171], v[190:193], v[104:107]
	v_mfma_f32_16x16x32_bf16 v[100:103], v[160:163], v[198:201], v[100:103]
	v_mfma_f32_16x16x32_bf16 v[96:99], v[168:171], v[198:201], v[96:99]
	v_mfma_f32_16x16x32_bf16 v[124:127], v[164:167], v[178:181], v[124:127]
	v_mfma_f32_16x16x32_bf16 v[120:123], v[172:175], v[178:181], v[120:123]
	v_mfma_f32_16x16x32_bf16 v[116:119], v[164:167], v[186:189], v[116:119]
	v_mfma_f32_16x16x32_bf16 v[112:115], v[172:175], v[186:189], v[112:115]
	v_mfma_f32_16x16x32_bf16 v[108:111], v[164:167], v[194:197], v[108:111]
	v_mfma_f32_16x16x32_bf16 v[104:107], v[172:175], v[194:197], v[104:107]
	v_mfma_f32_16x16x32_bf16 v[100:103], v[164:167], v[202:205], v[100:103]
	v_mfma_f32_16x16x32_bf16 v[96:99], v[172:175], v[202:205], v[96:99]
	s_setprio 0
	s_barrier
	s_add_u32 s42, s35, 0x180
	v_add_u32_e32 v152, 0x18000, v134
	s_addc_u32 s43, s45, 0
	v_readfirstlane_b32 s35, v152
	v_add_u32_e32 v153, 0x1a000, v134
	v_lshl_add_u64 v[222:223], s[42:43], 0, v[176:177]
	s_mov_b32 m0, s35
	v_readfirstlane_b32 s35, v153
	ds_read_b128 v[206:209], v139 offset:0
	ds_read_b128 v[210:213], v139 offset:1024
	ds_read_b128 v[214:217], v139 offset:2048
	ds_read_b128 v[218:221], v139 offset:3072
	global_load_lds_dwordx4 v[222:223], off
	v_lshl_add_u64 v[222:223], s[42:43], 0, v[132:133]
	s_mov_b32 m0, s35
	s_nop 0
	global_load_lds_dwordx4 v[222:223], off
	s_waitcnt vmcnt(10)
	s_barrier
	s_waitcnt lgkmcnt(0)
	s_setprio 1
	v_mfma_f32_16x16x32_bf16 v[92:95], v[206:209], v[154:157], v[92:95]
	v_mfma_f32_16x16x32_bf16 v[88:91], v[214:217], v[154:157], v[88:91]
	v_mfma_f32_16x16x32_bf16 v[84:87], v[206:209], v[182:185], v[84:87]
	v_mfma_f32_16x16x32_bf16 v[80:83], v[214:217], v[182:185], v[80:83]
	v_mfma_f32_16x16x32_bf16 v[76:79], v[206:209], v[190:193], v[76:79]
	v_mfma_f32_16x16x32_bf16 v[72:75], v[214:217], v[190:193], v[72:75]
	v_mfma_f32_16x16x32_bf16 v[68:71], v[206:209], v[198:201], v[68:71]
	v_mfma_f32_16x16x32_bf16 v[64:67], v[214:217], v[198:201], v[64:67]
	v_mfma_f32_16x16x32_bf16 v[92:95], v[210:213], v[178:181], v[92:95]
	v_mfma_f32_16x16x32_bf16 v[88:91], v[218:221], v[178:181], v[88:91]
	v_mfma_f32_16x16x32_bf16 v[84:87], v[210:213], v[186:189], v[84:87]
	v_mfma_f32_16x16x32_bf16 v[80:83], v[218:221], v[186:189], v[80:83]
	v_mfma_f32_16x16x32_bf16 v[76:79], v[210:213], v[194:197], v[76:79]
	v_mfma_f32_16x16x32_bf16 v[72:75], v[218:221], v[194:197], v[72:75]
	v_mfma_f32_16x16x32_bf16 v[68:71], v[210:213], v[202:205], v[68:71]
	v_mfma_f32_16x16x32_bf16 v[64:67], v[218:221], v[202:205], v[64:67]
	s_setprio 0
	s_add_u32 s42, s51, 0x180
	v_add_u32_e32 v154, 0x8000, v134
	s_addc_u32 s43, s54, 0
	v_readfirstlane_b32 s35, v154
	v_add_u32_e32 v155, 0xa000, v134
	v_lshl_add_u64 v[156:157], s[42:43], 0, v[128:129]
	s_mov_b32 m0, s35
	v_readfirstlane_b32 s35, v155
	s_barrier
	ds_read_b128 v[178:181], v138 offset:0
	ds_read_b128 v[182:185], v138 offset:1024
	ds_read_b128 v[186:189], v138 offset:2048
	ds_read_b128 v[190:193], v138 offset:3072
	ds_read_b128 v[194:197], v138 offset:4096
	ds_read_b128 v[198:201], v138 offset:5120
	ds_read_b128 v[202:205], v138 offset:6144
	ds_read_b128 v[222:225], v138 offset:7168
	global_load_lds_dwordx4 v[156:157], off
	v_lshl_add_u64 v[156:157], s[42:43], 0, v[130:131]
	s_mov_b32 m0, s35
	s_nop 0
	global_load_lds_dwordx4 v[156:157], off
	s_waitcnt vmcnt(10)
	s_barrier
	s_waitcnt lgkmcnt(0)
	s_setprio 1
	v_mfma_f32_16x16x32_bf16 v[60:63], v[160:163], v[178:181], v[60:63]
	v_mfma_f32_16x16x32_bf16 v[56:59], v[168:171], v[178:181], v[56:59]
	v_mfma_f32_16x16x32_bf16 v[52:55], v[160:163], v[186:189], v[52:55]
	v_mfma_f32_16x16x32_bf16 v[48:51], v[168:171], v[186:189], v[48:51]
	v_mfma_f32_16x16x32_bf16 v[44:47], v[160:163], v[194:197], v[44:47]
	v_mfma_f32_16x16x32_bf16 v[40:43], v[168:171], v[194:197], v[40:43]
	v_mfma_f32_16x16x32_bf16 v[36:39], v[160:163], v[202:205], v[36:39]
	v_mfma_f32_16x16x32_bf16 v[32:35], v[168:171], v[202:205], v[32:35]
	v_mfma_f32_16x16x32_bf16 v[60:63], v[164:167], v[182:185], v[60:63]
	v_mfma_f32_16x16x32_bf16 v[56:59], v[172:175], v[182:185], v[56:59]
	v_mfma_f32_16x16x32_bf16 v[52:55], v[164:167], v[190:193], v[52:55]
	v_mfma_f32_16x16x32_bf16 v[48:51], v[172:175], v[190:193], v[48:51]
	v_mfma_f32_16x16x32_bf16 v[44:47], v[164:167], v[198:201], v[44:47]
	v_mfma_f32_16x16x32_bf16 v[40:43], v[172:175], v[198:201], v[40:43]
	v_mfma_f32_16x16x32_bf16 v[36:39], v[164:167], v[222:225], v[36:39]
	v_mfma_f32_16x16x32_bf16 v[32:35], v[172:175], v[222:225], v[32:35]
	s_setprio 0
	s_barrier
	s_add_u32 s42, s88, 0x180
	v_add_u32_e32 v156, 0x1c000, v134
	s_addc_u32 s43, s89, 0
	v_readfirstlane_b32 s35, v156
	v_add_u32_e32 v157, 0x1e000, v134
	v_lshl_add_u64 v[160:161], s[42:43], 0, v[176:177]
	s_mov_b32 m0, s35
	v_readfirstlane_b32 s35, v157
	global_load_lds_dwordx4 v[160:161], off
	v_lshl_add_u64 v[160:161], s[42:43], 0, v[132:133]
	s_mov_b32 m0, s35
	s_nop 0
	global_load_lds_dwordx4 v[160:161], off
	s_waitcnt vmcnt(10)
	s_barrier
	s_setprio 1
	v_mfma_f32_16x16x32_bf16 v[28:31], v[206:209], v[178:181], v[28:31]
	v_mfma_f32_16x16x32_bf16 v[24:27], v[214:217], v[178:181], v[24:27]
	v_mfma_f32_16x16x32_bf16 v[20:23], v[206:209], v[186:189], v[20:23]
	v_mfma_f32_16x16x32_bf16 v[16:19], v[214:217], v[186:189], v[16:19]
	v_mfma_f32_16x16x32_bf16 v[12:15], v[206:209], v[194:197], v[12:15]
	v_mfma_f32_16x16x32_bf16 v[8:11], v[214:217], v[194:197], v[8:11]
	v_mfma_f32_16x16x32_bf16 v[4:7], v[206:209], v[202:205], v[4:7]
	v_mfma_f32_16x16x32_bf16 v[0:3], v[214:217], v[202:205], v[0:3]
	v_mfma_f32_16x16x32_bf16 v[28:31], v[210:213], v[182:185], v[28:31]
	v_mfma_f32_16x16x32_bf16 v[24:27], v[218:221], v[182:185], v[24:27]
	v_mfma_f32_16x16x32_bf16 v[20:23], v[210:213], v[190:193], v[20:23]
	v_mfma_f32_16x16x32_bf16 v[16:19], v[218:221], v[190:193], v[16:19]
	v_mfma_f32_16x16x32_bf16 v[12:15], v[210:213], v[198:201], v[12:15]
	v_mfma_f32_16x16x32_bf16 v[8:11], v[218:221], v[198:201], v[8:11]
	v_mfma_f32_16x16x32_bf16 v[4:7], v[210:213], v[222:225], v[4:7]
	v_mfma_f32_16x16x32_bf16 v[0:3], v[218:221], v[222:225], v[0:3]
	s_setprio 0
	s_add_i32 s31, s31, 2
	s_add_u32 s40, s40, 0x100
	s_addc_u32 s41, s41, 0
	s_cmp_gt_u32 s31, 11
	s_barrier
	s_cbranch_scc0 .LBB0_105
	s_add_u32 s2, s1, 0x780
	s_addc_u32 s3, s26, 0
	v_readfirstlane_b32 s1, v158
	v_lshl_add_u64 v[132:133], s[2:3], 0, v[128:129]
	s_mov_b32 m0, s1
	v_readfirstlane_b32 s1, v159
	ds_read_b128 v[160:163], v145 offset:0
	ds_read_b128 v[164:167], v145 offset:1024
	ds_read_b128 v[168:171], v145 offset:2048
	ds_read_b128 v[172:175], v145 offset:3072
	ds_read_b128 v[178:181], v144 offset:0
	ds_read_b128 v[182:185], v144 offset:1024
	ds_read_b128 v[186:189], v144 offset:2048
	ds_read_b128 v[190:193], v144 offset:3072
	ds_read_b128 v[194:197], v144 offset:4096
	ds_read_b128 v[198:201], v144 offset:5120
	ds_read_b128 v[202:205], v144 offset:6144
	ds_read_b128 v[206:209], v144 offset:7168
	global_load_lds_dwordx4 v[132:133], off
	v_lshl_add_u64 v[132:133], s[2:3], 0, v[130:131]
	s_mov_b32 m0, s1
	s_nop 0
	global_load_lds_dwordx4 v[132:133], off
	s_waitcnt vmcnt(10)
	s_barrier
	s_waitcnt lgkmcnt(0)
	s_waitcnt lgkmcnt(0)
	s_setprio 1
	v_mfma_f32_16x16x32_bf16 v[124:127], v[160:163], v[178:181], v[124:127]
	v_mfma_f32_16x16x32_bf16 v[120:123], v[168:171], v[178:181], v[120:123]
	v_mfma_f32_16x16x32_bf16 v[116:119], v[160:163], v[186:189], v[116:119]
	v_mfma_f32_16x16x32_bf16 v[112:115], v[168:171], v[186:189], v[112:115]
	v_mfma_f32_16x16x32_bf16 v[100:103], v[160:163], v[202:205], v[100:103]
	v_mfma_f32_16x16x32_bf16 v[96:99], v[168:171], v[202:205], v[96:99]
	v_mfma_f32_16x16x32_bf16 v[124:127], v[164:167], v[182:185], v[124:127]
	v_mfma_f32_16x16x32_bf16 v[120:123], v[172:175], v[182:185], v[120:123]
	v_mfma_f32_16x16x32_bf16 v[116:119], v[164:167], v[190:193], v[116:119]
	v_mfma_f32_16x16x32_bf16 v[112:115], v[172:175], v[190:193], v[112:115]
	v_mfma_f32_16x16x32_bf16 v[108:111], v[160:163], v[194:197], v[108:111]
	v_mfma_f32_16x16x32_bf16 v[104:107], v[168:171], v[194:197], v[104:107]
	v_mfma_f32_16x16x32_bf16 v[100:103], v[164:167], v[206:209], v[100:103]
	v_mfma_f32_16x16x32_bf16 v[96:99], v[172:175], v[206:209], v[96:99]
	v_mfma_f32_16x16x32_bf16 v[210:213], v[164:167], v[198:201], v[108:111]
	v_mfma_f32_16x16x32_bf16 v[214:217], v[172:175], v[198:201], v[104:107]
	s_setprio 0
	s_barrier
	ds_read_b128 v[104:107], v143 offset:0
	ds_read_b128 v[108:111], v143 offset:1024
	ds_read_b128 v[218:221], v143 offset:2048
	ds_read_b128 v[222:225], v143 offset:3072
	s_waitcnt vmcnt(8)
	s_barrier
	s_waitcnt lgkmcnt(0)
	s_setprio 1
	v_mfma_f32_16x16x32_bf16 v[92:95], v[104:107], v[178:181], v[92:95]
	v_mfma_f32_16x16x32_bf16 v[88:91], v[218:221], v[178:181], v[88:91]
	v_mfma_f32_16x16x32_bf16 v[76:79], v[104:107], v[194:197], v[76:79]
	v_mfma_f32_16x16x32_bf16 v[72:75], v[218:221], v[194:197], v[72:75]
	v_mfma_f32_16x16x32_bf16 v[68:71], v[104:107], v[202:205], v[68:71]
	v_mfma_f32_16x16x32_bf16 v[92:95], v[108:111], v[182:185], v[92:95]
	v_mfma_f32_16x16x32_bf16 v[88:91], v[222:225], v[182:185], v[88:91]
	v_mfma_f32_16x16x32_bf16 v[84:87], v[104:107], v[186:189], v[84:87]
	v_mfma_f32_16x16x32_bf16 v[80:83], v[218:221], v[186:189], v[80:83]
	v_mfma_f32_16x16x32_bf16 v[76:79], v[108:111], v[198:201], v[76:79]
	v_mfma_f32_16x16x32_bf16 v[72:75], v[222:225], v[198:201], v[72:75]
	v_mfma_f32_16x16x32_bf16 v[68:71], v[108:111], v[206:209], v[68:71]
	v_mfma_f32_16x16x32_bf16 v[64:67], v[218:221], v[202:205], v[64:67]
	v_mfma_f32_16x16x32_bf16 v[178:181], v[108:111], v[190:193], v[84:87]
	v_mfma_f32_16x16x32_bf16 v[182:185], v[222:225], v[190:193], v[80:83]
	v_mfma_f32_16x16x32_bf16 v[186:189], v[222:225], v[206:209], v[64:67]
	s_setprio 0
	s_barrier
	ds_read_b128 v[64:67], v142 offset:0
	ds_read_b128 v[80:83], v142 offset:1024
	ds_read_b128 v[84:87], v142 offset:2048
	ds_read_b128 v[190:193], v142 offset:3072
	ds_read_b128 v[194:197], v142 offset:4096
	ds_read_b128 v[198:201], v142 offset:5120
	ds_read_b128 v[202:205], v142 offset:6144
	ds_read_b128 v[142:145], v142 offset:7168
	s_waitcnt vmcnt(4)
	s_barrier
	s_waitcnt lgkmcnt(0)
	s_setprio 1
	s_nop 0
	v_mfma_f32_16x16x32_bf16 v[60:63], v[160:163], v[64:67], v[60:63]
	v_mfma_f32_16x16x32_bf16 v[56:59], v[168:171], v[64:67], v[56:59]
	v_mfma_f32_16x16x32_bf16 v[60:63], v[164:167], v[80:83], v[60:63]
	v_mfma_f32_16x16x32_bf16 v[56:59], v[172:175], v[80:83], v[56:59]
	v_mfma_f32_16x16x32_bf16 v[52:55], v[160:163], v[84:87], v[52:55]
	v_mfma_f32_16x16x32_bf16 v[48:51], v[168:171], v[84:87], v[48:51]
	v_mfma_f32_16x16x32_bf16 v[44:47], v[160:163], v[194:197], v[44:47]
	v_mfma_f32_16x16x32_bf16 v[40:43], v[168:171], v[194:197], v[40:43]
	v_mfma_f32_16x16x32_bf16 v[36:39], v[160:163], v[202:205], v[36:39]
	v_mfma_f32_16x16x32_bf16 v[32:35], v[168:171], v[202:205], v[32:35]
	v_mfma_f32_16x16x32_bf16 v[206:209], v[164:167], v[190:193], v[52:55]
	v_mfma_f32_16x16x32_bf16 v[226:229], v[172:175], v[190:193], v[48:51]
	v_mfma_f32_16x16x32_bf16 v[232:235], v[164:167], v[198:201], v[44:47]
	v_mfma_f32_16x16x32_bf16 v[238:241], v[172:175], v[198:201], v[40:43]
	v_mfma_f32_16x16x32_bf16 v[158:161], v[164:167], v[142:145], v[36:39]
	v_mfma_f32_16x16x32_bf16 v[162:165], v[172:175], v[142:145], v[32:35]
	s_setprio 0
	s_setprio 1
	v_mfma_f32_16x16x32_bf16 v[28:31], v[104:107], v[64:67], v[28:31]
	v_mfma_f32_16x16x32_bf16 v[24:27], v[218:221], v[64:67], v[24:27]
	v_mfma_f32_16x16x32_bf16 v[12:15], v[104:107], v[194:197], v[12:15]
	v_mfma_f32_16x16x32_bf16 v[8:11], v[218:221], v[194:197], v[8:11]
	v_mfma_f32_16x16x32_bf16 v[28:31], v[108:111], v[80:83], v[28:31]
	v_mfma_f32_16x16x32_bf16 v[24:27], v[222:225], v[80:83], v[24:27]
	v_mfma_f32_16x16x32_bf16 v[20:23], v[104:107], v[84:87], v[20:23]
	v_mfma_f32_16x16x32_bf16 v[16:19], v[218:221], v[84:87], v[16:19]
	v_mfma_f32_16x16x32_bf16 v[12:15], v[108:111], v[198:201], v[12:15]
	v_mfma_f32_16x16x32_bf16 v[8:11], v[222:225], v[198:201], v[8:11]
	v_mfma_f32_16x16x32_bf16 v[4:7], v[104:107], v[202:205], v[4:7]
	v_mfma_f32_16x16x32_bf16 v[0:3], v[218:221], v[202:205], v[0:3]
	v_mfma_f32_16x16x32_bf16 v[166:169], v[108:111], v[190:193], v[20:23]
	v_mfma_f32_16x16x32_bf16 v[170:173], v[222:225], v[190:193], v[16:19]
	v_mfma_f32_16x16x32_bf16 v[190:193], v[108:111], v[142:145], v[4:7]
	v_mfma_f32_16x16x32_bf16 v[142:145], v[222:225], v[142:145], v[0:3]
	s_setprio 0
	s_barrier
	ds_read_b128 v[0:3], v141 offset:0
	ds_read_b128 v[4:7], v141 offset:1024
	ds_read_b128 v[194:197], v141 offset:2048
	ds_read_b128 v[198:201], v141 offset:3072
	ds_read_b128 v[16:19], v140 offset:0
	ds_read_b128 v[20:23], v140 offset:1024
	ds_read_b128 v[40:43], v140 offset:2048
	ds_read_b128 v[44:47], v140 offset:3072
	ds_read_b128 v[64:67], v140 offset:4096
	ds_read_b128 v[202:205], v140 offset:5120
	ds_read_b128 v[218:221], v140 offset:6144
	ds_read_b128 v[222:225], v140 offset:7168
	s_waitcnt vmcnt(2)
	s_barrier
	s_waitcnt lgkmcnt(0)
	s_waitcnt lgkmcnt(0)
	s_setprio 1
	v_mfma_f32_16x16x32_bf16 v[32:35], v[0:3], v[16:19], v[124:127]
	v_mfma_f32_16x16x32_bf16 v[104:107], v[4:7], v[20:23], v[32:35]
	v_mfma_f32_16x16x32_bf16 v[32:35], v[194:197], v[16:19], v[120:123]
	v_mfma_f32_16x16x32_bf16 v[108:111], v[198:201], v[20:23], v[32:35]
	v_mfma_f32_16x16x32_bf16 v[32:35], v[0:3], v[40:43], v[116:119]
	v_mfma_f32_16x16x32_bf16 v[80:83], v[4:7], v[44:47], v[32:35]
	v_mfma_f32_16x16x32_bf16 v[32:35], v[194:197], v[40:43], v[112:115]
	v_mfma_f32_16x16x32_bf16 v[84:87], v[198:201], v[44:47], v[32:35]
	v_mfma_f32_16x16x32_bf16 v[32:35], v[0:3], v[64:67], v[210:213]
	v_mfma_f32_16x16x32_bf16 v[48:51], v[4:7], v[202:205], v[32:35]
	v_mfma_f32_16x16x32_bf16 v[32:35], v[194:197], v[64:67], v[214:217]
	v_mfma_f32_16x16x32_bf16 v[52:55], v[198:201], v[202:205], v[32:35]
	v_mfma_f32_16x16x32_bf16 v[32:35], v[0:3], v[218:221], v[100:103]
	v_mfma_f32_16x16x32_bf16 v[36:39], v[194:197], v[218:221], v[96:99]
	v_mfma_f32_16x16x32_bf16 v[32:35], v[4:7], v[222:225], v[32:35]
	v_mfma_f32_16x16x32_bf16 v[36:39], v[198:201], v[222:225], v[36:39]
	s_setprio 0
	s_barrier
	ds_read_b128 v[210:213], v139 offset:0
	ds_read_b128 v[214:217], v139 offset:1024
	ds_read_b128 v[242:245], v139 offset:2048
	ds_read_b128 v[246:249], v139 offset:3072
	s_waitcnt vmcnt(0)
	s_barrier
	s_waitcnt lgkmcnt(0)
	s_setprio 1
	v_mfma_f32_16x16x32_bf16 v[92:95], v[210:213], v[16:19], v[92:95]
	v_mfma_f32_16x16x32_bf16 v[16:19], v[242:245], v[16:19], v[88:91]
	v_mfma_f32_16x16x32_bf16 v[124:127], v[246:249], v[20:23], v[16:19]
	v_mfma_f32_16x16x32_bf16 v[16:19], v[210:213], v[40:43], v[178:181]
	v_mfma_f32_16x16x32_bf16 v[112:115], v[214:217], v[44:47], v[16:19]
	v_mfma_f32_16x16x32_bf16 v[16:19], v[242:245], v[40:43], v[182:185]
	v_mfma_f32_16x16x32_bf16 v[116:119], v[246:249], v[44:47], v[16:19]
	v_mfma_f32_16x16x32_bf16 v[16:19], v[210:213], v[64:67], v[76:79]
	v_mfma_f32_16x16x32_bf16 v[96:99], v[214:217], v[202:205], v[16:19]
	v_mfma_f32_16x16x32_bf16 v[16:19], v[242:245], v[64:67], v[72:75]
	v_mfma_f32_16x16x32_bf16 v[100:103], v[246:249], v[202:205], v[16:19]
	v_mfma_f32_16x16x32_bf16 v[16:19], v[210:213], v[218:221], v[68:71]
	v_mfma_f32_16x16x32_bf16 v[64:67], v[214:217], v[222:225], v[16:19]
	v_mfma_f32_16x16x32_bf16 v[16:19], v[242:245], v[218:221], v[186:189]
	v_mfma_f32_16x16x32_bf16 v[120:123], v[214:217], v[20:23], v[92:95]
	v_mfma_f32_16x16x32_bf16 v[68:71], v[246:249], v[222:225], v[16:19]
	s_setprio 0
	s_barrier
	ds_read_b128 v[92:95], v138 offset:0
	ds_read_b128 v[178:181], v138 offset:1024
	ds_read_b128 v[182:185], v138 offset:2048
	ds_read_b128 v[186:189], v138 offset:3072
	ds_read_b128 v[202:205], v138 offset:4096
	ds_read_b128 v[218:221], v138 offset:5120
	ds_read_b128 v[222:225], v138 offset:6144
	ds_read_b128 v[138:141], v138 offset:7168
	s_barrier
	s_waitcnt lgkmcnt(0)
	s_setprio 1
	v_mfma_f32_16x16x32_bf16 v[16:19], v[0:3], v[92:95], v[60:63]
	v_mfma_f32_16x16x32_bf16 v[72:75], v[4:7], v[178:181], v[16:19]
	v_mfma_f32_16x16x32_bf16 v[16:19], v[194:197], v[92:95], v[56:59]
	v_mfma_f32_16x16x32_bf16 v[76:79], v[198:201], v[178:181], v[16:19]
	v_mfma_f32_16x16x32_bf16 v[16:19], v[0:3], v[182:185], v[206:209]
	v_mfma_f32_16x16x32_bf16 v[40:43], v[4:7], v[186:189], v[16:19]
	v_mfma_f32_16x16x32_bf16 v[16:19], v[194:197], v[182:185], v[226:229]
	v_mfma_f32_16x16x32_bf16 v[44:47], v[198:201], v[186:189], v[16:19]
	v_mfma_f32_16x16x32_bf16 v[16:19], v[0:3], v[202:205], v[232:235]
	v_mfma_f32_16x16x32_bf16 v[0:3], v[0:3], v[222:225], v[158:161]
	v_mfma_f32_16x16x32_bf16 v[16:19], v[4:7], v[218:221], v[16:19]
	v_mfma_f32_16x16x32_bf16 v[20:23], v[194:197], v[202:205], v[238:241]
	v_mfma_f32_16x16x32_bf16 v[0:3], v[4:7], v[138:141], v[0:3]
	v_mfma_f32_16x16x32_bf16 v[4:7], v[194:197], v[222:225], v[162:165]
	v_mfma_f32_16x16x32_bf16 v[20:23], v[198:201], v[218:221], v[20:23]
	v_mfma_f32_16x16x32_bf16 v[4:7], v[198:201], v[138:141], v[4:7]
	s_setprio 0
	s_setprio 1
	v_mfma_f32_16x16x32_bf16 v[24:27], v[242:245], v[92:95], v[24:27]
	v_mfma_f32_16x16x32_bf16 v[28:31], v[210:213], v[92:95], v[28:31]
	v_mfma_f32_16x16x32_bf16 v[92:95], v[246:249], v[178:181], v[24:27]
	v_mfma_f32_16x16x32_bf16 v[24:27], v[210:213], v[182:185], v[166:169]
	v_mfma_f32_16x16x32_bf16 v[56:59], v[214:217], v[186:189], v[24:27]
	v_mfma_f32_16x16x32_bf16 v[24:27], v[242:245], v[182:185], v[170:173]
	v_mfma_f32_16x16x32_bf16 v[12:15], v[210:213], v[202:205], v[12:15]
	v_mfma_f32_16x16x32_bf16 v[8:11], v[242:245], v[202:205], v[8:11]
	v_mfma_f32_16x16x32_bf16 v[88:91], v[214:217], v[178:181], v[28:31]
	v_mfma_f32_16x16x32_bf16 v[60:63], v[246:249], v[186:189], v[24:27]
	v_mfma_f32_16x16x32_bf16 v[24:27], v[214:217], v[218:221], v[12:15]
	v_mfma_f32_16x16x32_bf16 v[28:31], v[246:249], v[218:221], v[8:11]
	v_mfma_f32_16x16x32_bf16 v[8:11], v[210:213], v[222:225], v[190:193]
	v_mfma_f32_16x16x32_bf16 v[12:15], v[242:245], v[222:225], v[142:145]
	v_mfma_f32_16x16x32_bf16 v[8:11], v[214:217], v[138:141], v[8:11]
	v_mfma_f32_16x16x32_bf16 v[12:15], v[246:249], v[138:141], v[12:15]
	s_setprio 0
	s_cmpk_lt_u32 s11, 0x100
	s_barrier
	s_cbranch_scc0 .LBB0_108
	s_barrier

.LBB0_140:
	v_and_b32_e32 v0, 15, v7
	v_and_b32_e32 v1, 48, v7
	v_lshlrev_b32_e32 v0, 6, v0
	v_lshlrev_b32_e32 v7, 2, v7
	v_or_b32_e32 v8, v0, v1
	v_and_b32_e32 v7, 32, v7
	s_lshl_b32 s1, s35, 13
	v_bitop3_b32 v144, v8, s1, v7 bitop3:0xde
	s_lshl_b32 s1, s11, 6
	v_bitop3_b32 v0, v0, v7, v1 bitop3:0x36
	s_and_b32 s1, s1, 0x3000
	v_or_b32_e32 v0, s1, v0
	s_add_u32 s1, s48, s30
	v_bfe_u32 v8, v134, 6, 2
	s_addc_u32 s26, s49, s31
	v_and_b32_e32 v1, 31, v4
	v_lshlrev_b32_e32 v7, 1, v4
	v_lshrrev_b32_e32 v6, 13, v6
	v_add_u32_e32 v4, v4, v8
	s_add_u32 s27, s52, s42
	v_and_b32_e32 v7, 24, v7
	v_and_b32_e32 v6, 4, v6
	v_sub_u32_e32 v1, v4, v1
	s_addc_u32 s28, s53, s43
	v_add3_u32 v1, v1, v7, v6
	v_lshl_or_b32 v136, v1, 11, v2
	v_and_b32_e32 v1, 31, v3
	v_lshlrev_b32_e32 v4, 1, v3
	v_lshrrev_b32_e32 v5, 13, v5
	v_add_u32_e32 v3, v3, v8
	s_add_u32 s2, s48, s2
	v_and_b32_e32 v4, 24, v4
	v_and_b32_e32 v5, 4, v5
	v_sub_u32_e32 v1, v3, v1
	s_addc_u32 s3, s49, s3
	v_add3_u32 v1, v1, v4, v5
	s_add_u32 s20, s52, s20
	v_or_b32_e32 v145, 0x10000, v0
	v_or_b32_e32 v143, 0x14000, v0
	v_lshl_or_b32 v137, v1, 11, v2
	s_addc_u32 s21, s53, s21
	v_or_b32_e32 v141, 0x18000, v0
	v_or_b32_e32 v139, 0x1c000, v0
	v_cndmask_b32_e64 v0, v128, v136, s[40:41]
	v_cndmask_b32_e64 v132, v176, v137, s[40:41]
	v_mov_b32_e32 v176, v0
	s_add_u32 s29, s1, 0x100
	v_mov_b32_e32 v0, 0
	v_add_u32_e32 v142, 0x4000, v144
	v_add_u32_e32 v140, 0x8000, v144
	v_add_u32_e32 v138, 0xc000, v144
	v_mov_b32_e32 v133, v177
	s_addc_u32 s30, s26, 0
	s_mov_b32 s31, -2
	s_mov_b64 s[38:39], 0
	v_mov_b32_e32 v1, v0
	v_mov_b32_e32 v2, v0
	v_mov_b32_e32 v3, v0
	v_mov_b32_e32 v4, v0
	v_mov_b32_e32 v5, v0
	v_mov_b32_e32 v6, v0
	v_mov_b32_e32 v7, v0
	v_mov_b32_e32 v8, v0
	v_mov_b32_e32 v9, v0
	v_mov_b32_e32 v10, v0
	v_mov_b32_e32 v11, v0
	v_mov_b32_e32 v12, v0
	v_mov_b32_e32 v13, v0
	v_mov_b32_e32 v14, v0
	v_mov_b32_e32 v15, v0
	v_mov_b32_e32 v16, v0
	v_mov_b32_e32 v17, v0
	v_mov_b32_e32 v18, v0
	v_mov_b32_e32 v19, v0
	v_mov_b32_e32 v20, v0
	v_mov_b32_e32 v21, v0
	v_mov_b32_e32 v22, v0
	v_mov_b32_e32 v23, v0
	v_mov_b32_e32 v24, v0
	v_mov_b32_e32 v25, v0
	v_mov_b32_e32 v26, v0
	v_mov_b32_e32 v27, v0
	v_mov_b32_e32 v28, v0
	v_mov_b32_e32 v29, v0
	v_mov_b32_e32 v30, v0
	v_mov_b32_e32 v31, v0
	v_mov_b32_e32 v32, v0
	v_mov_b32_e32 v33, v0
	v_mov_b32_e32 v34, v0
	v_mov_b32_e32 v35, v0
	v_mov_b32_e32 v36, v0
	v_mov_b32_e32 v37, v0
	v_mov_b32_e32 v38, v0
	v_mov_b32_e32 v39, v0
	v_mov_b32_e32 v40, v0
	v_mov_b32_e32 v41, v0
	v_mov_b32_e32 v42, v0
	v_mov_b32_e32 v43, v0
	v_mov_b32_e32 v44, v0
	v_mov_b32_e32 v45, v0
	v_mov_b32_e32 v46, v0
	v_mov_b32_e32 v47, v0
	v_mov_b32_e32 v48, v0
	v_mov_b32_e32 v49, v0
	v_mov_b32_e32 v50, v0
	v_mov_b32_e32 v51, v0
	v_mov_b32_e32 v52, v0
	v_mov_b32_e32 v53, v0
	v_mov_b32_e32 v54, v0
	v_mov_b32_e32 v55, v0
	v_mov_b32_e32 v56, v0
	v_mov_b32_e32 v57, v0
	v_mov_b32_e32 v58, v0
	v_mov_b32_e32 v59, v0
	v_mov_b32_e32 v60, v0
	v_mov_b32_e32 v61, v0
	v_mov_b32_e32 v62, v0
	v_mov_b32_e32 v63, v0
	s_nop 0
	v_mov_b32_e32 v64, v0
	v_mov_b32_e32 v65, v0
	v_mov_b32_e32 v66, v0
	v_mov_b32_e32 v67, v0
	v_mov_b32_e32 v68, v0
	v_mov_b32_e32 v69, v0
	v_mov_b32_e32 v70, v0
	v_mov_b32_e32 v71, v0
	v_mov_b32_e32 v72, v0
	v_mov_b32_e32 v73, v0
	v_mov_b32_e32 v74, v0
	v_mov_b32_e32 v75, v0
	v_mov_b32_e32 v76, v0
	v_mov_b32_e32 v77, v0
	v_mov_b32_e32 v78, v0
	v_mov_b32_e32 v79, v0
	v_mov_b32_e32 v80, v0
	v_mov_b32_e32 v81, v0
	v_mov_b32_e32 v82, v0
	v_mov_b32_e32 v83, v0
	v_mov_b32_e32 v84, v0
	v_mov_b32_e32 v85, v0
	v_mov_b32_e32 v86, v0
	v_mov_b32_e32 v87, v0
	v_mov_b32_e32 v88, v0
	v_mov_b32_e32 v89, v0
	v_mov_b32_e32 v90, v0
	v_mov_b32_e32 v91, v0
	v_mov_b32_e32 v92, v0
	v_mov_b32_e32 v93, v0
	v_mov_b32_e32 v94, v0
	v_mov_b32_e32 v95, v0
	v_mov_b32_e32 v96, v0
	v_mov_b32_e32 v97, v0
	v_mov_b32_e32 v98, v0
	v_mov_b32_e32 v99, v0
	v_mov_b32_e32 v100, v0
	v_mov_b32_e32 v101, v0
	v_mov_b32_e32 v102, v0
	v_mov_b32_e32 v103, v0
	v_mov_b32_e32 v104, v0
	v_mov_b32_e32 v105, v0
	v_mov_b32_e32 v106, v0
	v_mov_b32_e32 v107, v0
	v_mov_b32_e32 v108, v0
	v_mov_b32_e32 v109, v0
	v_mov_b32_e32 v110, v0
	v_mov_b32_e32 v111, v0
	v_mov_b32_e32 v112, v0
	v_mov_b32_e32 v113, v0
	v_mov_b32_e32 v114, v0
	v_mov_b32_e32 v115, v0
	v_mov_b32_e32 v116, v0
	v_mov_b32_e32 v117, v0
	v_mov_b32_e32 v118, v0
	v_mov_b32_e32 v119, v0
	v_mov_b32_e32 v120, v0
	v_mov_b32_e32 v121, v0
	v_mov_b32_e32 v122, v0
	v_mov_b32_e32 v123, v0
	v_mov_b32_e32 v124, v0
	v_mov_b32_e32 v125, v0
	v_mov_b32_e32 v126, v0
	v_mov_b32_e32 v127, v0
.LBB0_141:
	ds_read_b128 v[148:151], v145 offset:0
	ds_read_b128 v[152:155], v145 offset:1024
	ds_read_b128 v[160:163], v145 offset:2048
	ds_read_b128 v[164:167], v145 offset:3072
	s_add_u32 s35, s1, s38
	s_addc_u32 s41, s26, s39
	s_add_u32 s40, s35, 0x80
	v_add_u32_e32 v158, 0xc000, v134
	s_addc_u32 s41, s41, 0
	v_readfirstlane_b32 s35, v158
	v_add_u32_e32 v159, 0xe000, v134
	v_lshl_add_u64 v[146:147], s[40:41], 0, v[128:129]
	s_mov_b32 m0, s35
	v_readfirstlane_b32 s35, v159
	ds_read_b128 v[168:171], v144 offset:0
	ds_read_b128 v[172:175], v144 offset:1024
	ds_read_b128 v[178:181], v144 offset:2048
	ds_read_b128 v[182:185], v144 offset:3072
	ds_read_b128 v[186:189], v144 offset:4096
	ds_read_b128 v[190:193], v144 offset:5120
	ds_read_b128 v[194:197], v144 offset:6144
	ds_read_b128 v[198:201], v144 offset:7168
	global_load_lds_dwordx4 v[146:147], off
	v_lshl_add_u64 v[146:147], s[40:41], 0, v[130:131]
	s_mov_b32 m0, s35
	s_nop 0
	global_load_lds_dwordx4 v[146:147], off
	s_waitcnt vmcnt(10)
	s_waitcnt lgkmcnt(8)
	s_barrier
	s_waitcnt lgkmcnt(0)
	s_waitcnt lgkmcnt(0)
	s_setprio 1
	v_mfma_f32_16x16x32_bf16 v[124:127], v[148:151], v[168:171], v[124:127]
	v_mfma_f32_16x16x32_bf16 v[120:123], v[160:163], v[168:171], v[120:123]
	v_mfma_f32_16x16x32_bf16 v[116:119], v[148:151], v[178:181], v[116:119]
	v_mfma_f32_16x16x32_bf16 v[112:115], v[160:163], v[178:181], v[112:115]
	v_mfma_f32_16x16x32_bf16 v[108:111], v[148:151], v[186:189], v[108:111]
	v_mfma_f32_16x16x32_bf16 v[104:107], v[160:163], v[186:189], v[104:107]
	v_mfma_f32_16x16x32_bf16 v[100:103], v[148:151], v[194:197], v[100:103]
	v_mfma_f32_16x16x32_bf16 v[96:99], v[160:163], v[194:197], v[96:99]
	v_mfma_f32_16x16x32_bf16 v[124:127], v[152:155], v[172:175], v[124:127]
	v_mfma_f32_16x16x32_bf16 v[120:123], v[164:167], v[172:175], v[120:123]
	v_mfma_f32_16x16x32_bf16 v[116:119], v[152:155], v[182:185], v[116:119]
	v_mfma_f32_16x16x32_bf16 v[112:115], v[164:167], v[182:185], v[112:115]
	v_mfma_f32_16x16x32_bf16 v[108:111], v[152:155], v[190:193], v[108:111]
	v_mfma_f32_16x16x32_bf16 v[104:107], v[164:167], v[190:193], v[104:107]
	v_mfma_f32_16x16x32_bf16 v[100:103], v[152:155], v[198:201], v[100:103]
	v_mfma_f32_16x16x32_bf16 v[96:99], v[164:167], v[198:201], v[96:99]
	s_setprio 0
	s_barrier
	s_add_u32 s35, s27, s38
	s_addc_u32 s42, s28, s39
	s_add_u32 s40, s35, 0x100
	v_add_u32_e32 v146, 0x10000, v134
	s_addc_u32 s41, s42, 0
	v_readfirstlane_b32 s43, v146
	v_lshl_add_u64 v[156:157], s[40:41], 0, v[176:177]
	s_mov_b32 m0, s43
	v_add_u32_e32 v147, 0x12000, v134
	ds_read_b128 v[202:205], v143 offset:0
	ds_read_b128 v[206:209], v143 offset:1024
	ds_read_b128 v[210:213], v143 offset:2048
	ds_read_b128 v[214:217], v143 offset:3072
	global_load_lds_dwordx4 v[156:157], off
	v_lshl_add_u64 v[156:157], s[40:41], 0, v[132:133]
	v_readfirstlane_b32 s40, v147
	s_mov_b32 m0, s40
	s_nop 0
	global_load_lds_dwordx4 v[156:157], off
	s_waitcnt vmcnt(10)
	s_barrier
	s_waitcnt lgkmcnt(0)
	s_setprio 1
	v_mfma_f32_16x16x32_bf16 v[92:95], v[202:205], v[168:171], v[92:95]
	v_mfma_f32_16x16x32_bf16 v[88:91], v[210:213], v[168:171], v[88:91]
	v_mfma_f32_16x16x32_bf16 v[84:87], v[202:205], v[178:181], v[84:87]
	v_mfma_f32_16x16x32_bf16 v[80:83], v[210:213], v[178:181], v[80:83]
	v_mfma_f32_16x16x32_bf16 v[76:79], v[202:205], v[186:189], v[76:79]
	v_mfma_f32_16x16x32_bf16 v[72:75], v[210:213], v[186:189], v[72:75]
	v_mfma_f32_16x16x32_bf16 v[68:71], v[202:205], v[194:197], v[68:71]
	v_mfma_f32_16x16x32_bf16 v[64:67], v[210:213], v[194:197], v[64:67]
	v_mfma_f32_16x16x32_bf16 v[92:95], v[206:209], v[172:175], v[92:95]
	v_mfma_f32_16x16x32_bf16 v[88:91], v[214:217], v[172:175], v[88:91]
	v_mfma_f32_16x16x32_bf16 v[84:87], v[206:209], v[182:185], v[84:87]
	v_mfma_f32_16x16x32_bf16 v[80:83], v[214:217], v[182:185], v[80:83]
	v_mfma_f32_16x16x32_bf16 v[76:79], v[206:209], v[190:193], v[76:79]
	v_mfma_f32_16x16x32_bf16 v[72:75], v[214:217], v[190:193], v[72:75]
	v_mfma_f32_16x16x32_bf16 v[68:71], v[206:209], v[198:201], v[68:71]
	v_mfma_f32_16x16x32_bf16 v[64:67], v[214:217], v[198:201], v[64:67]
	s_setprio 0
	s_add_u32 s43, s2, s38
	s_addc_u32 s45, s3, s39
	s_add_u32 s40, s43, 0x100
	s_addc_u32 s41, s45, 0
	v_readfirstlane_b32 s48, v134
	v_lshl_add_u64 v[156:157], s[40:41], 0, v[128:129]
	s_mov_b32 m0, s48
	s_barrier
	ds_read_b128 v[168:171], v142 offset:0
	ds_read_b128 v[172:175], v142 offset:1024
	ds_read_b128 v[178:181], v142 offset:2048
	ds_read_b128 v[182:185], v142 offset:3072
	ds_read_b128 v[186:189], v142 offset:4096
	ds_read_b128 v[190:193], v142 offset:5120
	ds_read_b128 v[194:197], v142 offset:6144
	ds_read_b128 v[198:201], v142 offset:7168
	global_load_lds_dwordx4 v[156:157], off
	v_lshl_add_u64 v[156:157], s[40:41], 0, v[130:131]
	v_readfirstlane_b32 s40, v135
	s_mov_b32 m0, s40
	s_nop 0
	global_load_lds_dwordx4 v[156:157], off
	s_waitcnt vmcnt(10)
	s_barrier
	s_waitcnt lgkmcnt(0)
	s_setprio 1
	v_mfma_f32_16x16x32_bf16 v[60:63], v[148:151], v[168:171], v[60:63]
	v_mfma_f32_16x16x32_bf16 v[56:59], v[160:163], v[168:171], v[56:59]
	v_mfma_f32_16x16x32_bf16 v[52:55], v[148:151], v[178:181], v[52:55]
	v_mfma_f32_16x16x32_bf16 v[48:51], v[160:163], v[178:181], v[48:51]
	v_mfma_f32_16x16x32_bf16 v[44:47], v[148:151], v[186:189], v[44:47]
	v_mfma_f32_16x16x32_bf16 v[40:43], v[160:163], v[186:189], v[40:43]
	v_mfma_f32_16x16x32_bf16 v[36:39], v[148:151], v[194:197], v[36:39]
	v_mfma_f32_16x16x32_bf16 v[32:35], v[160:163], v[194:197], v[32:35]
	v_mfma_f32_16x16x32_bf16 v[60:63], v[152:155], v[172:175], v[60:63]
	v_mfma_f32_16x16x32_bf16 v[56:59], v[164:167], v[172:175], v[56:59]
	v_mfma_f32_16x16x32_bf16 v[52:55], v[152:155], v[182:185], v[52:55]
	v_mfma_f32_16x16x32_bf16 v[48:51], v[164:167], v[182:185], v[48:51]
	v_mfma_f32_16x16x32_bf16 v[44:47], v[152:155], v[190:193], v[44:47]
	v_mfma_f32_16x16x32_bf16 v[40:43], v[164:167], v[190:193], v[40:43]
	v_mfma_f32_16x16x32_bf16 v[36:39], v[152:155], v[198:201], v[36:39]
	v_mfma_f32_16x16x32_bf16 v[32:35], v[164:167], v[198:201], v[32:35]
	s_setprio 0
	s_barrier
	s_add_u32 s48, s20, s38
	s_addc_u32 s49, s21, s39
	s_add_u32 s40, s48, 0x100
	v_add_u32_e32 v148, 0x14000, v134
	s_addc_u32 s41, s49, 0
	v_readfirstlane_b32 s51, v148
	v_lshl_add_u64 v[150:151], s[40:41], 0, v[176:177]
	s_mov_b32 m0, s51
	v_add_u32_e32 v149, 0x16000, v134
	global_load_lds_dwordx4 v[150:151], off
	v_lshl_add_u64 v[150:151], s[40:41], 0, v[132:133]
	v_readfirstlane_b32 s40, v149
	s_mov_b32 m0, s40
	s_nop 0
	global_load_lds_dwordx4 v[150:151], off
	s_waitcnt vmcnt(10)
	s_barrier
	s_setprio 1
	v_mfma_f32_16x16x32_bf16 v[28:31], v[202:205], v[168:171], v[28:31]
	v_mfma_f32_16x16x32_bf16 v[24:27], v[210:213], v[168:171], v[24:27]
	v_mfma_f32_16x16x32_bf16 v[20:23], v[202:205], v[178:181], v[20:23]
	v_mfma_f32_16x16x32_bf16 v[16:19], v[210:213], v[178:181], v[16:19]
	v_mfma_f32_16x16x32_bf16 v[12:15], v[202:205], v[186:189], v[12:15]
	v_mfma_f32_16x16x32_bf16 v[8:11], v[210:213], v[186:189], v[8:11]
	v_mfma_f32_16x16x32_bf16 v[4:7], v[202:205], v[194:197], v[4:7]
	v_mfma_f32_16x16x32_bf16 v[0:3], v[210:213], v[194:197], v[0:3]
	v_mfma_f32_16x16x32_bf16 v[28:31], v[206:209], v[172:175], v[28:31]
	v_mfma_f32_16x16x32_bf16 v[24:27], v[214:217], v[172:175], v[24:27]
	v_mfma_f32_16x16x32_bf16 v[20:23], v[206:209], v[182:185], v[20:23]
	v_mfma_f32_16x16x32_bf16 v[16:19], v[214:217], v[182:185], v[16:19]
	v_mfma_f32_16x16x32_bf16 v[12:15], v[206:209], v[190:193], v[12:15]
	v_mfma_f32_16x16x32_bf16 v[8:11], v[214:217], v[190:193], v[8:11]
	v_mfma_f32_16x16x32_bf16 v[4:7], v[206:209], v[198:201], v[4:7]
	v_mfma_f32_16x16x32_bf16 v[0:3], v[214:217], v[198:201], v[0:3]
	s_setprio 0
	s_barrier
	ds_read_b128 v[160:163], v141 offset:0
	ds_read_b128 v[164:167], v141 offset:1024
	ds_read_b128 v[168:171], v141 offset:2048
	ds_read_b128 v[172:175], v141 offset:3072
	s_add_u32 s40, s29, s38
	v_add_u32_e32 v150, 0x4000, v134
	s_addc_u32 s41, s30, s39
	v_readfirstlane_b32 s51, v150
	v_lshl_add_u64 v[152:153], s[40:41], 0, v[128:129]
	s_mov_b32 m0, s51
	v_add_u32_e32 v151, 0x6000, v134
	ds_read_b128 v[154:157], v140 offset:0
	ds_read_b128 v[178:181], v140 offset:1024
	ds_read_b128 v[182:185], v140 offset:2048
	ds_read_b128 v[186:189], v140 offset:3072
	ds_read_b128 v[190:193], v140 offset:4096
	ds_read_b128 v[194:197], v140 offset:5120
	ds_read_b128 v[198:201], v140 offset:6144
	ds_read_b128 v[202:205], v140 offset:7168
	global_load_lds_dwordx4 v[152:153], off
	v_lshl_add_u64 v[152:153], s[40:41], 0, v[130:131]
	v_readfirstlane_b32 s40, v151
	s_mov_b32 m0, s40
	s_nop 0
	global_load_lds_dwordx4 v[152:153], off
	s_waitcnt vmcnt(10)
	s_waitcnt lgkmcnt(8)
	s_barrier
	s_waitcnt lgkmcnt(0)
	s_waitcnt lgkmcnt(0)
	s_setprio 1
	v_mfma_f32_16x16x32_bf16 v[124:127], v[160:163], v[154:157], v[124:127]
	v_mfma_f32_16x16x32_bf16 v[120:123], v[168:171], v[154:157], v[120:123]
	v_mfma_f32_16x16x32_bf16 v[116:119], v[160:163], v[182:185], v[116:119]
	v_mfma_f32_16x16x32_bf16 v[112:115], v[168:171], v[182:185], v[112:115]
	v_mfma_f32_16x16x32_bf16 v[108:111], v[160:163], v[190:193], v[108:111]
	v_mfma_f32_16x16x32_bf16 v[104:107], v[168:171], v[190:193], v[104:107]
	v_mfma_f32_16x16x32_bf16 v[100:103], v[160:163], v[198:201], v[100:103]
	v_mfma_f32_16x16x32_bf16 v[96:99], v[168:171], v[198:201], v[96:99]
	v_mfma_f32_16x16x32_bf16 v[124:127], v[164:167], v[178:181], v[124:127]
	v_mfma_f32_16x16x32_bf16 v[120:123], v[172:175], v[178:181], v[120:123]
	v_mfma_f32_16x16x32_bf16 v[116:119], v[164:167], v[186:189], v[116:119]
	v_mfma_f32_16x16x32_bf16 v[112:115], v[172:175], v[186:189], v[112:115]
	v_mfma_f32_16x16x32_bf16 v[108:111], v[164:167], v[194:197], v[108:111]
	v_mfma_f32_16x16x32_bf16 v[104:107], v[172:175], v[194:197], v[104:107]
	v_mfma_f32_16x16x32_bf16 v[100:103], v[164:167], v[202:205], v[100:103]
	v_mfma_f32_16x16x32_bf16 v[96:99], v[172:175], v[202:205], v[96:99]
	s_setprio 0
	s_barrier
	s_add_u32 s40, s35, 0x180
	v_add_u32_e32 v152, 0x18000, v134
	s_addc_u32 s41, s42, 0
	v_readfirstlane_b32 s35, v152
	v_add_u32_e32 v153, 0x1a000, v134
	v_lshl_add_u64 v[222:223], s[40:41], 0, v[176:177]
	s_mov_b32 m0, s35
	v_readfirstlane_b32 s35, v153
	ds_read_b128 v[206:209], v139 offset:0
	ds_read_b128 v[210:213], v139 offset:1024
	ds_read_b128 v[214:217], v139 offset:2048
	ds_read_b128 v[218:221], v139 offset:3072
	global_load_lds_dwordx4 v[222:223], off
	v_lshl_add_u64 v[222:223], s[40:41], 0, v[132:133]
	s_mov_b32 m0, s35
	s_nop 0
	global_load_lds_dwordx4 v[222:223], off
	s_waitcnt vmcnt(10)
	s_barrier
	s_waitcnt lgkmcnt(0)
	s_setprio 1
	v_mfma_f32_16x16x32_bf16 v[92:95], v[206:209], v[154:157], v[92:95]
	v_mfma_f32_16x16x32_bf16 v[88:91], v[214:217], v[154:157], v[88:91]
	v_mfma_f32_16x16x32_bf16 v[84:87], v[206:209], v[182:185], v[84:87]
	v_mfma_f32_16x16x32_bf16 v[80:83], v[214:217], v[182:185], v[80:83]
	v_mfma_f32_16x16x32_bf16 v[76:79], v[206:209], v[190:193], v[76:79]
	v_mfma_f32_16x16x32_bf16 v[72:75], v[214:217], v[190:193], v[72:75]
	v_mfma_f32_16x16x32_bf16 v[68:71], v[206:209], v[198:201], v[68:71]
	v_mfma_f32_16x16x32_bf16 v[64:67], v[214:217], v[198:201], v[64:67]
	v_mfma_f32_16x16x32_bf16 v[92:95], v[210:213], v[178:181], v[92:95]
	v_mfma_f32_16x16x32_bf16 v[88:91], v[218:221], v[178:181], v[88:91]
	v_mfma_f32_16x16x32_bf16 v[84:87], v[210:213], v[186:189], v[84:87]
	v_mfma_f32_16x16x32_bf16 v[80:83], v[218:221], v[186:189], v[80:83]
	v_mfma_f32_16x16x32_bf16 v[76:79], v[210:213], v[194:197], v[76:79]
	v_mfma_f32_16x16x32_bf16 v[72:75], v[218:221], v[194:197], v[72:75]
	v_mfma_f32_16x16x32_bf16 v[68:71], v[210:213], v[202:205], v[68:71]
	v_mfma_f32_16x16x32_bf16 v[64:67], v[218:221], v[202:205], v[64:67]
	s_setprio 0
	s_add_u32 s40, s43, 0x180
	v_add_u32_e32 v154, 0x8000, v134
	s_addc_u32 s41, s45, 0
	v_readfirstlane_b32 s35, v154
	v_add_u32_e32 v155, 0xa000, v134
	v_lshl_add_u64 v[156:157], s[40:41], 0, v[128:129]
	s_mov_b32 m0, s35
	v_readfirstlane_b32 s35, v155
	s_barrier
	ds_read_b128 v[178:181], v138 offset:0
	ds_read_b128 v[182:185], v138 offset:1024
	ds_read_b128 v[186:189], v138 offset:2048
	ds_read_b128 v[190:193], v138 offset:3072
	ds_read_b128 v[194:197], v138 offset:4096
	ds_read_b128 v[198:201], v138 offset:5120
	ds_read_b128 v[202:205], v138 offset:6144
	ds_read_b128 v[222:225], v138 offset:7168
	global_load_lds_dwordx4 v[156:157], off
	v_lshl_add_u64 v[156:157], s[40:41], 0, v[130:131]
	s_mov_b32 m0, s35
	s_nop 0
	global_load_lds_dwordx4 v[156:157], off
	s_waitcnt vmcnt(10)
	s_barrier
	s_waitcnt lgkmcnt(0)
	s_setprio 1
	v_mfma_f32_16x16x32_bf16 v[60:63], v[160:163], v[178:181], v[60:63]
	v_mfma_f32_16x16x32_bf16 v[56:59], v[168:171], v[178:181], v[56:59]
	v_mfma_f32_16x16x32_bf16 v[52:55], v[160:163], v[186:189], v[52:55]
	v_mfma_f32_16x16x32_bf16 v[48:51], v[168:171], v[186:189], v[48:51]
	v_mfma_f32_16x16x32_bf16 v[44:47], v[160:163], v[194:197], v[44:47]
	v_mfma_f32_16x16x32_bf16 v[40:43], v[168:171], v[194:197], v[40:43]
	v_mfma_f32_16x16x32_bf16 v[36:39], v[160:163], v[202:205], v[36:39]
	v_mfma_f32_16x16x32_bf16 v[32:35], v[168:171], v[202:205], v[32:35]
	v_mfma_f32_16x16x32_bf16 v[60:63], v[164:167], v[182:185], v[60:63]
	v_mfma_f32_16x16x32_bf16 v[56:59], v[172:175], v[182:185], v[56:59]
	v_mfma_f32_16x16x32_bf16 v[52:55], v[164:167], v[190:193], v[52:55]
	v_mfma_f32_16x16x32_bf16 v[48:51], v[172:175], v[190:193], v[48:51]
	v_mfma_f32_16x16x32_bf16 v[44:47], v[164:167], v[198:201], v[44:47]
	v_mfma_f32_16x16x32_bf16 v[40:43], v[172:175], v[198:201], v[40:43]
	v_mfma_f32_16x16x32_bf16 v[36:39], v[164:167], v[222:225], v[36:39]
	v_mfma_f32_16x16x32_bf16 v[32:35], v[172:175], v[222:225], v[32:35]
	s_setprio 0
	s_barrier
	s_add_u32 s40, s48, 0x180
	v_add_u32_e32 v156, 0x1c000, v134
	s_addc_u32 s41, s49, 0
	v_readfirstlane_b32 s35, v156
	v_add_u32_e32 v157, 0x1e000, v134
	v_lshl_add_u64 v[160:161], s[40:41], 0, v[176:177]
	s_mov_b32 m0, s35
	v_readfirstlane_b32 s35, v157
	global_load_lds_dwordx4 v[160:161], off
	v_lshl_add_u64 v[160:161], s[40:41], 0, v[132:133]
	s_mov_b32 m0, s35
	s_nop 0
	global_load_lds_dwordx4 v[160:161], off
	s_waitcnt vmcnt(10)
	s_barrier
	s_setprio 1
	v_mfma_f32_16x16x32_bf16 v[28:31], v[206:209], v[178:181], v[28:31]
	v_mfma_f32_16x16x32_bf16 v[24:27], v[214:217], v[178:181], v[24:27]
	v_mfma_f32_16x16x32_bf16 v[20:23], v[206:209], v[186:189], v[20:23]
	v_mfma_f32_16x16x32_bf16 v[16:19], v[214:217], v[186:189], v[16:19]
	v_mfma_f32_16x16x32_bf16 v[12:15], v[206:209], v[194:197], v[12:15]
	v_mfma_f32_16x16x32_bf16 v[8:11], v[214:217], v[194:197], v[8:11]
	v_mfma_f32_16x16x32_bf16 v[4:7], v[206:209], v[202:205], v[4:7]
	v_mfma_f32_16x16x32_bf16 v[0:3], v[214:217], v[202:205], v[0:3]
	v_mfma_f32_16x16x32_bf16 v[28:31], v[210:213], v[182:185], v[28:31]
	v_mfma_f32_16x16x32_bf16 v[24:27], v[218:221], v[182:185], v[24:27]
	v_mfma_f32_16x16x32_bf16 v[20:23], v[210:213], v[190:193], v[20:23]
	v_mfma_f32_16x16x32_bf16 v[16:19], v[218:221], v[190:193], v[16:19]
	v_mfma_f32_16x16x32_bf16 v[12:15], v[210:213], v[198:201], v[12:15]
	v_mfma_f32_16x16x32_bf16 v[8:11], v[218:221], v[198:201], v[8:11]
	v_mfma_f32_16x16x32_bf16 v[4:7], v[210:213], v[222:225], v[4:7]
	v_mfma_f32_16x16x32_bf16 v[0:3], v[218:221], v[222:225], v[0:3]
	s_setprio 0
	s_add_i32 s31, s31, 2
	s_add_u32 s38, s38, 0x100
	s_addc_u32 s39, s39, 0
	s_cmp_gt_u32 s31, 11
	s_barrier
	s_cbranch_scc0 .LBB0_141
	s_add_u32 s2, s1, 0x780
	s_addc_u32 s3, s26, 0
	v_readfirstlane_b32 s1, v158
	v_lshl_add_u64 v[132:133], s[2:3], 0, v[128:129]
	s_mov_b32 m0, s1
	v_readfirstlane_b32 s1, v159
	ds_read_b128 v[160:163], v145 offset:0
	ds_read_b128 v[164:167], v145 offset:1024
	ds_read_b128 v[168:171], v145 offset:2048
	ds_read_b128 v[172:175], v145 offset:3072
	ds_read_b128 v[178:181], v144 offset:0
	ds_read_b128 v[182:185], v144 offset:1024
	ds_read_b128 v[190:193], v144 offset:2048
	ds_read_b128 v[194:197], v144 offset:3072
	ds_read_b128 v[198:201], v144 offset:4096
	ds_read_b128 v[202:205], v144 offset:5120
	ds_read_b128 v[206:209], v144 offset:6144
	ds_read_b128 v[210:213], v144 offset:7168
	global_load_lds_dwordx4 v[132:133], off
	v_lshl_add_u64 v[132:133], s[2:3], 0, v[130:131]
	s_mov_b32 m0, s1
	s_nop 0
	global_load_lds_dwordx4 v[132:133], off
	s_waitcnt vmcnt(10)
	s_barrier
	s_waitcnt lgkmcnt(0)
	s_waitcnt lgkmcnt(0)
	s_setprio 1
	v_mfma_f32_16x16x32_bf16 v[124:127], v[160:163], v[178:181], v[124:127]
	v_mfma_f32_16x16x32_bf16 v[116:119], v[160:163], v[190:193], v[116:119]
	v_mfma_f32_16x16x32_bf16 v[108:111], v[160:163], v[198:201], v[108:111]
	v_mfma_f32_16x16x32_bf16 v[100:103], v[160:163], v[206:209], v[100:103]
	v_mfma_f32_16x16x32_bf16 v[124:127], v[164:167], v[182:185], v[124:127]
	v_mfma_f32_16x16x32_bf16 v[120:123], v[168:171], v[178:181], v[120:123]
	v_mfma_f32_16x16x32_bf16 v[116:119], v[164:167], v[194:197], v[116:119]
	v_mfma_f32_16x16x32_bf16 v[112:115], v[168:171], v[190:193], v[112:115]
	v_mfma_f32_16x16x32_bf16 v[108:111], v[164:167], v[202:205], v[108:111]
	v_mfma_f32_16x16x32_bf16 v[104:107], v[168:171], v[198:201], v[104:107]
	v_mfma_f32_16x16x32_bf16 v[100:103], v[164:167], v[210:213], v[100:103]
	v_mfma_f32_16x16x32_bf16 v[96:99], v[168:171], v[206:209], v[96:99]
	v_mfma_f32_16x16x32_bf16 v[214:217], v[172:175], v[182:185], v[120:123]
	v_mfma_f32_16x16x32_bf16 v[218:221], v[172:175], v[194:197], v[112:115]
	v_mfma_f32_16x16x32_bf16 v[222:225], v[172:175], v[202:205], v[104:107]
	v_mfma_f32_16x16x32_bf16 v[226:229], v[172:175], v[210:213], v[96:99]
	s_setprio 0
	s_barrier
	ds_read_b128 v[96:99], v143 offset:0
	ds_read_b128 v[104:107], v143 offset:1024
	ds_read_b128 v[112:115], v143 offset:2048
	ds_read_b128 v[120:123], v143 offset:3072
	s_waitcnt vmcnt(8)
	s_barrier
	s_waitcnt lgkmcnt(0)
	s_setprio 1
	v_mfma_f32_16x16x32_bf16 v[92:95], v[96:99], v[178:181], v[92:95]
	v_mfma_f32_16x16x32_bf16 v[88:91], v[112:115], v[178:181], v[88:91]
	v_mfma_f32_16x16x32_bf16 v[84:87], v[96:99], v[190:193], v[84:87]
	v_mfma_f32_16x16x32_bf16 v[80:83], v[112:115], v[190:193], v[80:83]
	v_mfma_f32_16x16x32_bf16 v[76:79], v[96:99], v[198:201], v[76:79]
	v_mfma_f32_16x16x32_bf16 v[72:75], v[112:115], v[198:201], v[72:75]
	v_mfma_f32_16x16x32_bf16 v[68:71], v[96:99], v[206:209], v[68:71]
	v_mfma_f32_16x16x32_bf16 v[64:67], v[112:115], v[206:209], v[64:67]
	v_mfma_f32_16x16x32_bf16 v[92:95], v[104:107], v[182:185], v[92:95]
	v_mfma_f32_16x16x32_bf16 v[88:91], v[120:123], v[182:185], v[88:91]
	v_mfma_f32_16x16x32_bf16 v[84:87], v[104:107], v[194:197], v[84:87]
	v_mfma_f32_16x16x32_bf16 v[80:83], v[120:123], v[194:197], v[80:83]
	v_mfma_f32_16x16x32_bf16 v[76:79], v[104:107], v[202:205], v[76:79]
	v_mfma_f32_16x16x32_bf16 v[72:75], v[120:123], v[202:205], v[72:75]
	v_mfma_f32_16x16x32_bf16 v[68:71], v[104:107], v[210:213], v[68:71]
	v_mfma_f32_16x16x32_bf16 v[64:67], v[120:123], v[210:213], v[64:67]
	s_setprio 0
	s_barrier
	ds_read_b128 v[178:181], v142 offset:0
	ds_read_b128 v[182:185], v142 offset:1024
	ds_read_b128 v[190:193], v142 offset:2048
	ds_read_b128 v[194:197], v142 offset:3072
	ds_read_b128 v[198:201], v142 offset:4096
	ds_read_b128 v[202:205], v142 offset:5120
	ds_read_b128 v[206:209], v142 offset:6144
	ds_read_b128 v[142:145], v142 offset:7168
	s_waitcnt vmcnt(4)
	s_barrier
	s_waitcnt lgkmcnt(0)
	s_setprio 1
	v_mfma_f32_16x16x32_bf16 v[60:63], v[160:163], v[178:181], v[60:63]
	v_mfma_f32_16x16x32_bf16 v[210:213], v[164:167], v[182:185], v[60:63]
	v_mfma_f32_16x16x32_bf16 v[56:59], v[168:171], v[178:181], v[56:59]
	v_mfma_f32_16x16x32_bf16 v[52:55], v[160:163], v[190:193], v[52:55]
	v_mfma_f32_16x16x32_bf16 v[48:51], v[168:171], v[190:193], v[48:51]
	v_mfma_f32_16x16x32_bf16 v[44:47], v[160:163], v[198:201], v[44:47]
	v_mfma_f32_16x16x32_bf16 v[40:43], v[168:171], v[198:201], v[40:43]
	v_mfma_f32_16x16x32_bf16 v[36:39], v[160:163], v[206:209], v[36:39]
	v_mfma_f32_16x16x32_bf16 v[32:35], v[168:171], v[206:209], v[32:35]
	v_mfma_f32_16x16x32_bf16 v[238:241], v[172:175], v[182:185], v[56:59]
	v_mfma_f32_16x16x32_bf16 v[242:245], v[164:167], v[194:197], v[52:55]
	v_mfma_f32_16x16x32_bf16 v[246:249], v[172:175], v[194:197], v[48:51]
	v_mfma_f32_16x16x32_bf16 v[232:235], v[164:167], v[202:205], v[44:47]
	v_mfma_f32_16x16x32_bf16 v[186:189], v[172:175], v[202:205], v[40:43]
	v_mfma_f32_16x16x32_bf16 v[158:161], v[164:167], v[142:145], v[36:39]
	v_mfma_f32_16x16x32_bf16 v[162:165], v[172:175], v[142:145], v[32:35]
	s_setprio 0
	s_setprio 1
	v_mfma_f32_16x16x32_bf16 v[28:31], v[96:99], v[178:181], v[28:31]
	v_mfma_f32_16x16x32_bf16 v[20:23], v[96:99], v[190:193], v[20:23]
	v_mfma_f32_16x16x32_bf16 v[12:15], v[96:99], v[198:201], v[12:15]
	v_mfma_f32_16x16x32_bf16 v[4:7], v[96:99], v[206:209], v[4:7]
	v_mfma_f32_16x16x32_bf16 v[28:31], v[104:107], v[182:185], v[28:31]
	v_mfma_f32_16x16x32_bf16 v[24:27], v[112:115], v[178:181], v[24:27]
	v_mfma_f32_16x16x32_bf16 v[20:23], v[104:107], v[194:197], v[20:23]
	v_mfma_f32_16x16x32_bf16 v[16:19], v[112:115], v[190:193], v[16:19]
	v_mfma_f32_16x16x32_bf16 v[12:15], v[104:107], v[202:205], v[12:15]
	v_mfma_f32_16x16x32_bf16 v[8:11], v[112:115], v[198:201], v[8:11]
	v_mfma_f32_16x16x32_bf16 v[4:7], v[104:107], v[142:145], v[4:7]
	v_mfma_f32_16x16x32_bf16 v[0:3], v[112:115], v[206:209], v[0:3]
	v_mfma_f32_16x16x32_bf16 v[166:169], v[120:123], v[182:185], v[24:27]
	v_mfma_f32_16x16x32_bf16 v[170:173], v[120:123], v[194:197], v[16:19]
	v_mfma_f32_16x16x32_bf16 v[178:181], v[120:123], v[202:205], v[8:11]
	v_mfma_f32_16x16x32_bf16 v[142:145], v[120:123], v[142:145], v[0:3]
	s_setprio 0
	s_barrier
	ds_read_b128 v[0:3], v141 offset:0
	ds_read_b128 v[8:11], v141 offset:1024
	ds_read_b128 v[16:19], v141 offset:2048
	ds_read_b128 v[24:27], v141 offset:3072
	ds_read_b128 v[32:35], v140 offset:0
	ds_read_b128 v[36:39], v140 offset:1024
	ds_read_b128 v[40:43], v140 offset:2048
	ds_read_b128 v[44:47], v140 offset:3072
	ds_read_b128 v[182:185], v140 offset:4096
	ds_read_b128 v[190:193], v140 offset:5120
	ds_read_b128 v[194:197], v140 offset:6144
	ds_read_b128 v[198:201], v140 offset:7168
	s_waitcnt vmcnt(2)
	s_barrier
	s_waitcnt lgkmcnt(0)
	s_waitcnt lgkmcnt(0)
	s_setprio 1
	v_mfma_f32_16x16x32_bf16 v[48:51], v[0:3], v[32:35], v[124:127]
	v_mfma_f32_16x16x32_bf16 v[120:123], v[8:11], v[36:39], v[48:51]
	v_mfma_f32_16x16x32_bf16 v[48:51], v[16:19], v[32:35], v[214:217]
	v_mfma_f32_16x16x32_bf16 v[124:127], v[24:27], v[36:39], v[48:51]
	v_mfma_f32_16x16x32_bf16 v[48:51], v[0:3], v[40:43], v[116:119]
	v_mfma_f32_16x16x32_bf16 v[112:115], v[8:11], v[44:47], v[48:51]
	v_mfma_f32_16x16x32_bf16 v[48:51], v[16:19], v[40:43], v[218:221]
	v_mfma_f32_16x16x32_bf16 v[116:119], v[24:27], v[44:47], v[48:51]
	v_mfma_f32_16x16x32_bf16 v[48:51], v[0:3], v[182:185], v[108:111]
	v_mfma_f32_16x16x32_bf16 v[104:107], v[8:11], v[190:193], v[48:51]
	v_mfma_f32_16x16x32_bf16 v[48:51], v[16:19], v[182:185], v[222:225]
	v_mfma_f32_16x16x32_bf16 v[108:111], v[24:27], v[190:193], v[48:51]
	v_mfma_f32_16x16x32_bf16 v[48:51], v[0:3], v[194:197], v[100:103]
	v_mfma_f32_16x16x32_bf16 v[96:99], v[8:11], v[198:201], v[48:51]
	v_mfma_f32_16x16x32_bf16 v[48:51], v[16:19], v[194:197], v[226:229]
	v_mfma_f32_16x16x32_bf16 v[100:103], v[24:27], v[198:201], v[48:51]
	s_setprio 0
	s_barrier
	ds_read_b128 v[202:205], v139 offset:0
	ds_read_b128 v[206:209], v139 offset:1024
	ds_read_b128 v[214:217], v139 offset:2048
	ds_read_b128 v[218:221], v139 offset:3072
	s_waitcnt vmcnt(0)
	s_barrier
	s_waitcnt lgkmcnt(0)
	s_setprio 1
	v_mfma_f32_16x16x32_bf16 v[48:51], v[202:205], v[32:35], v[92:95]
	v_mfma_f32_16x16x32_bf16 v[32:35], v[214:217], v[32:35], v[88:91]
	v_mfma_f32_16x16x32_bf16 v[60:63], v[218:221], v[36:39], v[32:35]
	v_mfma_f32_16x16x32_bf16 v[32:35], v[202:205], v[40:43], v[84:87]
	v_mfma_f32_16x16x32_bf16 v[56:59], v[206:209], v[44:47], v[32:35]
	v_mfma_f32_16x16x32_bf16 v[32:35], v[214:217], v[40:43], v[80:83]
	v_mfma_f32_16x16x32_bf16 v[52:55], v[218:221], v[44:47], v[32:35]
	v_mfma_f32_16x16x32_bf16 v[32:35], v[202:205], v[182:185], v[76:79]
	v_mfma_f32_16x16x32_bf16 v[92:95], v[206:209], v[36:39], v[48:51]
	v_mfma_f32_16x16x32_bf16 v[48:51], v[206:209], v[190:193], v[32:35]
	v_mfma_f32_16x16x32_bf16 v[32:35], v[214:217], v[182:185], v[72:75]
	v_mfma_f32_16x16x32_bf16 v[44:47], v[218:221], v[190:193], v[32:35]
	v_mfma_f32_16x16x32_bf16 v[32:35], v[202:205], v[194:197], v[68:71]
	v_mfma_f32_16x16x32_bf16 v[36:39], v[214:217], v[194:197], v[64:67]
	v_mfma_f32_16x16x32_bf16 v[40:43], v[206:209], v[198:201], v[32:35]
	v_mfma_f32_16x16x32_bf16 v[36:39], v[218:221], v[198:201], v[36:39]
	s_setprio 0
	s_barrier
	ds_read_b128 v[182:185], v138 offset:0
	ds_read_b128 v[190:193], v138 offset:1024
	ds_read_b128 v[194:197], v138 offset:2048
	ds_read_b128 v[198:201], v138 offset:3072
	ds_read_b128 v[222:225], v138 offset:4096
	ds_read_b128 v[226:229], v138 offset:5120
	ds_read_b128 v[32:35], v138 offset:6144
	ds_read_b128 v[138:141], v138 offset:7168
	s_barrier
	s_waitcnt lgkmcnt(0)
	s_setprio 1
	v_mfma_f32_16x16x32_bf16 v[64:67], v[0:3], v[182:185], v[210:213]
	v_mfma_f32_16x16x32_bf16 v[88:91], v[8:11], v[190:193], v[64:67]
	v_mfma_f32_16x16x32_bf16 v[64:67], v[16:19], v[182:185], v[238:241]
	v_mfma_f32_16x16x32_bf16 v[210:213], v[24:27], v[190:193], v[64:67]
	v_mfma_f32_16x16x32_bf16 v[64:67], v[0:3], v[194:197], v[242:245]
	v_mfma_f32_16x16x32_bf16 v[80:83], v[8:11], v[198:201], v[64:67]
	v_mfma_f32_16x16x32_bf16 v[64:67], v[16:19], v[194:197], v[246:249]
	v_mfma_f32_16x16x32_bf16 v[84:87], v[24:27], v[198:201], v[64:67]
	v_mfma_f32_16x16x32_bf16 v[64:67], v[0:3], v[222:225], v[232:235]
	v_mfma_f32_16x16x32_bf16 v[72:75], v[8:11], v[226:229], v[64:67]
	v_mfma_f32_16x16x32_bf16 v[64:67], v[16:19], v[222:225], v[186:189]
	v_mfma_f32_16x16x32_bf16 v[0:3], v[0:3], v[32:35], v[158:161]
	v_mfma_f32_16x16x32_bf16 v[76:79], v[24:27], v[226:229], v[64:67]
	v_mfma_f32_16x16x32_bf16 v[64:67], v[8:11], v[138:141], v[0:3]
	v_mfma_f32_16x16x32_bf16 v[0:3], v[16:19], v[32:35], v[162:165]
	v_mfma_f32_16x16x32_bf16 v[68:71], v[24:27], v[138:141], v[0:3]
	s_setprio 0
	s_setprio 1
	v_mfma_f32_16x16x32_bf16 v[0:3], v[202:205], v[182:185], v[28:31]
	v_mfma_f32_16x16x32_bf16 v[24:27], v[206:209], v[190:193], v[0:3]
	v_mfma_f32_16x16x32_bf16 v[0:3], v[214:217], v[182:185], v[166:169]
	v_mfma_f32_16x16x32_bf16 v[28:31], v[218:221], v[190:193], v[0:3]
	v_mfma_f32_16x16x32_bf16 v[0:3], v[202:205], v[194:197], v[20:23]
	v_mfma_f32_16x16x32_bf16 v[16:19], v[206:209], v[198:201], v[0:3]
	v_mfma_f32_16x16x32_bf16 v[0:3], v[214:217], v[194:197], v[170:173]
	v_mfma_f32_16x16x32_bf16 v[20:23], v[218:221], v[198:201], v[0:3]
	v_mfma_f32_16x16x32_bf16 v[0:3], v[202:205], v[222:225], v[12:15]
	v_mfma_f32_16x16x32_bf16 v[8:11], v[206:209], v[226:229], v[0:3]
	v_mfma_f32_16x16x32_bf16 v[0:3], v[214:217], v[222:225], v[178:181]
	v_mfma_f32_16x16x32_bf16 v[12:15], v[218:221], v[226:229], v[0:3]
	v_mfma_f32_16x16x32_bf16 v[0:3], v[202:205], v[32:35], v[4:7]
	v_mfma_f32_16x16x32_bf16 v[4:7], v[214:217], v[32:35], v[142:145]
	v_mfma_f32_16x16x32_bf16 v[0:3], v[206:209], v[138:141], v[0:3]
	v_mfma_f32_16x16x32_bf16 v[4:7], v[218:221], v[138:141], v[4:7]
	s_setprio 0
	s_cmpk_lt_u32 s11, 0x100
	s_barrier
	s_cbranch_scc0 .LBB0_144
	s_barrier

.LBB0_146:
	v_mov_b64_e32 v[182:183], v[42:43]
	v_mov_b64_e32 v[180:181], v[40:41]
	v_mov_b64_e32 v[40:41], v[48:49]
	v_mov_b32_e32 v147, v250
	v_mov_b64_e32 v[42:43], v[50:51]
	v_mov_b64_e32 v[48:49], v[56:57]
	v_mov_b64_e32 v[50:51], v[58:59]
	v_readfirstlane_b32 s1, v147
	v_mov_b64_e32 v[56:57], v[92:93]
	s_ashr_i32 s20, s1, 6
	v_and_b32_e32 v141, 15, v147
	v_bfe_u32 v148, v147, 4, 2
	s_mov_b64 s[2:3], -1
	s_and_b64 vcc, exec, s[18:19]
	v_mov_b64_e32 v[58:59], v[94:95]
	s_cbranch_vccz .LBB0_180
	v_mul_f32_e32 v33, v121, v121
	v_fmac_f32_e32 v33, v120, v120
	v_fmac_f32_e32 v33, v122, v122
	v_fmac_f32_e32 v33, v123, v123
	v_fmac_f32_e32 v33, v124, v124
	v_fmac_f32_e32 v33, v125, v125
	v_fmac_f32_e32 v33, v126, v126
	v_fmac_f32_e32 v33, v127, v127
	v_mov_b32_e32 v34, v33
	s_nop 1
	v_permlane16_swap_b32_e32 v33, v34
	v_add_f32_e32 v129, v33, v34
	s_lshl_b32 s19, s20, 10
	v_lshlrev_b32_e32 v32, 2, v141
	v_mov_b32_e32 v130, v129
	v_cmp_eq_u32_e32 vcc, 0, v148
	s_nop 0
	v_permlane32_swap_b32_e32 v129, v130
	v_add_u32_e32 v128, s19, v32
	s_and_saveexec_b64 s[2:3], vcc
	s_cbranch_execz .LBB0_149
	v_add_f32_e32 v32, v129, v130
	s_nop 0
	ds_write_b32 v128, v32 offset:49152
.LBB0_149:
	s_or_b64 exec, exec, s[2:3]
	v_mul_f32_e32 v32, v113, v113
	v_fmac_f32_e32 v32, v112, v112
	v_fmac_f32_e32 v32, v114, v114
	v_fmac_f32_e32 v32, v115, v115
	v_fmac_f32_e32 v32, v116, v116
	v_fmac_f32_e32 v32, v117, v117
	v_fmac_f32_e32 v32, v118, v118
	v_fmac_f32_e32 v32, v119, v119
	v_mov_b32_e32 v33, v32
	s_nop 1
	v_permlane16_swap_b32_e32 v32, v33
	v_add_f32_e32 v129, v32, v33
	v_mov_b32_e32 v130, v129
	s_nop 1
	v_permlane32_swap_b32_e32 v129, v130
	s_and_saveexec_b64 s[2:3], vcc
	s_cbranch_execz .LBB0_151
	v_add_f32_e32 v32, v129, v130
	s_nop 0
	ds_write_b32 v128, v32 offset:49216
.LBB0_151:
	s_or_b64 exec, exec, s[2:3]
	v_mul_f32_e32 v32, v105, v105
	v_fmac_f32_e32 v32, v104, v104
	v_fmac_f32_e32 v32, v106, v106
	v_fmac_f32_e32 v32, v107, v107
	v_fmac_f32_e32 v32, v108, v108
	v_fmac_f32_e32 v32, v109, v109
	v_fmac_f32_e32 v32, v110, v110
	v_fmac_f32_e32 v32, v111, v111
	v_mov_b32_e32 v33, v32
	s_nop 1
	v_permlane16_swap_b32_e32 v32, v33
	v_add_f32_e32 v129, v32, v33
	v_mov_b32_e32 v130, v129
	s_nop 1
	v_permlane32_swap_b32_e32 v129, v130
	s_and_saveexec_b64 s[2:3], vcc
	s_cbranch_execz .LBB0_153
	v_add_f32_e32 v32, v129, v130
	s_nop 0
	ds_write_b32 v128, v32 offset:49280
.LBB0_153:
	s_or_b64 exec, exec, s[2:3]
	v_mul_f32_e32 v32, v97, v97
	v_fmac_f32_e32 v32, v96, v96
	v_fmac_f32_e32 v32, v98, v98
	v_fmac_f32_e32 v32, v99, v99
	v_fmac_f32_e32 v32, v100, v100
	v_fmac_f32_e32 v32, v101, v101
	v_fmac_f32_e32 v32, v102, v102
	v_fmac_f32_e32 v32, v103, v103
	v_mov_b32_e32 v33, v32
	s_nop 1
	v_permlane16_swap_b32_e32 v32, v33
	v_add_f32_e32 v129, v32, v33
	v_mov_b32_e32 v130, v129
	s_nop 1
	v_permlane32_swap_b32_e32 v129, v130
	s_and_saveexec_b64 s[2:3], vcc
	s_cbranch_execz .LBB0_155
	v_add_f32_e32 v32, v129, v130
	s_nop 0
	ds_write_b32 v128, v32 offset:49344
.LBB0_155:
	s_or_b64 exec, exec, s[2:3]
	v_mul_f32_e32 v32, v57, v57
	v_fmac_f32_e32 v32, v56, v56
	v_fmac_f32_e32 v32, v58, v58
	v_fmac_f32_e32 v32, v59, v59
	v_fmac_f32_e32 v32, v60, v60
	v_fmac_f32_e32 v32, v61, v61
	v_fmac_f32_e32 v32, v62, v62
	v_fmac_f32_e32 v32, v63, v63
	v_mov_b32_e32 v33, v32
	s_nop 1
	v_permlane16_swap_b32_e32 v32, v33
	v_add_f32_e32 v129, v32, v33
	v_mov_b32_e32 v130, v129
	s_nop 1
	v_permlane32_swap_b32_e32 v129, v130
	s_and_saveexec_b64 s[2:3], vcc
	s_cbranch_execz .LBB0_157
	v_add_f32_e32 v32, v129, v130
	s_nop 0
	ds_write_b32 v128, v32 offset:49408
.LBB0_157:
	s_or_b64 exec, exec, s[2:3]
	v_mul_f32_e32 v32, v49, v49
	v_fmac_f32_e32 v32, v48, v48
	v_fmac_f32_e32 v32, v50, v50
	v_fmac_f32_e32 v32, v51, v51
	v_fmac_f32_e32 v32, v52, v52
	v_fmac_f32_e32 v32, v53, v53
	v_fmac_f32_e32 v32, v54, v54
	v_fmac_f32_e32 v32, v55, v55
	v_mov_b32_e32 v33, v32
	s_nop 1
	v_permlane16_swap_b32_e32 v32, v33
	v_add_f32_e32 v129, v32, v33
	v_mov_b32_e32 v130, v129
	s_nop 1
	v_permlane32_swap_b32_e32 v129, v130
	s_and_saveexec_b64 s[2:3], vcc
	s_cbranch_execz .LBB0_159
	v_add_f32_e32 v32, v129, v130
	s_nop 0
	ds_write_b32 v128, v32 offset:49472
.LBB0_159:
	s_or_b64 exec, exec, s[2:3]
	v_mul_f32_e32 v32, v41, v41
	v_fmac_f32_e32 v32, v40, v40
	v_fmac_f32_e32 v32, v42, v42
	v_fmac_f32_e32 v32, v43, v43
	v_fmac_f32_e32 v32, v44, v44
	v_fmac_f32_e32 v32, v45, v45
	v_fmac_f32_e32 v32, v46, v46
	v_fmac_f32_e32 v32, v47, v47
	v_mov_b32_e32 v33, v32
	s_nop 1
	v_permlane16_swap_b32_e32 v32, v33
	v_add_f32_e32 v129, v32, v33
	v_mov_b32_e32 v130, v129
	s_nop 1
	v_permlane32_swap_b32_e32 v129, v130
	s_and_saveexec_b64 s[2:3], vcc
	s_cbranch_execz .LBB0_161
	v_add_f32_e32 v32, v129, v130
	s_nop 0
	ds_write_b32 v128, v32 offset:49536
.LBB0_161:
	s_or_b64 exec, exec, s[2:3]
	v_mul_f32_e32 v32, v181, v181
	v_fmac_f32_e32 v32, v180, v180
	v_fmac_f32_e32 v32, v182, v182
	v_fmac_f32_e32 v32, v183, v183
	v_fmac_f32_e32 v32, v36, v36
	v_fmac_f32_e32 v32, v37, v37
	v_fmac_f32_e32 v32, v38, v38
	v_fmac_f32_e32 v32, v39, v39
	v_mov_b32_e32 v33, v32
	s_nop 1
	v_permlane16_swap_b32_e32 v32, v33
	v_add_f32_e32 v129, v32, v33
	v_mov_b32_e32 v130, v129
	s_nop 1
	v_permlane32_swap_b32_e32 v129, v130
	s_and_saveexec_b64 s[2:3], vcc
	s_cbranch_execz .LBB0_163
	v_add_f32_e32 v32, v129, v130
	s_nop 0
	ds_write_b32 v128, v32 offset:49600
.LBB0_163:
	s_or_b64 exec, exec, s[2:3]
	v_mul_f32_e32 v32, v89, v89
	v_fmac_f32_e32 v32, v88, v88
	v_fmac_f32_e32 v32, v90, v90
	v_fmac_f32_e32 v32, v91, v91
	v_fmac_f32_e32 v32, v210, v210
	v_fmac_f32_e32 v32, v211, v211
	v_fmac_f32_e32 v32, v212, v212
	v_fmac_f32_e32 v32, v213, v213
	v_mov_b32_e32 v33, v32
	s_nop 1
	v_permlane16_swap_b32_e32 v32, v33
	v_add_f32_e32 v129, v32, v33
	v_mov_b32_e32 v130, v129
	s_nop 1
	v_permlane32_swap_b32_e32 v129, v130
	s_and_saveexec_b64 s[2:3], vcc
	s_cbranch_execz .LBB0_165
	v_add_f32_e32 v32, v129, v130
	s_nop 0
	ds_write_b32 v128, v32 offset:49664
.LBB0_165:
	s_or_b64 exec, exec, s[2:3]
	v_mul_f32_e32 v32, v81, v81
	v_fmac_f32_e32 v32, v80, v80
	v_fmac_f32_e32 v32, v82, v82
	v_fmac_f32_e32 v32, v83, v83
	v_fmac_f32_e32 v32, v84, v84
	v_fmac_f32_e32 v32, v85, v85
	v_fmac_f32_e32 v32, v86, v86
	v_fmac_f32_e32 v32, v87, v87
	v_mov_b32_e32 v33, v32
	s_nop 1
	v_permlane16_swap_b32_e32 v32, v33
	v_add_f32_e32 v129, v32, v33
	v_mov_b32_e32 v130, v129
	s_nop 1
	v_permlane32_swap_b32_e32 v129, v130
	s_and_saveexec_b64 s[2:3], vcc
	s_cbranch_execz .LBB0_167
	v_add_f32_e32 v32, v129, v130
	s_nop 0
	ds_write_b32 v128, v32 offset:49728
.LBB0_167:
	s_or_b64 exec, exec, s[2:3]
	v_mul_f32_e32 v32, v73, v73
	v_fmac_f32_e32 v32, v72, v72
	v_fmac_f32_e32 v32, v74, v74
	v_fmac_f32_e32 v32, v75, v75
	v_fmac_f32_e32 v32, v76, v76
	v_fmac_f32_e32 v32, v77, v77
	v_fmac_f32_e32 v32, v78, v78
	v_fmac_f32_e32 v32, v79, v79
	v_mov_b32_e32 v33, v32
	s_nop 1
	v_permlane16_swap_b32_e32 v32, v33
	v_add_f32_e32 v129, v32, v33
	v_mov_b32_e32 v130, v129
	s_nop 1
	v_permlane32_swap_b32_e32 v129, v130
	s_and_saveexec_b64 s[2:3], vcc
	s_cbranch_execz .LBB0_169
	v_add_f32_e32 v32, v129, v130
	s_nop 0
	ds_write_b32 v128, v32 offset:49792
.LBB0_169:
	s_or_b64 exec, exec, s[2:3]
	v_mul_f32_e32 v32, v65, v65
	v_fmac_f32_e32 v32, v64, v64
	v_fmac_f32_e32 v32, v66, v66
	v_fmac_f32_e32 v32, v67, v67
	v_fmac_f32_e32 v32, v68, v68
	v_fmac_f32_e32 v32, v69, v69
	v_fmac_f32_e32 v32, v70, v70
	v_fmac_f32_e32 v32, v71, v71
	v_mov_b32_e32 v33, v32
	s_nop 1
	v_permlane16_swap_b32_e32 v32, v33
	v_add_f32_e32 v129, v32, v33
	v_mov_b32_e32 v130, v129
	s_nop 1
	v_permlane32_swap_b32_e32 v129, v130
	s_and_saveexec_b64 s[2:3], vcc
	s_cbranch_execz .LBB0_171
	v_add_f32_e32 v32, v129, v130
	s_nop 0
	ds_write_b32 v128, v32 offset:49856
.LBB0_171:
	s_or_b64 exec, exec, s[2:3]
	v_mul_f32_e32 v32, v25, v25
	v_fmac_f32_e32 v32, v24, v24
	v_fmac_f32_e32 v32, v26, v26
	v_fmac_f32_e32 v32, v27, v27
	v_fmac_f32_e32 v32, v28, v28
	v_fmac_f32_e32 v32, v29, v29
	v_fmac_f32_e32 v32, v30, v30
	v_fmac_f32_e32 v32, v31, v31
	v_mov_b32_e32 v33, v32
	s_nop 1
	v_permlane16_swap_b32_e32 v32, v33
	v_add_f32_e32 v129, v32, v33
	v_mov_b32_e32 v130, v129
	s_nop 1
	v_permlane32_swap_b32_e32 v129, v130
	s_and_saveexec_b64 s[2:3], vcc
	s_cbranch_execz .LBB0_173
	v_add_f32_e32 v32, v129, v130
	s_nop 0
	ds_write_b32 v128, v32 offset:49920
.LBB0_173:
	s_or_b64 exec, exec, s[2:3]
	v_mul_f32_e32 v32, v17, v17
	v_fmac_f32_e32 v32, v16, v16
	v_fmac_f32_e32 v32, v18, v18
	v_fmac_f32_e32 v32, v19, v19
	v_fmac_f32_e32 v32, v20, v20
	v_fmac_f32_e32 v32, v21, v21
	v_fmac_f32_e32 v32, v22, v22
	v_fmac_f32_e32 v32, v23, v23
	v_mov_b32_e32 v33, v32
	s_nop 1
	v_permlane16_swap_b32_e32 v32, v33
	v_add_f32_e32 v129, v32, v33
	v_mov_b32_e32 v130, v129
	s_nop 1
	v_permlane32_swap_b32_e32 v129, v130
	s_and_saveexec_b64 s[2:3], vcc
	s_cbranch_execz .LBB0_175
	v_add_f32_e32 v32, v129, v130
	s_nop 0
	ds_write_b32 v128, v32 offset:49984
.LBB0_175:
	s_or_b64 exec, exec, s[2:3]
	v_mul_f32_e32 v32, v9, v9
	v_fmac_f32_e32 v32, v8, v8
	v_fmac_f32_e32 v32, v10, v10
	v_fmac_f32_e32 v32, v11, v11
	v_fmac_f32_e32 v32, v12, v12
	v_fmac_f32_e32 v32, v13, v13
	v_fmac_f32_e32 v32, v14, v14
	v_fmac_f32_e32 v32, v15, v15
	v_mov_b32_e32 v33, v32
	s_nop 1
	v_permlane16_swap_b32_e32 v32, v33
	v_add_f32_e32 v129, v32, v33
	v_mov_b32_e32 v130, v129
	s_nop 1
	v_permlane32_swap_b32_e32 v129, v130
	s_and_saveexec_b64 s[2:3], vcc
	s_cbranch_execz .LBB0_177
	v_add_f32_e32 v32, v129, v130
	s_nop 0
	ds_write_b32 v128, v32 offset:50048
.LBB0_177:
	s_or_b64 exec, exec, s[2:3]
	v_mul_f32_e32 v32, v1, v1
	v_fmac_f32_e32 v32, v0, v0
	v_fmac_f32_e32 v32, v2, v2
	v_fmac_f32_e32 v32, v3, v3
	v_fmac_f32_e32 v32, v4, v4
	v_fmac_f32_e32 v32, v5, v5
	v_fmac_f32_e32 v32, v6, v6
	v_fmac_f32_e32 v32, v7, v7
	v_mov_b32_e32 v33, v32
	s_nop 1
	v_permlane16_swap_b32_e32 v32, v33
	v_add_f32_e32 v129, v32, v33
	v_mov_b32_e32 v130, v129
	s_nop 1
	v_permlane32_swap_b32_e32 v129, v130
	s_and_saveexec_b64 s[2:3], vcc
	s_cbranch_execz .LBB0_179
	v_add_f32_e32 v32, v129, v130
	s_nop 0
	ds_write_b32 v128, v32 offset:50112
.LBB0_179:
	s_or_b64 exec, exec, s[2:3]
	s_mov_b64 s[2:3], 0
	s_waitcnt lgkmcnt(0)
	s_barrier

.LBB0_504:
	s_movk_i32 s11, 0x7fe0
	v_cmp_gt_i32_e64 s[48:49], s11, v146
	s_movk_i32 s11, 0x7fd0
	v_cmp_gt_i32_e64 s[46:47], s11, v146
	s_movk_i32 s11, 0x7f80
	v_cmp_gt_i32_e64 s[44:45], s11, v146
	s_movk_i32 s11, 0x7f70
	v_bfe_i32 v33, v147, 4, 1
	s_and_b64 vcc, exec, s[0:1]
	s_mov_b32 s0, 0x8000
	v_cmp_gt_i32_e64 s[42:43], s11, v146
	s_movk_i32 s11, 0x7f60
	v_lshlrev_b32_e32 v32, 2, v148
	v_and_b32_e32 v33, 12, v33
	v_cmp_gt_i32_e64 s[52:53], s0, v146
	s_movk_i32 s0, 0x7ff0
	v_add_u32_e32 v152, 0x90, v146
	v_cmp_gt_i32_e64 s[40:41], s11, v146
	s_movk_i32 s11, 0x7f50
	s_lshl_b32 s21, s21, 5
	v_lshlrev_b32_e32 v150, 2, v162
	v_or_b32_e32 v150, 0x20010, v150
	v_or_b32_e32 v158, 16, v146
	v_cmp_gt_i32_e64 s[0:1], s0, v146
	v_or_b32_e32 v156, 32, v146
	v_or_b32_e32 v155, 48, v146
	v_add_u32_e32 v153, 0x80, v146
	v_lshlrev_b32_e32 v161, 2, v32
	v_lshlrev_b32_e32 v138, 1, v32
	v_lshlrev_b32_e32 v136, 1, v33
	v_bitop3_b32 v160, v146, 31, 16 bitop3:0xc8
	v_bitop3_b32 v159, v146, 47, 32 bitop3:0xc8
	v_bitop3_b32 v157, v146, 63, 48 bitop3:0xc8
	v_and_b32_e32 v154, 31, v152
	v_add_u32_e32 v151, 0xa0, v146
	v_add_u32_e32 v149, 0xb0, v146
	v_cmp_gt_i32_e64 s[38:39], s11, v146
	s_cbranch_vccz .LBB0_506
	s_cmpk_lt_i32 s3, 0x400
	s_cselect_b64 vcc, -1, 0
	v_mov_b32_e32 v32, 0x3e38aa3b
	v_mov_b32_e32 v176, 0xfc0
	v_cndmask_b32_e32 v140, 1.0, v32, vcc
	s_and_b64 s[26:27], vcc, exec
	v_cndmask_b32_e64 v32, v176, v236, s[52:53]
	v_readlane_b32 s3, v255, 5
	v_readlane_b32 s11, v255, 7
	v_and_b32_e32 v32, s18, v32
	s_cselect_b32 s3, s3, s11
	v_readlane_b32 s11, v255, 4
	v_readlane_b32 s26, v255, 6
	v_lshrrev_b32_e32 v32, 6, v32
	s_cselect_b32 s11, s11, s26
	s_lshl_b32 s26, s21, 2
	v_cndmask_b32_e64 v32, v141, v32, s[36:37]
	s_add_u32 s26, s11, s26
	v_lshl_or_b32 v128, v32, 7, v150
	s_addc_u32 s27, s3, 0
	ds_read_b128 v[32:35], v128 offset:16
	ds_read_b128 v[166:169], v128
	s_nop 0
	s_and_b32 s27, vcc_lo, 0x100
	s_sub_u32 s27, 0x22110, s27
	s_lshl_b32 s26, s21, 2
	s_add_u32 s26, s26, s27
	v_add_u32_e32 v184, s26, v161
	ds_read_b128 v[128:131], v184
	ds_read_b128 v[132:135], v184 offset:64
	v_mov_b64_e32 v[142:143], s[92:93]
	v_cndmask_b32_e64 v163, v176, v236, s[0:1]
	v_mad_i64_i32 v[170:171], s[0:1], v146, s33, v[142:143]
	v_and_b32_e32 v163, s18, v163
	v_lshrrev_b32_e32 v163, 6, v163
	s_lshl_b32 s0, s20, 8
	v_cndmask_b32_e64 v165, v160, v163, s[36:37]
	v_or_b32_e32 v163, s0, v141
	v_bitop3_b32 v164, s0, v231, v141 bitop3:0x36
	v_lshlrev_b32_e32 v163, 2, v163
	v_lshlrev_b32_e32 v164, 2, v164
	v_add_u32_e32 v163, 0xc000, v163
	v_add_u32_e32 v164, 0xc000, v164
	s_waitcnt lgkmcnt(0)
	ds_read2_b32 v[172:173], v163 offset1:16
	ds_read2_b32 v[174:175], v164 offset1:16
	s_mov_b32 s26, 0x358637bd
	v_mov_b64_e32 v[144:145], s[26:27]
	s_mov_b32 s28, 0x3c800000
	s_waitcnt lgkmcnt(0)
	v_mov_b32_e32 v178, v173
	v_mov_b32_e32 v179, v172
	v_mov_b32_e32 v172, v175
	v_mov_b32_e32 v173, v174
	v_pk_add_f32 v[172:173], v[178:179], v[172:173]
	s_mov_b32 s11, s55
	v_pk_fma_f32 v[172:173], v[172:173], s[28:29], v[144:145] op_sel_hi:[1,0,0]
	s_lshl_b64 s[0:1], s[10:11], 1
	v_mul_f32_e32 v174, 0x4b800000, v173
	v_cmp_gt_f32_e32 vcc, s91, v173
	v_mov_b32_e32 v139, v177
	v_lshl_add_u64 v[170:171], v[170:171], 0, s[0:1]
	v_cndmask_b32_e32 v173, v173, v174, vcc
	v_rsq_f32_e32 v173, v173
	v_mov_b32_e32 v137, v177
	v_lshl_add_u64 v[170:171], v[170:171], 0, v[138:139]
	v_lshl_add_u64 v[170:171], v[170:171], 0, v[136:137]
	v_mul_f32_e32 v174, 0x45800000, v173
	v_cndmask_b32_e32 v174, v173, v174, vcc
	v_pk_mul_f32 v[120:121], v[120:121], v[174:175] op_sel_hi:[1,0]
	v_pk_mul_f32 v[124:125], v[124:125], v[174:175] op_sel_hi:[1,0]
	v_pk_mul_f32 v[126:127], v[126:127], v[174:175] op_sel_hi:[1,0]
	v_pk_mul_f32 v[122:123], v[122:123], v[174:175] op_sel_hi:[1,0]
	v_lshl_or_b32 v165, v165, 7, v150
	v_cmp_gt_f32_e32 vcc, s91, v172
	v_pk_mul_f32 v[122:123], v[130:131], v[122:123]
	v_mov_b32_e32 v174, v166
	v_mov_b32_e32 v175, v168
	v_mov_b32_e32 v168, v167
	v_mov_b32_e32 v166, v32
	v_mov_b32_e32 v167, v34
	v_mov_b32_e32 v34, v33
	v_pk_mul_f32 v[32:33], v[128:129], v[120:121]
	v_pk_mul_f32 v[120:121], v[132:133], v[124:125]
	v_pk_mul_f32 v[124:125], v[134:135], v[126:127]
	v_pk_mul_f32 v[126:127], v[168:169], v[120:121]
	v_pk_mul_f32 v[120:121], v[174:175], v[120:121]
	v_pk_mul_f32 v[178:179], v[34:35], v[124:125]
	v_pk_mul_f32 v[124:125], v[166:167], v[124:125]
	v_pk_fma_f32 v[126:127], v[174:175], v[32:33], v[126:127] neg_lo:[0,0,1] neg_hi:[0,0,1]
	v_pk_fma_f32 v[32:33], v[168:169], v[32:33], v[120:121]
	v_pk_fma_f32 v[120:121], v[166:167], v[122:123], v[178:179] neg_lo:[0,0,1] neg_hi:[0,0,1]
	v_pk_fma_f32 v[34:35], v[34:35], v[122:123], v[124:125]
	v_pk_mul_f32 v[122:123], v[140:141], v[126:127] op_sel_hi:[0,1]
	v_pk_mul_f32 v[124:125], v[140:141], v[32:33] op_sel_hi:[0,1]
	v_pk_mul_f32 v[120:121], v[140:141], v[120:121] op_sel_hi:[0,1]
	v_pk_mul_f32 v[126:127], v[140:141], v[34:35] op_sel_hi:[0,1]
	v_cvt_pk_bf16_f32 v32, v122, v123
	v_cvt_pk_bf16_f32 v33, v120, v121
	v_cvt_pk_bf16_f32 v34, v124, v125
	v_cvt_pk_bf16_f32 v35, v126, v127
	s_nop 0
	v_permlane16_swap_b32_e32 v32, v34
	v_permlane16_swap_b32_e32 v33, v35
	global_store_dwordx4 v[170:171], v[32:35], off
	s_nop 0
	ds_read_b128 v[32:35], v165
	s_nop 0
	ds_read_b128 v[120:123], v165 offset:16
	v_cndmask_b32_e64 v126, v176, v236, s[48:49]
	v_and_b32_e32 v126, s18, v126
	v_lshrrev_b32_e32 v126, 6, v126
	v_cndmask_b32_e64 v126, v159, v126, s[36:37]
	v_lshl_or_b32 v165, v126, 7, v150
	v_mul_f32_e32 v126, 0x4b800000, v172
	v_cndmask_b32_e32 v126, v172, v126, vcc
	v_rsq_f32_e32 v126, v126
	v_mad_i64_i32 v[124:125], s[26:27], v158, s33, v[142:143]
	v_lshl_add_u64 v[124:125], v[124:125], 0, s[0:1]
	v_mul_f32_e32 v127, 0x45800000, v126
	v_cndmask_b32_e32 v126, v126, v127, vcc
	v_pk_mul_f32 v[116:117], v[116:117], v[126:127] op_sel_hi:[1,0]
	v_pk_mul_f32 v[118:119], v[118:119], v[126:127] op_sel_hi:[1,0]
	v_pk_mul_f32 v[112:113], v[112:113], v[126:127] op_sel_hi:[1,0]
	v_pk_mul_f32 v[114:115], v[114:115], v[126:127] op_sel_hi:[1,0]
	v_pk_mul_f32 v[116:117], v[132:133], v[116:117]
	v_pk_mul_f32 v[118:119], v[134:135], v[118:119]
	v_pk_mul_f32 v[112:113], v[128:129], v[112:113]
	v_pk_mul_f32 v[114:115], v[130:131], v[114:115]
	v_lshl_add_u64 v[124:125], v[124:125], 0, v[138:139]
	v_lshl_add_u64 v[124:125], v[124:125], 0, v[136:137]
	s_waitcnt lgkmcnt(1)
	v_mov_b32_e32 v126, v32
	v_mov_b32_e32 v127, v34
	v_mov_b32_e32 v34, v33
	s_waitcnt lgkmcnt(0)
	v_mov_b32_e32 v32, v120
	v_mov_b32_e32 v33, v122
	v_mov_b32_e32 v122, v121
	v_pk_mul_f32 v[120:121], v[34:35], v[116:117]
	v_pk_mul_f32 v[116:117], v[126:127], v[116:117]
	v_pk_mul_f32 v[166:167], v[122:123], v[118:119]
	v_pk_mul_f32 v[118:119], v[32:33], v[118:119]
	v_pk_fma_f32 v[120:121], v[126:127], v[112:113], v[120:121] neg_lo:[0,0,1] neg_hi:[0,0,1]
	v_pk_fma_f32 v[34:35], v[34:35], v[112:113], v[116:117]
	v_pk_fma_f32 v[32:33], v[32:33], v[114:115], v[166:167] neg_lo:[0,0,1] neg_hi:[0,0,1]
	v_pk_fma_f32 v[112:113], v[122:123], v[114:115], v[118:119]
	v_pk_mul_f32 v[114:115], v[140:141], v[120:121] op_sel_hi:[0,1]
	v_pk_mul_f32 v[34:35], v[140:141], v[34:35] op_sel_hi:[0,1]
	v_pk_mul_f32 v[116:117], v[140:141], v[32:33] op_sel_hi:[0,1]
	v_pk_mul_f32 v[112:113], v[140:141], v[112:113] op_sel_hi:[0,1]
	v_cvt_pk_bf16_f32 v32, v114, v115
	v_cvt_pk_bf16_f32 v33, v116, v117
	v_cvt_pk_bf16_f32 v34, v34, v35
	v_cvt_pk_bf16_f32 v35, v112, v113
	s_nop 0
	v_permlane16_swap_b32_e32 v32, v34
	v_permlane16_swap_b32_e32 v33, v35
	global_store_dwordx4 v[124:125], v[32:35], off
	s_nop 0
	ds_read_b128 v[32:35], v165
	s_nop 0
	ds_read_b128 v[112:115], v165 offset:16
	v_cndmask_b32_e64 v118, v176, v236, s[46:47]
	v_and_b32_e32 v120, s18, v118
	ds_read2_b32 v[118:119], v163 offset0:32 offset1:48
	v_lshrrev_b32_e32 v122, 6, v120
	ds_read2_b32 v[120:121], v164 offset0:32 offset1:48
	v_cndmask_b32_e64 v122, v157, v122, s[36:37]
	v_lshl_or_b32 v124, v122, 7, v150
	s_waitcnt lgkmcnt(1)
	v_mov_b32_e32 v122, v119
	v_mov_b32_e32 v123, v118
	s_waitcnt lgkmcnt(0)
	v_mov_b32_e32 v118, v121
	v_mov_b32_e32 v119, v120
	v_pk_add_f32 v[118:119], v[122:123], v[118:119]
	v_mad_i64_i32 v[116:117], s[26:27], v156, s33, v[142:143]
	v_pk_fma_f32 v[118:119], v[118:119], s[28:29], v[144:145] op_sel_hi:[1,0,0]
	v_lshl_add_u64 v[116:117], v[116:117], 0, s[0:1]
	v_mul_f32_e32 v120, 0x4b800000, v119
	v_cmp_gt_f32_e32 vcc, s91, v119
	v_lshl_add_u64 v[116:117], v[116:117], 0, v[138:139]
	v_lshl_add_u64 v[116:117], v[116:117], 0, v[136:137]
	v_cndmask_b32_e32 v119, v119, v120, vcc
	v_rsq_f32_e32 v119, v119
	s_nop 0
	v_mul_f32_e32 v120, 0x45800000, v119
	v_cndmask_b32_e32 v120, v119, v120, vcc
	v_pk_mul_f32 v[108:109], v[108:109], v[120:121] op_sel_hi:[1,0]
	v_pk_mul_f32 v[110:111], v[110:111], v[120:121] op_sel_hi:[1,0]
	v_pk_mul_f32 v[104:105], v[104:105], v[120:121] op_sel_hi:[1,0]
	v_pk_mul_f32 v[106:107], v[106:107], v[120:121] op_sel_hi:[1,0]
	v_pk_mul_f32 v[108:109], v[132:133], v[108:109]
	v_pk_mul_f32 v[110:111], v[134:135], v[110:111]
	v_pk_mul_f32 v[104:105], v[128:129], v[104:105]
	v_pk_mul_f32 v[106:107], v[130:131], v[106:107]
	v_cmp_gt_f32_e32 vcc, s91, v118
	s_waitcnt lgkmcnt(1)
	v_mov_b32_e32 v120, v32
	v_mov_b32_e32 v121, v34
	v_mov_b32_e32 v34, v33
	s_waitcnt lgkmcnt(0)
	v_mov_b32_e32 v32, v112
	v_mov_b32_e32 v33, v114
	v_mov_b32_e32 v114, v113
	v_pk_mul_f32 v[112:113], v[34:35], v[108:109]
	v_pk_mul_f32 v[108:109], v[120:121], v[108:109]
	v_pk_mul_f32 v[122:123], v[114:115], v[110:111]
	v_pk_mul_f32 v[110:111], v[32:33], v[110:111]
	v_pk_fma_f32 v[112:113], v[120:121], v[104:105], v[112:113] neg_lo:[0,0,1] neg_hi:[0,0,1]
	v_pk_fma_f32 v[34:35], v[34:35], v[104:105], v[108:109]
	v_pk_fma_f32 v[32:33], v[32:33], v[106:107], v[122:123] neg_lo:[0,0,1] neg_hi:[0,0,1]
	v_pk_fma_f32 v[104:105], v[114:115], v[106:107], v[110:111]
	v_pk_mul_f32 v[106:107], v[140:141], v[112:113] op_sel_hi:[0,1]
	v_pk_mul_f32 v[34:35], v[140:141], v[34:35] op_sel_hi:[0,1]
	v_pk_mul_f32 v[108:109], v[140:141], v[32:33] op_sel_hi:[0,1]
	v_pk_mul_f32 v[104:105], v[140:141], v[104:105] op_sel_hi:[0,1]
	v_cvt_pk_bf16_f32 v32, v106, v107
	v_cvt_pk_bf16_f32 v33, v108, v109
	v_cvt_pk_bf16_f32 v34, v34, v35
	v_cvt_pk_bf16_f32 v35, v104, v105
	s_nop 0
	v_permlane16_swap_b32_e32 v32, v34
	v_permlane16_swap_b32_e32 v33, v35
	global_store_dwordx4 v[116:117], v[32:35], off
	s_nop 0
	ds_read_b128 v[32:35], v124
	s_nop 0
	ds_read_b128 v[104:107], v124 offset:16
	v_cndmask_b32_e64 v110, v176, v236, s[44:45]
	v_and_b32_e32 v110, v110, v153
	v_lshrrev_b32_e32 v110, 6, v110
	v_cndmask_b32_e64 v110, v141, v110, s[36:37]
	v_lshl_or_b32 v114, v110, 7, v150
	v_mul_f32_e32 v110, 0x4b800000, v118
	v_cndmask_b32_e32 v110, v118, v110, vcc
	v_rsq_f32_e32 v110, v110
	v_mad_i64_i32 v[108:109], s[26:27], v155, s33, v[142:143]
	v_lshl_add_u64 v[108:109], v[108:109], 0, s[0:1]
	v_mul_f32_e32 v111, 0x45800000, v110
	v_cndmask_b32_e32 v110, v110, v111, vcc
	v_pk_mul_f32 v[100:101], v[100:101], v[110:111] op_sel_hi:[1,0]
	v_pk_mul_f32 v[102:103], v[102:103], v[110:111] op_sel_hi:[1,0]
	v_pk_mul_f32 v[96:97], v[96:97], v[110:111] op_sel_hi:[1,0]
	v_pk_mul_f32 v[98:99], v[98:99], v[110:111] op_sel_hi:[1,0]
	v_pk_mul_f32 v[100:101], v[132:133], v[100:101]
	v_pk_mul_f32 v[102:103], v[134:135], v[102:103]
	v_pk_mul_f32 v[96:97], v[128:129], v[96:97]
	v_pk_mul_f32 v[98:99], v[130:131], v[98:99]
	v_lshl_add_u64 v[108:109], v[108:109], 0, v[138:139]
	v_lshl_add_u64 v[108:109], v[108:109], 0, v[136:137]
	s_waitcnt lgkmcnt(1)
	v_mov_b32_e32 v110, v32
	v_mov_b32_e32 v111, v34
	v_mov_b32_e32 v34, v33
	s_waitcnt lgkmcnt(0)
	v_mov_b32_e32 v32, v104
	v_mov_b32_e32 v33, v106
	v_mov_b32_e32 v106, v105
	v_pk_mul_f32 v[104:105], v[34:35], v[100:101]
	v_pk_mul_f32 v[100:101], v[110:111], v[100:101]
	v_pk_mul_f32 v[112:113], v[106:107], v[102:103]
	v_pk_mul_f32 v[102:103], v[32:33], v[102:103]
	v_pk_fma_f32 v[104:105], v[110:111], v[96:97], v[104:105] neg_lo:[0,0,1] neg_hi:[0,0,1]
	v_pk_fma_f32 v[34:35], v[34:35], v[96:97], v[100:101]
	v_pk_fma_f32 v[32:33], v[32:33], v[98:99], v[112:113] neg_lo:[0,0,1] neg_hi:[0,0,1]
	v_pk_fma_f32 v[96:97], v[106:107], v[98:99], v[102:103]
	v_pk_mul_f32 v[98:99], v[140:141], v[104:105] op_sel_hi:[0,1]
	v_pk_mul_f32 v[34:35], v[140:141], v[34:35] op_sel_hi:[0,1]
	v_pk_mul_f32 v[100:101], v[140:141], v[32:33] op_sel_hi:[0,1]
	v_pk_mul_f32 v[96:97], v[140:141], v[96:97] op_sel_hi:[0,1]
	v_cvt_pk_bf16_f32 v32, v98, v99
	v_cvt_pk_bf16_f32 v33, v100, v101
	v_cvt_pk_bf16_f32 v34, v34, v35
	v_cvt_pk_bf16_f32 v35, v96, v97
	s_nop 0
	v_permlane16_swap_b32_e32 v32, v34
	v_permlane16_swap_b32_e32 v33, v35
	global_store_dwordx4 v[108:109], v[32:35], off
	s_nop 0
	ds_read_b128 v[32:35], v114
	s_nop 0
	ds_read_b128 v[96:99], v114 offset:16
	v_cndmask_b32_e64 v102, v176, v236, s[42:43]
	v_and_b32_e32 v104, v102, v152
	ds_read2_b32 v[102:103], v163 offset0:128 offset1:144
	v_lshrrev_b32_e32 v106, 6, v104
	ds_read2_b32 v[104:105], v164 offset0:128 offset1:144
	v_cndmask_b32_e64 v106, v154, v106, s[36:37]
	v_lshl_or_b32 v108, v106, 7, v150
	s_waitcnt lgkmcnt(1)
	v_mov_b32_e32 v106, v103
	v_mov_b32_e32 v107, v102
	s_waitcnt lgkmcnt(0)
	v_mov_b32_e32 v102, v105
	v_mov_b32_e32 v103, v104
	v_pk_add_f32 v[102:103], v[106:107], v[102:103]
	v_mad_i64_i32 v[100:101], s[26:27], v153, s33, v[142:143]
	v_pk_fma_f32 v[102:103], v[102:103], s[28:29], v[144:145] op_sel_hi:[1,0,0]
	v_lshl_add_u64 v[100:101], v[100:101], 0, s[0:1]
	v_mul_f32_e32 v104, 0x4b800000, v103
	v_cmp_gt_f32_e32 vcc, s91, v103
	v_lshl_add_u64 v[100:101], v[100:101], 0, v[138:139]
	v_lshl_add_u64 v[100:101], v[100:101], 0, v[136:137]
	v_cndmask_b32_e32 v103, v103, v104, vcc
	v_rsq_f32_e32 v103, v103
	s_nop 0
	v_mul_f32_e32 v104, 0x45800000, v103
	v_cndmask_b32_e32 v104, v103, v104, vcc
	v_pk_mul_f32 v[92:93], v[210:211], v[104:105] op_sel_hi:[1,0]
	v_pk_mul_f32 v[94:95], v[212:213], v[104:105] op_sel_hi:[1,0]
	v_pk_mul_f32 v[88:89], v[88:89], v[104:105] op_sel_hi:[1,0]
	v_pk_mul_f32 v[90:91], v[90:91], v[104:105] op_sel_hi:[1,0]
	v_pk_mul_f32 v[92:93], v[132:133], v[92:93]
	v_pk_mul_f32 v[94:95], v[134:135], v[94:95]
	v_pk_mul_f32 v[88:89], v[128:129], v[88:89]
	v_pk_mul_f32 v[90:91], v[130:131], v[90:91]
	v_cmp_gt_f32_e32 vcc, s91, v102
	s_waitcnt lgkmcnt(1)
	v_mov_b32_e32 v104, v32
	v_mov_b32_e32 v105, v34
	v_mov_b32_e32 v34, v33
	s_waitcnt lgkmcnt(0)
	v_mov_b32_e32 v32, v96
	v_mov_b32_e32 v33, v98
	v_mov_b32_e32 v98, v97
	v_pk_mul_f32 v[96:97], v[34:35], v[92:93]
	v_pk_mul_f32 v[92:93], v[104:105], v[92:93]
	v_pk_mul_f32 v[106:107], v[98:99], v[94:95]
	v_pk_mul_f32 v[94:95], v[32:33], v[94:95]
	v_pk_fma_f32 v[96:97], v[104:105], v[88:89], v[96:97] neg_lo:[0,0,1] neg_hi:[0,0,1]
	v_pk_fma_f32 v[34:35], v[34:35], v[88:89], v[92:93]
	v_pk_fma_f32 v[32:33], v[32:33], v[90:91], v[106:107] neg_lo:[0,0,1] neg_hi:[0,0,1]
	v_pk_fma_f32 v[88:89], v[98:99], v[90:91], v[94:95]
	v_pk_mul_f32 v[90:91], v[140:141], v[96:97] op_sel_hi:[0,1]
	v_pk_mul_f32 v[34:35], v[140:141], v[34:35] op_sel_hi:[0,1]
	v_pk_mul_f32 v[92:93], v[140:141], v[32:33] op_sel_hi:[0,1]
	v_pk_mul_f32 v[88:89], v[140:141], v[88:89] op_sel_hi:[0,1]
	v_cvt_pk_bf16_f32 v32, v90, v91
	v_cvt_pk_bf16_f32 v33, v92, v93
	v_cvt_pk_bf16_f32 v34, v34, v35
	v_cvt_pk_bf16_f32 v35, v88, v89
	s_nop 0
	v_permlane16_swap_b32_e32 v32, v34
	v_permlane16_swap_b32_e32 v33, v35
	global_store_dwordx4 v[100:101], v[32:35], off
	s_nop 0
	ds_read_b128 v[32:35], v108
	s_nop 0
	ds_read_b128 v[88:91], v108 offset:16
	v_cndmask_b32_e64 v94, v176, v236, s[40:41]
	v_and_b32_e32 v94, v94, v151
	v_and_b32_e32 v95, 47, v151
	v_lshrrev_b32_e32 v94, 6, v94
	v_cndmask_b32_e64 v94, v95, v94, s[36:37]
	v_lshl_or_b32 v98, v94, 7, v150
	v_mul_f32_e32 v94, 0x4b800000, v102
	v_cndmask_b32_e32 v94, v102, v94, vcc
	v_rsq_f32_e32 v94, v94
	v_mad_i64_i32 v[92:93], s[26:27], v152, s33, v[142:143]
	v_lshl_add_u64 v[92:93], v[92:93], 0, s[0:1]
	v_mul_f32_e32 v95, 0x45800000, v94
	v_cndmask_b32_e32 v94, v94, v95, vcc
	v_pk_mul_f32 v[84:85], v[84:85], v[94:95] op_sel_hi:[1,0]
	v_pk_mul_f32 v[86:87], v[86:87], v[94:95] op_sel_hi:[1,0]
	v_pk_mul_f32 v[80:81], v[80:81], v[94:95] op_sel_hi:[1,0]
	v_pk_mul_f32 v[82:83], v[82:83], v[94:95] op_sel_hi:[1,0]
	v_pk_mul_f32 v[84:85], v[132:133], v[84:85]
	v_pk_mul_f32 v[86:87], v[134:135], v[86:87]
	v_pk_mul_f32 v[80:81], v[128:129], v[80:81]
	v_pk_mul_f32 v[82:83], v[130:131], v[82:83]
	v_lshl_add_u64 v[92:93], v[92:93], 0, v[138:139]
	v_lshl_add_u64 v[92:93], v[92:93], 0, v[136:137]
	s_waitcnt lgkmcnt(1)
	v_mov_b32_e32 v94, v32
	v_mov_b32_e32 v95, v34
	v_mov_b32_e32 v34, v33
	s_waitcnt lgkmcnt(0)
	v_mov_b32_e32 v32, v88
	v_mov_b32_e32 v33, v90
	v_mov_b32_e32 v90, v89
	v_pk_mul_f32 v[88:89], v[34:35], v[84:85]
	v_pk_mul_f32 v[84:85], v[94:95], v[84:85]
	v_pk_mul_f32 v[96:97], v[90:91], v[86:87]
	v_pk_mul_f32 v[86:87], v[32:33], v[86:87]
	v_pk_fma_f32 v[88:89], v[94:95], v[80:81], v[88:89] neg_lo:[0,0,1] neg_hi:[0,0,1]
	v_pk_fma_f32 v[34:35], v[34:35], v[80:81], v[84:85]
	v_pk_fma_f32 v[32:33], v[32:33], v[82:83], v[96:97] neg_lo:[0,0,1] neg_hi:[0,0,1]
	v_pk_fma_f32 v[80:81], v[90:91], v[82:83], v[86:87]
	v_pk_mul_f32 v[82:83], v[140:141], v[88:89] op_sel_hi:[0,1]
	v_pk_mul_f32 v[34:35], v[140:141], v[34:35] op_sel_hi:[0,1]
	v_pk_mul_f32 v[84:85], v[140:141], v[32:33] op_sel_hi:[0,1]
	v_pk_mul_f32 v[80:81], v[140:141], v[80:81] op_sel_hi:[0,1]
	v_cvt_pk_bf16_f32 v32, v82, v83
	v_cvt_pk_bf16_f32 v33, v84, v85
	v_cvt_pk_bf16_f32 v34, v34, v35
	v_cvt_pk_bf16_f32 v35, v80, v81
	s_nop 0
	v_permlane16_swap_b32_e32 v32, v34
	v_permlane16_swap_b32_e32 v33, v35
	global_store_dwordx4 v[92:93], v[32:35], off
	s_nop 0
	ds_read_b128 v[32:35], v98
	s_nop 0
	ds_read_b128 v[80:83], v98 offset:16
	v_cndmask_b32_e64 v86, v176, v236, s[38:39]
	v_and_b32_e32 v88, v86, v149
	ds_read2_b32 v[86:87], v163 offset0:160 offset1:176
	v_lshrrev_b32_e32 v91, 6, v88
	ds_read2_b32 v[88:89], v164 offset0:160 offset1:176
	v_and_b32_e32 v90, 63, v149
	v_cndmask_b32_e64 v90, v90, v91, s[36:37]
	v_lshl_or_b32 v92, v90, 7, v150
	s_waitcnt lgkmcnt(1)
	v_mov_b32_e32 v90, v87
	v_mov_b32_e32 v91, v86
	s_waitcnt lgkmcnt(0)
	v_mov_b32_e32 v86, v89
	v_mov_b32_e32 v87, v88
	v_pk_add_f32 v[86:87], v[90:91], v[86:87]
	v_mad_i64_i32 v[84:85], s[26:27], v151, s33, v[142:143]
	v_pk_fma_f32 v[86:87], v[86:87], s[28:29], v[144:145] op_sel_hi:[1,0,0]
	v_lshl_add_u64 v[84:85], v[84:85], 0, s[0:1]
	v_mul_f32_e32 v88, 0x4b800000, v87
	v_cmp_gt_f32_e32 vcc, s91, v87
	v_lshl_add_u64 v[84:85], v[84:85], 0, v[138:139]
	v_lshl_add_u64 v[84:85], v[84:85], 0, v[136:137]
	v_cndmask_b32_e32 v87, v87, v88, vcc
	v_rsq_f32_e32 v87, v87
	s_nop 0
	v_mul_f32_e32 v88, 0x45800000, v87
	v_cndmask_b32_e32 v88, v87, v88, vcc
	v_pk_mul_f32 v[76:77], v[76:77], v[88:89] op_sel_hi:[1,0]
	v_pk_mul_f32 v[78:79], v[78:79], v[88:89] op_sel_hi:[1,0]
	v_pk_mul_f32 v[72:73], v[72:73], v[88:89] op_sel_hi:[1,0]
	v_pk_mul_f32 v[74:75], v[74:75], v[88:89] op_sel_hi:[1,0]
	v_pk_mul_f32 v[76:77], v[132:133], v[76:77]
	v_pk_mul_f32 v[78:79], v[134:135], v[78:79]
	v_pk_mul_f32 v[72:73], v[128:129], v[72:73]
	v_pk_mul_f32 v[74:75], v[130:131], v[74:75]
	v_cmp_gt_f32_e32 vcc, s91, v86
	s_waitcnt lgkmcnt(1)
	v_mov_b32_e32 v88, v32
	v_mov_b32_e32 v89, v34
	v_mov_b32_e32 v34, v33
	s_waitcnt lgkmcnt(0)
	v_mov_b32_e32 v32, v80
	v_mov_b32_e32 v33, v82
	v_mov_b32_e32 v82, v81
	v_pk_mul_f32 v[80:81], v[34:35], v[76:77]
	v_pk_mul_f32 v[76:77], v[88:89], v[76:77]
	v_pk_mul_f32 v[90:91], v[82:83], v[78:79]
	v_pk_mul_f32 v[78:79], v[32:33], v[78:79]
	v_pk_fma_f32 v[80:81], v[88:89], v[72:73], v[80:81] neg_lo:[0,0,1] neg_hi:[0,0,1]
	v_pk_fma_f32 v[34:35], v[34:35], v[72:73], v[76:77]
	v_pk_fma_f32 v[32:33], v[32:33], v[74:75], v[90:91] neg_lo:[0,0,1] neg_hi:[0,0,1]
	v_pk_fma_f32 v[72:73], v[82:83], v[74:75], v[78:79]
	v_pk_mul_f32 v[74:75], v[140:141], v[80:81] op_sel_hi:[0,1]
	v_pk_mul_f32 v[34:35], v[140:141], v[34:35] op_sel_hi:[0,1]
	v_pk_mul_f32 v[76:77], v[140:141], v[32:33] op_sel_hi:[0,1]
	v_pk_mul_f32 v[72:73], v[140:141], v[72:73] op_sel_hi:[0,1]
	v_cvt_pk_bf16_f32 v32, v74, v75
	v_cvt_pk_bf16_f32 v33, v76, v77
	v_cvt_pk_bf16_f32 v34, v34, v35
	v_cvt_pk_bf16_f32 v35, v72, v73
	s_nop 0
	v_permlane16_swap_b32_e32 v32, v34
	v_permlane16_swap_b32_e32 v33, v35
	global_store_dwordx4 v[84:85], v[32:35], off
	s_nop 0
	ds_read_b128 v[32:35], v92
	s_nop 0
	ds_read_b128 v[72:75], v92 offset:16
	v_mul_f32_e32 v76, 0x4b800000, v86
	v_cndmask_b32_e32 v76, v86, v76, vcc
	v_rsq_f32_e32 v78, v76
	v_mad_i64_i32 v[76:77], s[26:27], v149, s33, v[142:143]
	v_lshl_add_u64 v[76:77], v[76:77], 0, s[0:1]
	v_mul_f32_e32 v79, 0x45800000, v78
	v_cndmask_b32_e32 v78, v78, v79, vcc
	v_pk_mul_f32 v[68:69], v[68:69], v[78:79] op_sel_hi:[1,0]
	v_pk_mul_f32 v[70:71], v[70:71], v[78:79] op_sel_hi:[1,0]
	v_pk_mul_f32 v[64:65], v[64:65], v[78:79] op_sel_hi:[1,0]
	v_pk_mul_f32 v[66:67], v[66:67], v[78:79] op_sel_hi:[1,0]
	v_pk_mul_f32 v[68:69], v[132:133], v[68:69]
	v_pk_mul_f32 v[70:71], v[134:135], v[70:71]
	v_pk_mul_f32 v[64:65], v[128:129], v[64:65]
	v_pk_mul_f32 v[66:67], v[130:131], v[66:67]
	v_lshl_add_u64 v[76:77], v[76:77], 0, v[138:139]
	s_waitcnt lgkmcnt(1)
	v_mov_b32_e32 v78, v32
	v_mov_b32_e32 v79, v34
	v_mov_b32_e32 v34, v33
	s_waitcnt lgkmcnt(0)
	v_mov_b32_e32 v32, v72
	v_mov_b32_e32 v33, v74
	v_mov_b32_e32 v74, v73
	v_pk_mul_f32 v[72:73], v[34:35], v[68:69]
	v_pk_mul_f32 v[68:69], v[78:79], v[68:69]
	v_pk_mul_f32 v[80:81], v[74:75], v[70:71]
	v_pk_mul_f32 v[70:71], v[32:33], v[70:71]
	v_pk_fma_f32 v[72:73], v[78:79], v[64:65], v[72:73] neg_lo:[0,0,1] neg_hi:[0,0,1]
	v_pk_fma_f32 v[34:35], v[34:35], v[64:65], v[68:69]
	v_pk_fma_f32 v[32:33], v[32:33], v[66:67], v[80:81] neg_lo:[0,0,1] neg_hi:[0,0,1]
	v_pk_fma_f32 v[64:65], v[74:75], v[66:67], v[70:71]
	v_pk_mul_f32 v[66:67], v[140:141], v[72:73] op_sel_hi:[0,1]
	v_pk_mul_f32 v[34:35], v[140:141], v[34:35] op_sel_hi:[0,1]
	v_pk_mul_f32 v[68:69], v[140:141], v[32:33] op_sel_hi:[0,1]
	v_pk_mul_f32 v[64:65], v[140:141], v[64:65] op_sel_hi:[0,1]
	v_cvt_pk_bf16_f32 v32, v66, v67
	v_cvt_pk_bf16_f32 v33, v68, v69
	v_cvt_pk_bf16_f32 v34, v34, v35
	v_cvt_pk_bf16_f32 v35, v64, v65
	s_nop 0
	v_permlane16_swap_b32_e32 v32, v34
	v_permlane16_swap_b32_e32 v33, v35
	v_lshl_add_u64 v[64:65], v[76:77], 0, v[136:137]
	global_store_dwordx4 v[64:65], v[32:35], off

.LBB0_834:
	v_lshlrev_b32_e32 v32, 1, v141
	v_lshl_add_u32 v33, v148, 7, s19
	v_add_u32_e32 v65, v33, v32
	v_cvt_pk_bf16_f32 v32, v60, s0
	s_nop 0
	ds_write_b16 v65, v32 offset:57856
	v_cvt_pk_bf16_f32 v32, v57, s0
	ds_write_b16 v65, v32 offset:57376
	v_cvt_pk_bf16_f32 v32, v61, s0
	ds_write_b16 v65, v32 offset:57888
	v_cvt_pk_bf16_f32 v32, v58, s0
	v_bfe_u32 v64, v147, 1, 5
	v_and_b32_e32 v67, 1, v147
	ds_write_b16 v65, v32 offset:57408
	v_cvt_pk_bf16_f32 v32, v62, s0
	v_lshl_add_u32 v34, v64, 5, s19
	v_lshlrev_b32_e32 v68, 4, v67
	ds_write_b16 v65, v32 offset:57920
	v_cvt_pk_bf16_f32 v32, v59, s0
	v_cvt_pk_bf16_f32 v35, v56, s0
	ds_write_b16 v65, v32 offset:57440
	v_cvt_pk_bf16_f32 v32, v63, s0
	v_add_u32_e32 v66, v34, v68
	s_lshl_b64 s[30:31], s[54:55], 1
	ds_write_b16 v65, v35 offset:57344
	ds_write_b16 v65, v32 offset:57952
	ds_read_b128 v[32:35], v66 offset:57344
	s_add_u32 s2, s2, s30
	v_mul_u32_u24_e32 v69, s0, v64
	s_addc_u32 s3, s3, s31
	v_lshlrev_b32_e32 v176, 1, v69
	v_lshl_add_u64 v[70:71], s[2:3], 0, v[176:177]
	v_mov_b32_e32 v69, v177
	s_or_b32 s19, s18, 16
	v_lshl_add_u64 v[68:69], v[70:71], 0, v[68:69]
	s_cmpk_lt_i32 s18, 0x7ff0
	s_mov_b64 s[2:3], -1
	s_waitcnt lgkmcnt(0)
	global_store_dwordx4 v[68:69], v[32:35], off
	s_cbranch_scc1 .LBB0_836
	s_add_i32 s0, s18, 0xffff8010
	s_lshr_b32 s0, s0, 11
	s_and_b32 s0, s0, 0x1ffffe
	s_add_i32 s0, s0, s11
	s_lshl_b32 s0, s0, 6
	s_or_b32 s54, s0, s28
	s_and_b32 s29, s19, 0xfd0
	s_lshl_b64 s[0:1], s[54:55], 13
	s_add_u32 s0, s39, s0
	s_addc_u32 s1, s40, s1
	s_mov_b64 s[2:3], 0
	s_mov_b32 s54, s29

.LBB0_864:
	s_andn2_b64 vcc, exec, s[0:1]
	s_cbranch_vccnz .LBB0_74
	s_cmpk_lt_i32 s26, 0x400
	s_cselect_b64 vcc, -1, 0
	s_and_b64 s[0:1], vcc, exec
	v_mov_b32_e32 v32, 0x3e38aa3b
	s_mov_b32 s0, 0x8000
	v_cndmask_b32_e32 v72, 1.0, v32, vcc
	v_cmp_gt_i32_e32 vcc, s0, v146
	v_mov_b32_e32 v92, 0xfc0
	v_readlane_b32 s0, v255, 5
	v_cndmask_b32_e32 v32, v92, v236, vcc
	v_readlane_b32 s1, v255, 7
	v_and_b32_e32 v32, s18, v32
	s_cselect_b32 s1, s0, s1
	v_readlane_b32 s0, v255, 4
	v_readlane_b32 s2, v255, 6
	v_lshrrev_b32_e32 v32, 6, v32
	s_cselect_b32 s0, s0, s2
	s_lshl_b32 s2, s21, 2
	v_cndmask_b32_e64 v32, v141, v32, s[36:37]
	s_add_u32 s0, s0, s2
	v_lshl_or_b32 v64, v32, 7, v150
	s_addc_u32 s1, s1, 0
	ds_read_b128 v[32:35], v64 offset:16
	ds_read_b128 v[80:83], v64
	s_nop 0
	s_mov_b32 s1, 0x22110
	s_cmpk_lt_i32 s26, 0x400
	s_cselect_b32 s1, 0x22010, s1
	s_add_u32 s1, s1, s2
	v_add_u32_e32 v184, s1, v161
	ds_read_b128 v[64:67], v184
	ds_read_b128 v[68:71], v184 offset:64
	s_mov_b32 s0, 0x358637bd
	v_mov_b64_e32 v[76:77], s[0:1]
	s_movk_i32 s0, 0x7ff0
	v_cmp_gt_i32_e32 vcc, s0, v146
	v_mov_b64_e32 v[74:75], s[92:93]
	v_mad_i64_i32 v[84:85], s[0:1], v146, s33, v[74:75]
	v_cndmask_b32_e32 v73, v92, v236, vcc
	v_and_b32_e32 v73, s18, v73
	v_lshrrev_b32_e32 v73, 6, v73
	s_lshl_b32 s0, s20, 8
	v_cndmask_b32_e64 v79, v160, v73, s[36:37]
	v_or_b32_e32 v73, s0, v141
	v_bitop3_b32 v78, s0, v231, v141 bitop3:0x36
	v_lshlrev_b32_e32 v73, 2, v73
	v_lshlrev_b32_e32 v78, 2, v78
	v_add_u32_e32 v73, 0xc000, v73
	v_add_u32_e32 v78, 0xc000, v78
	s_waitcnt lgkmcnt(0)
	ds_read2_b32 v[86:87], v73 offset0:64 offset1:80
	ds_read2_b32 v[88:89], v78 offset0:64 offset1:80
	s_mov_b32 s11, s55
	s_lshl_b64 s[0:1], s[10:11], 1
	s_mov_b32 s10, 0x3c800000
	s_waitcnt lgkmcnt(0)
	v_mov_b32_e32 v90, v87
	v_mov_b32_e32 v91, v86
	v_mov_b32_e32 v86, v89
	v_mov_b32_e32 v87, v88
	v_pk_add_f32 v[86:87], v[90:91], v[86:87]
	v_mov_b32_e32 v139, v177
	v_pk_fma_f32 v[86:87], v[86:87], s[10:11], v[76:77] op_sel_hi:[1,0,0]
	v_lshl_add_u64 v[84:85], v[84:85], 0, s[0:1]
	v_mul_f32_e32 v88, 0x4b800000, v87
	v_cmp_gt_f32_e32 vcc, s91, v87
	v_mov_b32_e32 v137, v177
	v_lshl_add_u64 v[84:85], v[84:85], 0, v[138:139]
	v_cndmask_b32_e32 v87, v87, v88, vcc
	v_rsq_f32_e32 v87, v87
	v_lshl_add_u64 v[84:85], v[84:85], 0, v[136:137]
	v_lshl_or_b32 v79, v79, 7, v150
	s_movk_i32 s2, 0x7fe0
	v_mul_f32_e32 v88, 0x45800000, v87
	v_cndmask_b32_e32 v88, v87, v88, vcc
	v_pk_mul_f32 v[56:57], v[56:57], v[88:89] op_sel_hi:[1,0]
	v_pk_mul_f32 v[60:61], v[60:61], v[88:89] op_sel_hi:[1,0]
	v_pk_mul_f32 v[62:63], v[62:63], v[88:89] op_sel_hi:[1,0]
	v_pk_mul_f32 v[58:59], v[58:59], v[88:89] op_sel_hi:[1,0]
	v_cmp_gt_i32_e32 vcc, s2, v146
	v_pk_mul_f32 v[58:59], v[66:67], v[58:59]
	v_mov_b32_e32 v88, v80
	v_mov_b32_e32 v89, v82
	v_mov_b32_e32 v82, v81
	v_mov_b32_e32 v80, v32
	v_mov_b32_e32 v81, v34
	v_mov_b32_e32 v34, v33
	v_pk_mul_f32 v[32:33], v[64:65], v[56:57]
	v_pk_mul_f32 v[56:57], v[68:69], v[60:61]
	v_pk_mul_f32 v[60:61], v[70:71], v[62:63]
	v_pk_mul_f32 v[62:63], v[82:83], v[56:57]
	v_pk_mul_f32 v[56:57], v[88:89], v[56:57]
	v_pk_mul_f32 v[90:91], v[34:35], v[60:61]
	v_pk_mul_f32 v[60:61], v[80:81], v[60:61]
	v_pk_fma_f32 v[62:63], v[88:89], v[32:33], v[62:63] neg_lo:[0,0,1] neg_hi:[0,0,1]
	v_pk_fma_f32 v[32:33], v[82:83], v[32:33], v[56:57]
	v_pk_fma_f32 v[56:57], v[80:81], v[58:59], v[90:91] neg_lo:[0,0,1] neg_hi:[0,0,1]
	v_pk_fma_f32 v[34:35], v[34:35], v[58:59], v[60:61]
	v_pk_mul_f32 v[58:59], v[72:73], v[62:63] op_sel_hi:[0,1]
	v_pk_mul_f32 v[60:61], v[72:73], v[32:33] op_sel_hi:[0,1]
	v_pk_mul_f32 v[56:57], v[72:73], v[56:57] op_sel_hi:[0,1]
	v_pk_mul_f32 v[62:63], v[72:73], v[34:35] op_sel_hi:[0,1]
	v_cvt_pk_bf16_f32 v32, v58, v59
	v_cvt_pk_bf16_f32 v33, v56, v57
	v_cvt_pk_bf16_f32 v34, v60, v61
	v_cvt_pk_bf16_f32 v35, v62, v63
	s_nop 0
	v_permlane16_swap_b32_e32 v32, v34
	v_permlane16_swap_b32_e32 v33, v35
	global_store_dwordx4 v[84:85], v[32:35], off offset:256
	s_nop 0
	ds_read_b128 v[32:35], v79
	s_nop 0
	ds_read_b128 v[56:59], v79 offset:16
	v_cndmask_b32_e32 v62, v92, v236, vcc
	v_and_b32_e32 v62, s18, v62
	v_lshrrev_b32_e32 v62, 6, v62
	v_cndmask_b32_e64 v62, v159, v62, s[36:37]
	v_lshl_or_b32 v79, v62, 7, v150
	v_mul_f32_e32 v62, 0x4b800000, v86
	v_cmp_gt_f32_e32 vcc, s91, v86
	v_mad_i64_i32 v[60:61], s[2:3], v158, s33, v[74:75]
	s_nop 0
	v_cndmask_b32_e32 v62, v86, v62, vcc
	v_rsq_f32_e32 v62, v62
	v_lshl_add_u64 v[60:61], v[60:61], 0, s[0:1]
	v_lshl_add_u64 v[60:61], v[60:61], 0, v[138:139]
	v_lshl_add_u64 v[60:61], v[60:61], 0, v[136:137]
	v_mul_f32_e32 v63, 0x45800000, v62
	v_cndmask_b32_e32 v62, v62, v63, vcc
	v_pk_mul_f32 v[52:53], v[52:53], v[62:63] op_sel_hi:[1,0]
	v_pk_mul_f32 v[54:55], v[54:55], v[62:63] op_sel_hi:[1,0]
	v_pk_mul_f32 v[48:49], v[48:49], v[62:63] op_sel_hi:[1,0]
	v_pk_mul_f32 v[50:51], v[50:51], v[62:63] op_sel_hi:[1,0]
	v_pk_mul_f32 v[52:53], v[68:69], v[52:53]
	v_pk_mul_f32 v[54:55], v[70:71], v[54:55]
	v_pk_mul_f32 v[48:49], v[64:65], v[48:49]
	v_pk_mul_f32 v[50:51], v[66:67], v[50:51]
	s_movk_i32 s2, 0x7fd0
	v_cmp_gt_i32_e32 vcc, s2, v146
	s_waitcnt lgkmcnt(1)
	v_mov_b32_e32 v62, v32
	v_mov_b32_e32 v63, v34
	v_mov_b32_e32 v34, v33
	s_waitcnt lgkmcnt(0)
	v_mov_b32_e32 v32, v56
	v_mov_b32_e32 v33, v58
	v_mov_b32_e32 v58, v57
	v_pk_mul_f32 v[56:57], v[34:35], v[52:53]
	v_pk_mul_f32 v[52:53], v[62:63], v[52:53]
	v_pk_mul_f32 v[80:81], v[58:59], v[54:55]
	v_pk_mul_f32 v[54:55], v[32:33], v[54:55]
	v_pk_fma_f32 v[56:57], v[62:63], v[48:49], v[56:57] neg_lo:[0,0,1] neg_hi:[0,0,1]
	v_pk_fma_f32 v[34:35], v[34:35], v[48:49], v[52:53]
	v_pk_fma_f32 v[32:33], v[32:33], v[50:51], v[80:81] neg_lo:[0,0,1] neg_hi:[0,0,1]
	v_pk_fma_f32 v[48:49], v[58:59], v[50:51], v[54:55]
	v_pk_mul_f32 v[50:51], v[72:73], v[56:57] op_sel_hi:[0,1]
	v_pk_mul_f32 v[34:35], v[72:73], v[34:35] op_sel_hi:[0,1]
	v_pk_mul_f32 v[52:53], v[72:73], v[32:33] op_sel_hi:[0,1]
	v_pk_mul_f32 v[48:49], v[72:73], v[48:49] op_sel_hi:[0,1]
	v_cvt_pk_bf16_f32 v32, v50, v51
	v_cvt_pk_bf16_f32 v33, v52, v53
	v_cvt_pk_bf16_f32 v34, v34, v35
	v_cvt_pk_bf16_f32 v35, v48, v49
	s_nop 0
	v_permlane16_swap_b32_e32 v32, v34
	v_permlane16_swap_b32_e32 v33, v35
	global_store_dwordx4 v[60:61], v[32:35], off offset:256
	s_nop 0
	ds_read_b128 v[32:35], v79
	s_nop 0
	ds_read_b128 v[48:51], v79 offset:16
	v_cndmask_b32_e32 v54, v92, v236, vcc
	v_and_b32_e32 v56, s18, v54
	ds_read2_b32 v[54:55], v73 offset0:96 offset1:112
	v_lshrrev_b32_e32 v58, 6, v56
	ds_read2_b32 v[56:57], v78 offset0:96 offset1:112
	v_cndmask_b32_e64 v58, v157, v58, s[36:37]
	v_lshl_or_b32 v60, v58, 7, v150
	s_waitcnt lgkmcnt(1)
	v_mov_b32_e32 v58, v55
	v_mov_b32_e32 v59, v54
	s_waitcnt lgkmcnt(0)
	v_mov_b32_e32 v54, v57
	v_mov_b32_e32 v55, v56
	v_pk_add_f32 v[54:55], v[58:59], v[54:55]
	v_mad_i64_i32 v[52:53], s[2:3], v156, s33, v[74:75]
	v_pk_fma_f32 v[54:55], v[54:55], s[10:11], v[76:77] op_sel_hi:[1,0,0]
	v_lshl_add_u64 v[52:53], v[52:53], 0, s[0:1]
	v_mul_f32_e32 v56, 0x4b800000, v55
	v_cmp_gt_f32_e32 vcc, s91, v55
	v_lshl_add_u64 v[52:53], v[52:53], 0, v[138:139]
	v_lshl_add_u64 v[52:53], v[52:53], 0, v[136:137]
	v_cndmask_b32_e32 v55, v55, v56, vcc
	v_rsq_f32_e32 v55, v55
	s_movk_i32 s2, 0x7f80
	v_mul_f32_e32 v56, 0x45800000, v55
	v_cndmask_b32_e32 v56, v55, v56, vcc
	v_pk_mul_f32 v[44:45], v[44:45], v[56:57] op_sel_hi:[1,0]
	v_pk_mul_f32 v[46:47], v[46:47], v[56:57] op_sel_hi:[1,0]
	v_pk_mul_f32 v[40:41], v[40:41], v[56:57] op_sel_hi:[1,0]
	v_pk_mul_f32 v[42:43], v[42:43], v[56:57] op_sel_hi:[1,0]
	v_pk_mul_f32 v[44:45], v[68:69], v[44:45]
	v_pk_mul_f32 v[46:47], v[70:71], v[46:47]
	v_pk_mul_f32 v[40:41], v[64:65], v[40:41]
	v_pk_mul_f32 v[42:43], v[66:67], v[42:43]
	v_cmp_gt_i32_e32 vcc, s2, v146
	s_waitcnt lgkmcnt(1)
	v_mov_b32_e32 v56, v32
	v_mov_b32_e32 v57, v34
	v_mov_b32_e32 v34, v33
	s_waitcnt lgkmcnt(0)
	v_mov_b32_e32 v32, v48
	v_mov_b32_e32 v33, v50
	v_mov_b32_e32 v50, v49
	v_pk_mul_f32 v[48:49], v[34:35], v[44:45]
	v_pk_mul_f32 v[44:45], v[56:57], v[44:45]
	v_pk_mul_f32 v[58:59], v[50:51], v[46:47]
	v_pk_mul_f32 v[46:47], v[32:33], v[46:47]
	v_pk_fma_f32 v[48:49], v[56:57], v[40:41], v[48:49] neg_lo:[0,0,1] neg_hi:[0,0,1]
	v_pk_fma_f32 v[34:35], v[34:35], v[40:41], v[44:45]
	v_pk_fma_f32 v[32:33], v[32:33], v[42:43], v[58:59] neg_lo:[0,0,1] neg_hi:[0,0,1]
	v_pk_fma_f32 v[40:41], v[50:51], v[42:43], v[46:47]
	v_pk_mul_f32 v[42:43], v[72:73], v[48:49] op_sel_hi:[0,1]
	v_pk_mul_f32 v[34:35], v[72:73], v[34:35] op_sel_hi:[0,1]
	v_pk_mul_f32 v[44:45], v[72:73], v[32:33] op_sel_hi:[0,1]
	v_pk_mul_f32 v[40:41], v[72:73], v[40:41] op_sel_hi:[0,1]
	v_cvt_pk_bf16_f32 v32, v42, v43
	v_cvt_pk_bf16_f32 v33, v44, v45
	v_cvt_pk_bf16_f32 v34, v34, v35
	v_cvt_pk_bf16_f32 v35, v40, v41
	s_nop 0
	v_permlane16_swap_b32_e32 v32, v34
	v_permlane16_swap_b32_e32 v33, v35
	global_store_dwordx4 v[52:53], v[32:35], off offset:256
	s_nop 0
	ds_read_b128 v[32:35], v60
	s_nop 0
	ds_read_b128 v[40:43], v60 offset:16
	v_cndmask_b32_e32 v46, v92, v236, vcc
	v_and_b32_e32 v46, v46, v153
	v_lshrrev_b32_e32 v46, 6, v46
	v_cndmask_b32_e64 v46, v141, v46, s[36:37]
	v_lshl_or_b32 v55, v46, 7, v150
	v_mul_f32_e32 v46, 0x4b800000, v54
	v_cmp_gt_f32_e32 vcc, s91, v54
	v_mad_i64_i32 v[44:45], s[2:3], v155, s33, v[74:75]
	s_nop 0
	v_cndmask_b32_e32 v46, v54, v46, vcc
	v_rsq_f32_e32 v46, v46
	v_lshl_add_u64 v[44:45], v[44:45], 0, s[0:1]
	v_lshl_add_u64 v[44:45], v[44:45], 0, v[138:139]
	v_lshl_add_u64 v[44:45], v[44:45], 0, v[136:137]
	v_mul_f32_e32 v47, 0x45800000, v46
	v_cndmask_b32_e32 v46, v46, v47, vcc
	v_pk_mul_f32 v[48:49], v[180:181], v[46:47] op_sel_hi:[1,0]
	v_pk_mul_f32 v[36:37], v[36:37], v[46:47] op_sel_hi:[1,0]
	v_pk_mul_f32 v[50:51], v[182:183], v[46:47] op_sel_hi:[1,0]
	v_pk_mul_f32 v[38:39], v[38:39], v[46:47] op_sel_hi:[1,0]
	v_pk_mul_f32 v[46:47], v[64:65], v[48:49]
	v_pk_mul_f32 v[36:37], v[68:69], v[36:37]
	v_pk_mul_f32 v[48:49], v[66:67], v[50:51]
	v_pk_mul_f32 v[38:39], v[70:71], v[38:39]
	s_movk_i32 s2, 0x7f70
	v_cmp_gt_i32_e32 vcc, s2, v146
	s_waitcnt lgkmcnt(1)
	v_mov_b32_e32 v50, v32
	v_mov_b32_e32 v51, v34
	v_mov_b32_e32 v34, v33
	s_waitcnt lgkmcnt(0)
	v_mov_b32_e32 v32, v40
	v_mov_b32_e32 v33, v42
	v_mov_b32_e32 v42, v41
	v_pk_mul_f32 v[40:41], v[34:35], v[36:37]
	v_pk_mul_f32 v[36:37], v[50:51], v[36:37]
	v_pk_mul_f32 v[52:53], v[42:43], v[38:39]
	v_pk_mul_f32 v[38:39], v[32:33], v[38:39]
	v_pk_fma_f32 v[40:41], v[50:51], v[46:47], v[40:41] neg_lo:[0,0,1] neg_hi:[0,0,1]
	v_pk_fma_f32 v[34:35], v[34:35], v[46:47], v[36:37]
	v_pk_fma_f32 v[32:33], v[32:33], v[48:49], v[52:53] neg_lo:[0,0,1] neg_hi:[0,0,1]
	v_pk_fma_f32 v[36:37], v[42:43], v[48:49], v[38:39]
	v_pk_mul_f32 v[38:39], v[72:73], v[40:41] op_sel_hi:[0,1]
	v_pk_mul_f32 v[34:35], v[72:73], v[34:35] op_sel_hi:[0,1]
	v_pk_mul_f32 v[40:41], v[72:73], v[32:33] op_sel_hi:[0,1]
	v_pk_mul_f32 v[36:37], v[72:73], v[36:37] op_sel_hi:[0,1]
	v_cvt_pk_bf16_f32 v32, v38, v39
	v_cvt_pk_bf16_f32 v33, v40, v41
	v_cvt_pk_bf16_f32 v34, v34, v35
	v_cvt_pk_bf16_f32 v35, v36, v37
	s_nop 0
	v_permlane16_swap_b32_e32 v32, v34
	v_permlane16_swap_b32_e32 v33, v35
	global_store_dwordx4 v[44:45], v[32:35], off offset:256
	s_nop 0
	ds_read_b128 v[32:35], v55
	s_nop 0
	ds_read_b128 v[36:39], v55 offset:16
	v_cndmask_b32_e32 v42, v92, v236, vcc
	v_and_b32_e32 v44, v42, v152
	ds_read2_b32 v[42:43], v73 offset0:192 offset1:208
	v_lshrrev_b32_e32 v46, 6, v44
	ds_read2_b32 v[44:45], v78 offset0:192 offset1:208
	v_cndmask_b32_e64 v46, v154, v46, s[36:37]
	v_lshl_or_b32 v48, v46, 7, v150
	s_waitcnt lgkmcnt(1)
	v_mov_b32_e32 v46, v43
	v_mov_b32_e32 v47, v42
	s_waitcnt lgkmcnt(0)
	v_mov_b32_e32 v42, v45
	v_mov_b32_e32 v43, v44
	v_pk_add_f32 v[42:43], v[46:47], v[42:43]
	v_mad_i64_i32 v[40:41], s[2:3], v153, s33, v[74:75]
	v_pk_fma_f32 v[42:43], v[42:43], s[10:11], v[76:77] op_sel_hi:[1,0,0]
	v_lshl_add_u64 v[40:41], v[40:41], 0, s[0:1]
	v_mul_f32_e32 v44, 0x4b800000, v43
	v_cmp_gt_f32_e32 vcc, s91, v43
	v_lshl_add_u64 v[40:41], v[40:41], 0, v[138:139]
	v_lshl_add_u64 v[40:41], v[40:41], 0, v[136:137]
	v_cndmask_b32_e32 v43, v43, v44, vcc
	v_rsq_f32_e32 v43, v43
	s_movk_i32 s2, 0x7f60
	v_mul_f32_e32 v44, 0x45800000, v43
	v_cndmask_b32_e32 v44, v43, v44, vcc
	v_pk_mul_f32 v[28:29], v[28:29], v[44:45] op_sel_hi:[1,0]
	v_pk_mul_f32 v[30:31], v[30:31], v[44:45] op_sel_hi:[1,0]
	v_pk_mul_f32 v[24:25], v[24:25], v[44:45] op_sel_hi:[1,0]
	v_pk_mul_f32 v[26:27], v[26:27], v[44:45] op_sel_hi:[1,0]
	v_pk_mul_f32 v[28:29], v[68:69], v[28:29]
	v_pk_mul_f32 v[30:31], v[70:71], v[30:31]
	v_pk_mul_f32 v[24:25], v[64:65], v[24:25]
	v_pk_mul_f32 v[26:27], v[66:67], v[26:27]
	v_cmp_gt_i32_e32 vcc, s2, v146
	s_waitcnt lgkmcnt(1)
	v_mov_b32_e32 v44, v32
	v_mov_b32_e32 v45, v34
	v_mov_b32_e32 v34, v33
	s_waitcnt lgkmcnt(0)
	v_mov_b32_e32 v32, v36
	v_mov_b32_e32 v33, v38
	v_mov_b32_e32 v38, v37
	v_pk_mul_f32 v[36:37], v[34:35], v[28:29]
	v_pk_mul_f32 v[28:29], v[44:45], v[28:29]
	v_pk_mul_f32 v[46:47], v[38:39], v[30:31]
	v_pk_mul_f32 v[30:31], v[32:33], v[30:31]
	v_pk_fma_f32 v[36:37], v[44:45], v[24:25], v[36:37] neg_lo:[0,0,1] neg_hi:[0,0,1]
	v_pk_fma_f32 v[24:25], v[34:35], v[24:25], v[28:29]
	v_pk_fma_f32 v[28:29], v[32:33], v[26:27], v[46:47] neg_lo:[0,0,1] neg_hi:[0,0,1]
	v_pk_fma_f32 v[26:27], v[38:39], v[26:27], v[30:31]
	v_pk_mul_f32 v[30:31], v[72:73], v[36:37] op_sel_hi:[0,1]
	v_pk_mul_f32 v[32:33], v[72:73], v[24:25] op_sel_hi:[0,1]
	v_pk_mul_f32 v[28:29], v[72:73], v[28:29] op_sel_hi:[0,1]
	v_pk_mul_f32 v[34:35], v[72:73], v[26:27] op_sel_hi:[0,1]
	v_cvt_pk_bf16_f32 v24, v30, v31
	v_cvt_pk_bf16_f32 v25, v28, v29
	v_cvt_pk_bf16_f32 v26, v32, v33
	v_cvt_pk_bf16_f32 v27, v34, v35
	s_nop 0
	v_permlane16_swap_b32_e32 v24, v26
	v_permlane16_swap_b32_e32 v25, v27
	global_store_dwordx4 v[40:41], v[24:27], off offset:256
	s_nop 0
	ds_read_b128 v[24:27], v48
	s_nop 0
	ds_read_b128 v[28:31], v48 offset:16
	v_cndmask_b32_e32 v34, v92, v236, vcc
	v_and_b32_e32 v34, v34, v151
	v_and_b32_e32 v35, 47, v151
	v_lshrrev_b32_e32 v34, 6, v34
	v_cndmask_b32_e64 v34, v35, v34, s[36:37]
	v_lshl_or_b32 v38, v34, 7, v150
	v_mul_f32_e32 v34, 0x4b800000, v42
	v_cmp_gt_f32_e32 vcc, s91, v42
	v_mad_i64_i32 v[32:33], s[2:3], v152, s33, v[74:75]
	s_nop 0
	v_cndmask_b32_e32 v34, v42, v34, vcc
	v_rsq_f32_e32 v34, v34
	v_lshl_add_u64 v[32:33], v[32:33], 0, s[0:1]
	v_lshl_add_u64 v[32:33], v[32:33], 0, v[138:139]
	v_lshl_add_u64 v[32:33], v[32:33], 0, v[136:137]
	v_mul_f32_e32 v35, 0x45800000, v34
	v_cndmask_b32_e32 v34, v34, v35, vcc
	v_pk_mul_f32 v[20:21], v[20:21], v[34:35] op_sel_hi:[1,0]
	v_pk_mul_f32 v[22:23], v[22:23], v[34:35] op_sel_hi:[1,0]
	v_pk_mul_f32 v[16:17], v[16:17], v[34:35] op_sel_hi:[1,0]
	v_pk_mul_f32 v[18:19], v[18:19], v[34:35] op_sel_hi:[1,0]
	v_pk_mul_f32 v[20:21], v[68:69], v[20:21]
	v_pk_mul_f32 v[22:23], v[70:71], v[22:23]
	v_pk_mul_f32 v[16:17], v[64:65], v[16:17]
	v_pk_mul_f32 v[18:19], v[66:67], v[18:19]
	s_movk_i32 s2, 0x7f50
	v_cmp_gt_i32_e32 vcc, s2, v146
	s_waitcnt lgkmcnt(1)
	v_mov_b32_e32 v34, v24
	v_mov_b32_e32 v35, v26
	v_mov_b32_e32 v26, v25
	s_waitcnt lgkmcnt(0)
	v_mov_b32_e32 v24, v28
	v_mov_b32_e32 v25, v30
	v_mov_b32_e32 v30, v29
	v_pk_mul_f32 v[28:29], v[26:27], v[20:21]
	v_pk_mul_f32 v[20:21], v[34:35], v[20:21]
	v_pk_mul_f32 v[36:37], v[30:31], v[22:23]
	v_pk_mul_f32 v[22:23], v[24:25], v[22:23]
	v_pk_fma_f32 v[28:29], v[34:35], v[16:17], v[28:29] neg_lo:[0,0,1] neg_hi:[0,0,1]
	v_pk_fma_f32 v[16:17], v[26:27], v[16:17], v[20:21]
	v_pk_fma_f32 v[20:21], v[24:25], v[18:19], v[36:37] neg_lo:[0,0,1] neg_hi:[0,0,1]
	v_pk_fma_f32 v[18:19], v[30:31], v[18:19], v[22:23]
	v_pk_mul_f32 v[22:23], v[72:73], v[28:29] op_sel_hi:[0,1]
	v_pk_mul_f32 v[24:25], v[72:73], v[16:17] op_sel_hi:[0,1]
	v_pk_mul_f32 v[20:21], v[72:73], v[20:21] op_sel_hi:[0,1]
	v_pk_mul_f32 v[26:27], v[72:73], v[18:19] op_sel_hi:[0,1]
	v_cvt_pk_bf16_f32 v16, v22, v23
	v_cvt_pk_bf16_f32 v17, v20, v21
	v_cvt_pk_bf16_f32 v18, v24, v25
	v_cvt_pk_bf16_f32 v19, v26, v27
	s_nop 0
	v_permlane16_swap_b32_e32 v16, v18
	v_permlane16_swap_b32_e32 v17, v19
	global_store_dwordx4 v[32:33], v[16:19], off offset:256
	s_nop 0
	ds_read_b128 v[16:19], v38
	s_nop 0
	ds_read_b128 v[20:23], v38 offset:16
	v_cndmask_b32_e32 v26, v92, v236, vcc
	v_and_b32_e32 v28, v26, v149
	ds_read2_b32 v[26:27], v73 offset0:224 offset1:240
	v_lshrrev_b32_e32 v31, 6, v28
	ds_read2_b32 v[28:29], v78 offset0:224 offset1:240
	v_and_b32_e32 v30, 63, v149
	v_cndmask_b32_e64 v30, v30, v31, s[36:37]
	v_lshl_or_b32 v32, v30, 7, v150
	s_waitcnt lgkmcnt(1)
	v_mov_b32_e32 v30, v27
	v_mov_b32_e32 v31, v26
	s_waitcnt lgkmcnt(0)
	v_mov_b32_e32 v26, v29
	v_mov_b32_e32 v27, v28
	v_pk_add_f32 v[26:27], v[30:31], v[26:27]
	v_mad_i64_i32 v[24:25], s[2:3], v151, s33, v[74:75]
	v_pk_fma_f32 v[26:27], v[26:27], s[10:11], v[76:77] op_sel_hi:[1,0,0]
	v_lshl_add_u64 v[24:25], v[24:25], 0, s[0:1]
	v_mul_f32_e32 v28, 0x4b800000, v27
	v_cmp_gt_f32_e32 vcc, s91, v27
	v_lshl_add_u64 v[24:25], v[24:25], 0, v[138:139]
	v_lshl_add_u64 v[24:25], v[24:25], 0, v[136:137]
	v_cndmask_b32_e32 v27, v27, v28, vcc
	v_rsq_f32_e32 v27, v27
	s_nop 0
	v_mul_f32_e32 v28, 0x45800000, v27
	v_cndmask_b32_e32 v28, v27, v28, vcc
	v_pk_mul_f32 v[12:13], v[12:13], v[28:29] op_sel_hi:[1,0]
	v_pk_mul_f32 v[14:15], v[14:15], v[28:29] op_sel_hi:[1,0]
	v_pk_mul_f32 v[8:9], v[8:9], v[28:29] op_sel_hi:[1,0]
	v_pk_mul_f32 v[10:11], v[10:11], v[28:29] op_sel_hi:[1,0]
	v_pk_mul_f32 v[12:13], v[68:69], v[12:13]
	v_pk_mul_f32 v[14:15], v[70:71], v[14:15]
	v_pk_mul_f32 v[8:9], v[64:65], v[8:9]
	v_pk_mul_f32 v[10:11], v[66:67], v[10:11]
	v_cmp_gt_f32_e32 vcc, s91, v26
	s_waitcnt lgkmcnt(1)
	v_mov_b32_e32 v28, v16
	v_mov_b32_e32 v29, v18
	v_mov_b32_e32 v18, v17
	s_waitcnt lgkmcnt(0)
	v_mov_b32_e32 v16, v20
	v_mov_b32_e32 v17, v22
	v_mov_b32_e32 v22, v21
	v_pk_mul_f32 v[20:21], v[18:19], v[12:13]
	v_pk_mul_f32 v[12:13], v[28:29], v[12:13]
	v_pk_mul_f32 v[30:31], v[22:23], v[14:15]
	v_pk_mul_f32 v[14:15], v[16:17], v[14:15]
	v_pk_fma_f32 v[20:21], v[28:29], v[8:9], v[20:21] neg_lo:[0,0,1] neg_hi:[0,0,1]
	v_pk_fma_f32 v[8:9], v[18:19], v[8:9], v[12:13]
	v_pk_fma_f32 v[12:13], v[16:17], v[10:11], v[30:31] neg_lo:[0,0,1] neg_hi:[0,0,1]
	v_pk_fma_f32 v[10:11], v[22:23], v[10:11], v[14:15]
	v_pk_mul_f32 v[14:15], v[72:73], v[20:21] op_sel_hi:[0,1]
	v_pk_mul_f32 v[16:17], v[72:73], v[8:9] op_sel_hi:[0,1]
	v_pk_mul_f32 v[12:13], v[72:73], v[12:13] op_sel_hi:[0,1]
	v_pk_mul_f32 v[18:19], v[72:73], v[10:11] op_sel_hi:[0,1]
	v_cvt_pk_bf16_f32 v8, v14, v15
	v_cvt_pk_bf16_f32 v9, v12, v13
	v_cvt_pk_bf16_f32 v10, v16, v17
	v_cvt_pk_bf16_f32 v11, v18, v19
	s_nop 0
	v_permlane16_swap_b32_e32 v8, v10
	v_permlane16_swap_b32_e32 v9, v11
	global_store_dwordx4 v[24:25], v[8:11], off offset:256
	s_nop 0
	ds_read_b128 v[8:11], v32
	s_nop 0
	ds_read_b128 v[12:15], v32 offset:16
	v_mul_f32_e32 v16, 0x4b800000, v26
	v_cndmask_b32_e32 v16, v26, v16, vcc
	v_rsq_f32_e32 v18, v16
	v_mad_i64_i32 v[16:17], s[2:3], v149, s33, v[74:75]
	v_lshl_add_u64 v[16:17], v[16:17], 0, s[0:1]
	v_mul_f32_e32 v19, 0x45800000, v18
	v_cndmask_b32_e32 v18, v18, v19, vcc
	v_pk_mul_f32 v[4:5], v[4:5], v[18:19] op_sel_hi:[1,0]
	v_pk_mul_f32 v[6:7], v[6:7], v[18:19] op_sel_hi:[1,0]
	v_pk_mul_f32 v[0:1], v[0:1], v[18:19] op_sel_hi:[1,0]
	v_pk_mul_f32 v[2:3], v[2:3], v[18:19] op_sel_hi:[1,0]
	v_pk_mul_f32 v[4:5], v[68:69], v[4:5]
	v_pk_mul_f32 v[6:7], v[70:71], v[6:7]
	v_pk_mul_f32 v[0:1], v[64:65], v[0:1]
	v_pk_mul_f32 v[2:3], v[66:67], v[2:3]
	v_lshl_add_u64 v[16:17], v[16:17], 0, v[138:139]
	s_waitcnt lgkmcnt(1)
	v_mov_b32_e32 v18, v8
	v_mov_b32_e32 v19, v10
	v_mov_b32_e32 v10, v9
	s_waitcnt lgkmcnt(0)
	v_mov_b32_e32 v8, v12
	v_mov_b32_e32 v9, v14
	v_mov_b32_e32 v14, v13
	v_pk_mul_f32 v[12:13], v[10:11], v[4:5]
	v_pk_mul_f32 v[4:5], v[18:19], v[4:5]
	v_pk_mul_f32 v[20:21], v[14:15], v[6:7]
	v_pk_mul_f32 v[6:7], v[8:9], v[6:7]
	v_pk_fma_f32 v[12:13], v[18:19], v[0:1], v[12:13] neg_lo:[0,0,1] neg_hi:[0,0,1]
	v_pk_fma_f32 v[0:1], v[10:11], v[0:1], v[4:5]
	v_pk_fma_f32 v[4:5], v[8:9], v[2:3], v[20:21] neg_lo:[0,0,1] neg_hi:[0,0,1]
	v_pk_fma_f32 v[2:3], v[14:15], v[2:3], v[6:7]
	v_pk_mul_f32 v[6:7], v[72:73], v[12:13] op_sel_hi:[0,1]
	v_pk_mul_f32 v[8:9], v[72:73], v[0:1] op_sel_hi:[0,1]
	v_pk_mul_f32 v[4:5], v[72:73], v[4:5] op_sel_hi:[0,1]
	v_pk_mul_f32 v[10:11], v[72:73], v[2:3] op_sel_hi:[0,1]
	v_cvt_pk_bf16_f32 v0, v6, v7
	v_cvt_pk_bf16_f32 v1, v4, v5
	v_cvt_pk_bf16_f32 v2, v8, v9
	v_cvt_pk_bf16_f32 v3, v10, v11
	s_nop 0
	v_permlane16_swap_b32_e32 v0, v2
	v_permlane16_swap_b32_e32 v1, v3
	v_lshl_add_u64 v[4:5], v[16:17], 0, v[136:137]
	global_store_dwordx4 v[4:5], v[0:3], off offset:256
	s_branch .LBB0_74

.LBB0_885:
	s_ashr_i32 s28, s12, 2
	s_ashr_i32 s29, s28, 31
	s_lshl_b64 s[28:29], s[28:29], 8
	s_add_u32 s28, s28, s6
	s_addc_u32 s29, s29, s7
	s_mul_i32 s9, s29, 0x1200
	s_mul_hi_u32 s15, s28, 0x1200
	s_add_i32 s15, s15, s9
	s_mul_i32 s9, s28, 0x1200
	s_add_u32 s9, s92, s9
	s_mulk_i32 s7, 0x1200
	s_mul_hi_u32 s27, s6, 0x1200
	s_addc_u32 s15, s93, s15
	s_add_i32 s27, s27, s7
	s_mulk_i32 s6, 0x1200
	s_add_u32 s6, s92, s6
	s_addc_u32 s7, s93, s27
	s_lshl_b32 s27, s13, 7
	s_add_u32 s40, s6, s27
	s_addc_u32 s41, s7, 0
	s_lshl_b64 s[38:39], s[2:3], 1
	s_add_u32 s42, s47, s38
	s_addc_u32 s43, s52, s39
	s_lshl_b64 s[2:3], s[28:29], 11
	s_add_u32 s2, s94, s2
	s_addc_u32 s3, s95, s3
	s_lshl_b32 s7, s12, 7
	s_lshl_b32 s6, s13, 9
	s_and_b32 s7, s7, 0x180
	s_or_b32 s12, s6, s7
	s_add_u32 s6, s2, s12
	s_addc_u32 s7, s3, 0
	s_add_u32 s12, s9, s12
	s_addc_u32 s13, s15, 0
	s_ashr_i32 s2, s14, 2
	s_ashr_i32 s3, s2, 31
	s_lshl_b64 s[2:3], s[2:3], 8
	s_add_u32 s2, s2, s18
	s_addc_u32 s3, s3, s19
	s_mulk_i32 s3, 0x1200
	s_mul_hi_u32 s9, s2, 0x1200
	s_add_i32 s9, s9, s3
	s_mulk_i32 s2, 0x1200
	s_add_u32 s2, s92, s2
	s_addc_u32 s3, s93, s9
	s_lshl_b32 s14, s14, 7
	s_lshl_b32 s9, s26, 9
	s_and_b32 s14, s14, 0x180
	s_or_b32 s9, s9, s14
	s_add_u32 s14, s2, s9
	s_addc_u32 s15, s3, 0
	s_mul_i32 s2, s19, 0x1200
	s_mul_hi_u32 s3, s18, 0x1200
	s_add_i32 s3, s3, s2
	s_mul_i32 s2, s18, 0x1200
	s_add_u32 s2, s92, s2
	s_addc_u32 s3, s93, s3
	s_lshl_b32 s9, s26, 7
	s_add_u32 s34, s2, s9
	s_addc_u32 s35, s3, 0
	s_lshl_b64 s[2:3], s[10:11], 1
	s_add_u32 s10, s47, s2
	s_addc_u32 s11, s52, s3
	s_and_saveexec_b64 s[2:3], s[36:37]
	s_xor_b64 s[44:45], exec, s[2:3]
	s_cbranch_execz .LBB0_896
	v_mov_b32_e32 v151, v250
	s_waitcnt lgkmcnt(0)
	s_barrier
	s_nop 0
	v_lshlrev_b32_e32 v2, 4, v151
	v_lshlrev_b32_e32 v3, 1, v151
	v_lshrrev_b32_e32 v152, 1, v151
	v_lshlrev_b32_e32 v0, 3, v151
	v_xor_b32_e32 v4, v2, v151
	v_and_b32_e32 v2, 19, v151
	v_and_b32_e32 v3, 8, v3
	v_and_b32_e32 v5, 4, v152
	v_ashrrev_i32_e32 v136, 3, v151
	v_and_b32_e32 v138, 56, v0
	v_or3_b32 v5, v3, v2, v5
	v_mov_b64_e32 v[2:3], s[40:41]
	v_mad_i64_i32 v[0:1], s[2:3], v136, s21, 0
	v_lshlrev_b32_e32 v176, 1, v138
	v_mad_i64_i32 v[2:3], s[2:3], v136, s33, v[2:3]
	v_lshl_add_u64 v[140:141], v[2:3], 0, v[176:177]
	v_lshlrev_b32_e32 v2, 7, v136
	s_movk_i32 s2, 0x70
	v_and_or_b32 v153, v4, s2, v2
	s_mov_b32 s2, 0xd8000
	v_add_co_u32_e32 v2, vcc, s2, v140
	v_lshl_add_u64 v[0:1], v[0:1], 1, s[42:43]
	s_waitcnt vmcnt(4)
	ds_write_b128 v153, v[64:67] offset:16384
	ds_write_b128 v153, v[68:71] offset:24576
	ds_write_b128 v153, v[72:75]
	ds_write_b128 v153, v[76:79] offset:8192
	v_addc_co_u32_e32 v3, vcc, 0, v141, vcc
	v_lshl_add_u64 v[0:1], v[0:1], 0, v[176:177]
	global_load_dwordx4 v[112:115], v[2:3], off offset:2048
	global_load_dwordx4 v[116:119], v[0:1], off offset:128
	v_lshrrev_b32_e32 v40, 1, v5
	v_bfe_u32 v147, v151, 5, 1
	v_bitop3_b32 v0, v40, v147, 7 bitop3:0x6c
	v_lshlrev_b32_e32 v154, 7, v5
	v_lshlrev_b32_e32 v155, 4, v0
	s_waitcnt lgkmcnt(0)
	s_barrier
	v_or_b32_e32 v41, v154, v155
	ds_read_b128 v[0:3], v41 offset:16384
	ds_read_b128 v[4:7], v41 offset:20480
	s_waitcnt lgkmcnt(0)
	v_mfma_f32_32x32x16_bf16 v[16:31], v[0:3], v[96:99], 0
	v_or_b32_e32 v32, 2, v147
	v_bitop3_b32 v32, v40, v32, 7 bitop3:0x6c
	v_lshlrev_b32_e32 v156, 4, v32
	v_or_b32_e32 v42, v154, v156
	ds_read_b128 v[32:35], v42 offset:16384
	ds_read_b128 v[36:39], v42 offset:20480
	s_lshr_b32 s3, s21, 6
	s_mov_b32 s2, 5
	v_mfma_f32_32x32x16_bf16 v[0:15], v[4:7], v[96:99], 0
	v_and_b32_e32 v157, 31, v151
	v_mad_i64_i32 v[142:143], s[18:19], v136, s33, 0
	s_add_i32 s3, s3, -1
	v_lshrrev_b32_e32 v69, 5, v151
	v_bfe_u32 v70, v151, 1, 3
	v_lshlrev_b32_e32 v71, 7, v157
	s_waitcnt lgkmcnt(1)
	v_mfma_f32_32x32x16_bf16 v[16:31], v[32:35], v[100:103], v[16:31]
	v_or_b32_e32 v32, 4, v147
	v_bitop3_b32 v32, v40, v32, 7 bitop3:0x6c
	v_lshlrev_b32_e32 v158, 4, v32
	v_or_b32_e32 v52, v154, v158
	s_waitcnt lgkmcnt(0)
	v_mfma_f32_32x32x16_bf16 v[0:15], v[36:39], v[100:103], v[0:15]
	ds_read_b128 v[32:35], v52 offset:16384
	ds_read_b128 v[36:39], v52 offset:20480
	s_waitcnt lgkmcnt(1)
	v_mfma_f32_32x32x16_bf16 v[16:31], v[32:35], v[104:107], v[16:31]
	v_or_b32_e32 v32, 6, v147
	v_bitop3_b32 v32, v40, v32, 7 bitop3:0x6c
	v_lshlrev_b32_e32 v159, 4, v32
	v_or_b32_e32 v68, v154, v159
	ds_read_b128 v[32:35], v68 offset:16384
	s_waitcnt lgkmcnt(1)
	v_mfma_f32_32x32x16_bf16 v[0:15], v[36:39], v[104:107], v[0:15]
	ds_read_b128 v[36:39], v68 offset:20480
	s_waitcnt lgkmcnt(1)
	v_mfma_f32_32x32x16_bf16 v[16:31], v[32:35], v[108:111], v[16:31]
	s_waitcnt lgkmcnt(0)
	v_mfma_f32_32x32x16_bf16 v[0:15], v[36:39], v[108:111], v[0:15]
	s_nop 9
	v_max_f32_e32 v32, v17, v17
	v_max_f32_e32 v33, v16, v16
	v_max_f32_e32 v32, v33, v32
	v_max3_f32 v32, v32, v18, v19
	v_max3_f32 v32, v32, v20, v21
	v_max3_f32 v32, v32, v22, v23
	v_max3_f32 v32, v32, v24, v25
	v_max3_f32 v32, v32, v26, v27
	v_max3_f32 v32, v32, v28, v29
	v_max3_f32 v32, v32, v30, v31
	v_max3_f32 v32, v32, v0, v1
	v_max3_f32 v32, v32, v2, v3
	v_max3_f32 v32, v32, v4, v5
	v_max3_f32 v32, v32, v6, v7
	v_max3_f32 v32, v32, v8, v9
	v_max3_f32 v32, v32, v10, v11
	v_max3_f32 v32, v32, v12, v13
	v_max3_f32 v32, v32, v14, v15
	v_mov_b32_e32 v33, v32
	s_nop 1
	v_permlane32_swap_b32_e32 v32, v33
	v_max_f32_e32 v33, v33, v33
	v_max_f32_e32 v32, v32, v32
	v_max_f32_e32 v32, v32, v33
	s_mov_b32 s9, 0xf149f2ca
	v_cmp_lt_f32_e32 vcc, s9, v32
	v_mov_b32_e32 v33, 0xf149f2ca
	s_nop 0
	v_cndmask_b32_e32 v160, v33, v32, vcc
	v_sub_f32_e32 v72, 0xf149f2ca, v160
	v_sub_f32_e32 v16, v16, v160
	v_exp_f32_e32 v73, v16
	v_sub_f32_e32 v16, v17, v160
	v_exp_f32_e32 v74, v16
	v_sub_f32_e32 v16, v18, v160
	v_exp_f32_e32 v75, v16
	v_sub_f32_e32 v16, v19, v160
	ds_read_b128 v[32:35], v41 offset:24576
	ds_read_b128 v[48:51], v41 offset:28672
	v_exp_f32_e32 v76, v16
	v_add_f32_e32 v16, 0, v73
	v_add_f32_e32 v16, v74, v16
	v_add_f32_e32 v16, v75, v16
	v_add_f32_e32 v36, v76, v16
	v_sub_f32_e32 v20, v20, v160
	v_exp_f32_e32 v77, v20
	v_sub_f32_e32 v20, v21, v160
	v_exp_f32_e32 v78, v20
	v_sub_f32_e32 v20, v22, v160
	v_exp_f32_e32 v79, v20
	v_sub_f32_e32 v20, v23, v160
	ds_read_b128 v[16:19], v42 offset:24576
	ds_read_b128 v[64:67], v42 offset:28672
	v_exp_f32_e32 v80, v20
	v_add_f32_e32 v20, v77, v36
	v_add_f32_e32 v20, v78, v20
	v_add_f32_e32 v20, v79, v20
	v_add_f32_e32 v20, v80, v20
	v_sub_f32_e32 v21, v24, v160
	v_exp_f32_e32 v81, v21
	v_sub_f32_e32 v21, v25, v160
	v_exp_f32_e32 v82, v21
	v_sub_f32_e32 v21, v26, v160
	v_exp_f32_e32 v83, v21
	v_sub_f32_e32 v21, v27, v160
	v_exp_f32_e32 v84, v21
	v_add_f32_e32 v20, v81, v20
	v_add_f32_e32 v20, v82, v20
	v_add_f32_e32 v20, v83, v20
	v_add_f32_e32 v20, v84, v20
	v_sub_f32_e32 v21, v28, v160
	v_exp_f32_e32 v85, v21
	v_sub_f32_e32 v21, v29, v160
	v_exp_f32_e32 v86, v21
	v_sub_f32_e32 v21, v30, v160
	v_exp_f32_e32 v87, v21
	v_sub_f32_e32 v21, v31, v160
	v_exp_f32_e32 v88, v21
	v_add_f32_e32 v20, v85, v20
	v_add_f32_e32 v20, v86, v20
	v_add_f32_e32 v20, v87, v20
	v_add_f32_e32 v28, v88, v20
	s_waitcnt lgkmcnt(3)
	v_mfma_f32_32x32x16_bf16 v[32:47], v[32:35], v[96:99], 0
	v_sub_f32_e32 v0, v0, v160
	v_exp_f32_e32 v89, v0
	v_sub_f32_e32 v1, v1, v160
	v_exp_f32_e32 v90, v1
	v_sub_f32_e32 v1, v2, v160
	ds_read_b128 v[20:23], v52 offset:24576
	ds_read_b128 v[24:27], v52 offset:28672
	v_exp_f32_e32 v91, v1
	v_sub_f32_e32 v1, v3, v160
	v_exp_f32_e32 v92, v1
	v_add_f32_e32 v0, v89, v28
	v_add_f32_e32 v0, v90, v0
	v_add_f32_e32 v0, v91, v0
	v_add_f32_e32 v93, v92, v0
	s_waitcnt lgkmcnt(4)
	v_mfma_f32_32x32x16_bf16 v[48:63], v[48:51], v[96:99], 0
	v_sub_f32_e32 v4, v4, v160
	v_exp_f32_e32 v4, v4
	v_sub_f32_e32 v5, v5, v160
	v_exp_f32_e32 v5, v5
	v_sub_f32_e32 v6, v6, v160
	ds_read_b128 v[0:3], v68 offset:24576
	ds_read_b128 v[28:31], v68 offset:28672
	v_exp_f32_e32 v6, v6
	v_sub_f32_e32 v7, v7, v160
	v_exp_f32_e32 v7, v7
	v_add_f32_e32 v68, v4, v93
	v_add_f32_e32 v68, v5, v68
	v_add_f32_e32 v68, v6, v68
	v_add_f32_e32 v68, v7, v68
	v_sub_f32_e32 v8, v8, v160
	s_waitcnt lgkmcnt(5)
	v_mfma_f32_32x32x16_bf16 v[32:47], v[16:19], v[100:103], v[32:47]
	v_exp_f32_e32 v8, v8
	v_sub_f32_e32 v9, v9, v160
	v_exp_f32_e32 v9, v9
	v_sub_f32_e32 v10, v10, v160
	v_exp_f32_e32 v10, v10
	v_sub_f32_e32 v11, v11, v160
	v_exp_f32_e32 v11, v11
	v_add_f32_e32 v16, v8, v68
	v_add_f32_e32 v16, v9, v16
	v_add_f32_e32 v16, v10, v16
	v_add_f32_e32 v16, v11, v16
	v_sub_f32_e32 v12, v12, v160
	v_exp_f32_e32 v12, v12
	v_sub_f32_e32 v13, v13, v160
	v_exp_f32_e32 v13, v13
	v_sub_f32_e32 v14, v14, v160
	v_exp_f32_e32 v14, v14
	v_sub_f32_e32 v15, v15, v160
	s_waitcnt lgkmcnt(4)
	v_mfma_f32_32x32x16_bf16 v[48:63], v[64:67], v[100:103], v[48:63]
	v_exp_f32_e32 v15, v15
	v_add_f32_e32 v16, v12, v16
	v_add_f32_e32 v16, v13, v16
	v_add_f32_e32 v16, v14, v16
	v_add_f32_e32 v137, v15, v16
	v_exp_f32_e32 v16, v72
	s_waitcnt lgkmcnt(3)
	v_mfma_f32_32x32x16_bf16 v[32:47], v[20:23], v[104:107], v[32:47]
	v_cvt_pk_bf16_f32 v132, v73, v74
	v_cvt_pk_bf16_f32 v133, v75, v76
	v_cvt_pk_bf16_f32 v134, v77, v78
	v_cvt_pk_bf16_f32 v135, v79, v80
	s_waitcnt lgkmcnt(2)
	v_mfma_f32_32x32x16_bf16 v[48:63], v[24:27], v[104:107], v[48:63]
	v_cvt_pk_bf16_f32 v128, v81, v82
	v_cvt_pk_bf16_f32 v129, v83, v84
	v_cvt_pk_bf16_f32 v130, v85, v86
	v_cvt_pk_bf16_f32 v131, v87, v88
	s_waitcnt lgkmcnt(1)
	v_mfma_f32_32x32x16_bf16 v[32:47], v[0:3], v[108:111], v[32:47]
	v_cvt_pk_bf16_f32 v124, v89, v90
	v_cvt_pk_bf16_f32 v125, v91, v92
	v_cvt_pk_bf16_f32 v126, v4, v5
	v_cvt_pk_bf16_f32 v127, v6, v7
	s_waitcnt lgkmcnt(0)
	v_mfma_f32_32x32x16_bf16 v[48:63], v[28:31], v[108:111], v[48:63]
	v_cvt_pk_bf16_f32 v120, v8, v9
	v_cvt_pk_bf16_f32 v121, v10, v11
	v_cvt_pk_bf16_f32 v122, v12, v13
	v_cvt_pk_bf16_f32 v123, v14, v15
	v_mul_f32_e32 v0, 0, v16
	v_fmac_f32_e32 v137, 0, v16
	s_cmp_lg_u64 vcc, 0
	s_cselect_b64 vcc, -1, 0
	v_cndmask_b32_e32 v16, 0, v0, vcc
	v_bitop3_b32 v0, v69, v70, 1 bitop3:0x6c
	v_lshlrev_b32_e32 v2, 4, v0
	v_bitop3_b32 v0, v147, v70, 2 bitop3:0x36
	v_lshlrev_b32_e32 v3, 4, v0
	v_bitop3_b32 v0, v147, v70, 4 bitop3:0x36
	v_lshlrev_b32_e32 v4, 4, v0
	v_bitop3_b32 v0, v147, v70, 6 bitop3:0x36
	v_lshlrev_b32_e32 v5, 4, v0
	v_and_b32_e32 v0, 7, v151
	v_lshlrev_b32_e32 v176, 4, v0
	v_lshlrev_b32_e32 v0, 1, v136
	v_mad_i64_i32 v[0:1], s[18:19], v0, s21, v[176:177]
	v_readlane_b32 s9, v254, 52
	s_add_u32 s18, s9, s38
	v_readlane_b32 s9, v254, 53
	v_mov_b32_e32 v17, v16
	s_waitcnt lgkmcnt(0)
	s_barrier
	s_addc_u32 s19, s9, s39
	v_mov_b32_e32 v18, v16
	v_mov_b32_e32 v19, v16
	v_mov_b32_e32 v20, v16
	v_mov_b32_e32 v21, v16
	v_mov_b32_e32 v22, v16
	v_mov_b32_e32 v23, v16
	v_mov_b32_e32 v24, v16
	v_mov_b32_e32 v25, v16
	v_mov_b32_e32 v26, v16
	v_mov_b32_e32 v27, v16
	v_mov_b32_e32 v28, v16
	v_mov_b32_e32 v29, v16
	v_mov_b32_e32 v30, v16
	v_mov_b32_e32 v31, v16
	v_lshl_add_u64 v[144:145], s[18:19], 0, v[0:1]
	v_add_u32_e32 v150, v71, v2
	v_add_u32_e32 v149, v71, v3
	v_add_u32_e32 v148, v71, v4
	v_add_u32_e32 v139, v71, v5
	v_mov_b64_e32 v[0:1], v[16:17]
	v_mov_b64_e32 v[2:3], v[18:19]
	v_mov_b64_e32 v[4:5], v[20:21]
	v_mov_b64_e32 v[6:7], v[22:23]
	v_mov_b64_e32 v[8:9], v[24:25]
	v_mov_b64_e32 v[10:11], v[26:27]
	v_mov_b64_e32 v[12:13], v[28:29]
	v_mov_b64_e32 v[14:15], v[30:31]

.LBB0_896:
	s_andn2_saveexec_b64 s[44:45], s[44:45]
	s_cbranch_execz .LBB0_876
	v_mov_b32_e32 v129, v250
	s_waitcnt lgkmcnt(0)
	s_barrier
	v_readlane_b32 s9, v254, 52
	v_lshlrev_b32_e32 v2, 4, v129
	v_lshlrev_b32_e32 v3, 1, v129
	v_lshrrev_b32_e32 v131, 1, v129
	v_lshlrev_b32_e32 v0, 3, v129
	v_xor_b32_e32 v4, v2, v129
	v_and_b32_e32 v2, 19, v129
	v_and_b32_e32 v3, 8, v3
	v_and_b32_e32 v5, 4, v131
	v_ashrrev_i32_e32 v128, 3, v129
	v_and_b32_e32 v130, 56, v0
	v_or3_b32 v5, v3, v2, v5
	v_mov_b64_e32 v[2:3], s[40:41]
	v_mad_i64_i32 v[0:1], s[2:3], v128, s21, 0
	v_lshlrev_b32_e32 v176, 1, v130
	v_mad_i64_i32 v[2:3], s[2:3], v128, s33, v[2:3]
	v_lshl_add_u64 v[132:133], v[2:3], 0, v[176:177]
	v_lshlrev_b32_e32 v2, 7, v128
	s_movk_i32 s2, 0x70
	v_and_or_b32 v142, v4, s2, v2
	s_mov_b32 s2, 0xd8000
	v_lshl_add_u64 v[0:1], v[0:1], 1, s[42:43]
	v_add_co_u32_e32 v2, vcc, s2, v132
	v_lshl_add_u64 v[0:1], v[0:1], 0, v[176:177]
	v_lshrrev_b32_e32 v40, 1, v5
	v_bfe_u32 v138, v129, 5, 1
	s_waitcnt vmcnt(4)
	ds_write_b128 v142, v[64:67] offset:16384
	ds_write_b128 v142, v[68:71] offset:24576
	ds_write_b128 v142, v[72:75]
	ds_write_b128 v142, v[76:79] offset:8192
	v_addc_co_u32_e32 v3, vcc, 0, v133, vcc
	global_load_dwordx4 v[112:115], v[2:3], off offset:2048
	global_load_dwordx4 v[116:119], v[0:1], off offset:128
	v_bitop3_b32 v0, v40, v138, 7 bitop3:0x6c
	v_lshlrev_b32_e32 v143, 7, v5
	v_lshlrev_b32_e32 v145, 4, v0
	s_waitcnt lgkmcnt(0)
	s_barrier
	v_or_b32_e32 v41, v143, v145
	ds_read_b128 v[0:3], v41 offset:16384
	ds_read_b128 v[4:7], v41 offset:20480
	s_waitcnt lgkmcnt(0)
	v_mfma_f32_32x32x16_bf16 v[16:31], v[0:3], v[96:99], 0
	v_or_b32_e32 v32, 2, v138
	v_bitop3_b32 v32, v40, v32, 7 bitop3:0x6c
	v_lshlrev_b32_e32 v146, 4, v32
	v_or_b32_e32 v42, v143, v146
	ds_read_b128 v[32:35], v42 offset:16384
	ds_read_b128 v[36:39], v42 offset:20480
	v_lshrrev_b32_e32 v73, 5, v129
	v_bfe_u32 v74, v129, 1, 3
	v_mfma_f32_32x32x16_bf16 v[0:15], v[4:7], v[96:99], 0
	s_lshr_b32 s2, s21, 6
	v_mad_i64_i32 v[134:135], s[18:19], v128, s33, 0
	s_add_i32 s2, s2, -1
	v_and_b32_e32 v148, 31, v129
	v_lshlrev_b32_e32 v75, 7, v148
	s_mov_b32 s3, 5
	s_waitcnt lgkmcnt(1)
	v_mfma_f32_32x32x16_bf16 v[16:31], v[32:35], v[100:103], v[16:31]
	v_or_b32_e32 v32, 4, v138
	v_bitop3_b32 v32, v40, v32, 7 bitop3:0x6c
	v_lshlrev_b32_e32 v147, 4, v32
	v_or_b32_e32 v43, v143, v147
	s_waitcnt lgkmcnt(0)
	v_mfma_f32_32x32x16_bf16 v[0:15], v[36:39], v[100:103], v[0:15]
	ds_read_b128 v[32:35], v43 offset:16384
	ds_read_b128 v[36:39], v43 offset:20480
	s_waitcnt lgkmcnt(1)
	v_mfma_f32_32x32x16_bf16 v[16:31], v[32:35], v[104:107], v[16:31]
	v_or_b32_e32 v32, 6, v138
	v_bitop3_b32 v32, v40, v32, 7 bitop3:0x6c
	v_lshlrev_b32_e32 v149, 4, v32
	v_or_b32_e32 v72, v143, v149
	ds_read_b128 v[32:35], v72 offset:16384
	s_waitcnt lgkmcnt(1)
	v_mfma_f32_32x32x16_bf16 v[0:15], v[36:39], v[104:107], v[0:15]
	ds_read_b128 v[36:39], v72 offset:20480
	s_waitcnt lgkmcnt(1)
	v_mfma_f32_32x32x16_bf16 v[16:31], v[32:35], v[108:111], v[16:31]
	s_waitcnt lgkmcnt(0)
	v_mfma_f32_32x32x16_bf16 v[0:15], v[36:39], v[108:111], v[0:15]
	s_nop 9
	v_exp_f32_e32 v32, v16
	v_exp_f32_e32 v33, v17
	v_exp_f32_e32 v34, v18
	v_exp_f32_e32 v35, v19
	v_exp_f32_e32 v37, v20
	v_exp_f32_e32 v38, v21
	v_add_f32_e32 v16, 0, v32
	v_add_f32_e32 v17, 0, v33
	v_add_f32_e32 v36, 0, v34
	v_add_f32_e32 v39, 0, v35
	v_add_f32_e32 v40, v37, v16
	v_add_f32_e32 v44, v38, v17
	v_exp_f32_e32 v45, v22
	v_exp_f32_e32 v46, v23
	ds_read_b128 v[16:19], v41 offset:24576
	ds_read_b128 v[20:23], v41 offset:28672
	s_waitcnt lgkmcnt(1)
	v_mfma_f32_32x32x16_bf16 v[48:63], v[16:19], v[96:99], 0
	v_exp_f32_e32 v41, v24
	v_add_f32_e32 v36, v45, v36
	v_add_f32_e32 v39, v46, v39
	ds_read_b128 v[64:67], v42 offset:24576
	ds_read_b128 v[68:71], v42 offset:28672
	v_exp_f32_e32 v42, v25
	v_add_f32_e32 v24, v41, v40
	v_exp_f32_e32 v40, v26
	v_exp_f32_e32 v47, v27
	v_exp_f32_e32 v28, v28
	v_exp_f32_e32 v29, v29
	v_exp_f32_e32 v30, v30
	v_exp_f32_e32 v31, v31
	v_exp_f32_e32 v77, v0
	v_exp_f32_e32 v78, v1
	v_add_f32_e32 v25, v42, v44
	s_waitcnt lgkmcnt(1)
	v_mfma_f32_32x32x16_bf16 v[48:63], v[64:67], v[100:103], v[48:63]
	v_add_f32_e32 v26, v40, v36
	v_add_f32_e32 v27, v47, v39
	v_cvt_pk_bf16_f32 v80, v32, v33
	v_cvt_pk_bf16_f32 v81, v34, v35
	v_cvt_pk_bf16_f32 v82, v37, v38
	v_cvt_pk_bf16_f32 v83, v45, v46
	v_add_f32_e32 v24, v28, v24
	v_add_f32_e32 v25, v29, v25
	v_exp_f32_e32 v4, v4
	v_add_f32_e32 v76, v30, v26
	v_add_f32_e32 v0, v31, v27
	v_add_f32_e32 v79, v77, v24
	v_add_f32_e32 v88, v78, v25
	ds_read_b128 v[16:19], v43 offset:24576
	ds_read_b128 v[24:27], v43 offset:28672
	v_cvt_pk_bf16_f32 v86, v28, v29
	v_exp_f32_e32 v28, v2
	v_exp_f32_e32 v29, v3
	v_exp_f32_e32 v5, v5
	s_waitcnt lgkmcnt(1)
	v_mfma_f32_32x32x16_bf16 v[48:63], v[16:19], v[104:107], v[48:63]
	v_cvt_pk_bf16_f32 v84, v41, v42
	v_cvt_pk_bf16_f32 v85, v40, v47
	v_exp_f32_e32 v6, v6
	v_exp_f32_e32 v7, v7
	v_cvt_pk_bf16_f32 v87, v30, v31
	v_add_f32_e32 v30, v28, v76
	v_add_f32_e32 v31, v29, v0
	v_mfma_f32_32x32x16_bf16 v[32:47], v[20:23], v[96:99], 0
	ds_read_b128 v[0:3], v72 offset:24576
	ds_read_b128 v[20:23], v72 offset:28672
	v_add_f32_e32 v64, v4, v79
	v_add_f32_e32 v65, v5, v88
	v_add_f32_e32 v30, v6, v30
	v_exp_f32_e32 v8, v8
	v_exp_f32_e32 v9, v9
	v_add_f32_e32 v31, v7, v31
	v_cvt_pk_bf16_f32 v90, v4, v5
	v_exp_f32_e32 v4, v10
	v_exp_f32_e32 v5, v11
	v_exp_f32_e32 v11, v13
	v_cvt_pk_bf16_f32 v91, v6, v7
	v_exp_f32_e32 v7, v12
	s_waitcnt lgkmcnt(1)
	v_mfma_f32_32x32x16_bf16 v[48:63], v[0:3], v[108:111], v[48:63]
	v_exp_f32_e32 v0, v14
	v_exp_f32_e32 v1, v15
	v_add_f32_e32 v64, v8, v64
	v_add_f32_e32 v65, v9, v65
	v_cvt_pk_bf16_f32 v88, v77, v78
	v_cvt_pk_bf16_f32 v89, v28, v29
	v_add_f32_e32 v6, v4, v30
	v_mfma_f32_32x32x16_bf16 v[32:47], v[68:71], v[100:103], v[32:47]
	v_add_f32_e32 v10, v5, v31
	v_mov_b32_e32 v16, 0
	v_add_f32_e32 v12, v7, v64
	v_add_f32_e32 v2, v11, v65
	v_add_f32_e32 v3, v0, v6
	v_add_f32_e32 v6, v1, v10
	v_mfma_f32_32x32x16_bf16 v[32:47], v[24:27], v[104:107], v[32:47]
	v_cvt_pk_bf16_f32 v95, v0, v1
	v_add_f32_e32 v0, v12, v2
	v_add_f32_e32 v1, v3, v6
	v_add_f32_e32 v0, v0, v1
	v_add_f32_e32 v150, 0, v0
	v_bitop3_b32 v0, v73, v74, 1 bitop3:0x6c
	v_lshlrev_b32_e32 v2, 4, v0
	v_bitop3_b32 v0, v138, v74, 2 bitop3:0x36
	v_lshlrev_b32_e32 v3, 4, v0
	v_bitop3_b32 v0, v138, v74, 4 bitop3:0x36
	v_cvt_pk_bf16_f32 v93, v4, v5
	v_lshlrev_b32_e32 v4, 4, v0
	v_bitop3_b32 v0, v138, v74, 6 bitop3:0x36
	v_lshlrev_b32_e32 v5, 4, v0
	v_and_b32_e32 v0, 7, v129
	v_cvt_pk_bf16_f32 v92, v8, v9
	v_cvt_pk_bf16_f32 v94, v7, v11
	v_lshlrev_b32_e32 v176, 4, v0
	v_lshlrev_b32_e32 v0, 1, v128
	s_waitcnt lgkmcnt(0)
	s_barrier
	v_mad_i64_i32 v[0:1], s[18:19], v0, s21, v[176:177]
	s_add_u32 s18, s9, s38
	v_readlane_b32 s9, v254, 53
	s_addc_u32 s19, s9, s39
	s_waitcnt lgkmcnt(0)
	v_mfma_f32_32x32x16_bf16 v[32:47], v[20:23], v[108:111], v[32:47]
	v_lshl_add_u64 v[136:137], s[18:19], 0, v[0:1]
	v_add_u32_e32 v144, v75, v2
	v_add_u32_e32 v141, v75, v3
	v_add_u32_e32 v140, v75, v4
	v_add_u32_e32 v139, v75, v5
	v_mov_b32_e32 v17, v16
	v_mov_b32_e32 v18, v16
	v_mov_b32_e32 v19, v16
	v_mov_b32_e32 v20, v16
	v_mov_b32_e32 v21, v16
	v_mov_b32_e32 v22, v16
	v_mov_b32_e32 v23, v16
	v_mov_b32_e32 v24, v16
	v_mov_b32_e32 v25, v16
	v_mov_b32_e32 v26, v16
	v_mov_b32_e32 v27, v16
	v_mov_b32_e32 v28, v16
	v_mov_b32_e32 v29, v16
	v_mov_b32_e32 v30, v16
	v_mov_b32_e32 v31, v16
	v_mov_b32_e32 v0, v16
	v_mov_b32_e32 v1, v16
	v_mov_b32_e32 v2, v16
	v_mov_b32_e32 v3, v16
	v_mov_b32_e32 v4, v16
	v_mov_b32_e32 v5, v16
	v_mov_b32_e32 v6, v16
	v_mov_b32_e32 v7, v16
	v_mov_b32_e32 v8, v16
	v_mov_b32_e32 v9, v16
	v_mov_b32_e32 v10, v16
	v_mov_b32_e32 v11, v16
	v_mov_b32_e32 v12, v16
	v_mov_b32_e32 v13, v16
	v_mov_b32_e32 v14, v16
	v_mov_b32_e32 v15, v16

	.amdhsa_kernel _Z14fwd_megakernel6Params
		.amdhsa_group_segment_fixed_size 139792
		.amdhsa_private_segment_fixed_size 0
		.amdhsa_kernarg_size 392
		.amdhsa_user_sgpr_count 2
		.amdhsa_user_sgpr_dispatch_ptr 0
		.amdhsa_user_sgpr_queue_ptr 0
		.amdhsa_user_sgpr_kernarg_segment_ptr 1
		.amdhsa_user_sgpr_dispatch_id 0
		.amdhsa_user_sgpr_kernarg_preload_length 0
		.amdhsa_user_sgpr_kernarg_preload_offset 0
		.amdhsa_user_sgpr_private_segment_size 0
		.amdhsa_uses_dynamic_stack 0
		.amdhsa_enable_private_segment 0
		.amdhsa_system_sgpr_workgroup_id_x 1
		.amdhsa_system_sgpr_workgroup_id_y 0
		.amdhsa_system_sgpr_workgroup_id_z 0
		.amdhsa_system_sgpr_workgroup_info 0
		.amdhsa_system_vgpr_workitem_id 2
		.amdhsa_next_free_vgpr 256
		.amdhsa_next_free_sgpr 100
		.amdhsa_accum_offset 256
		.amdhsa_reserve_vcc 1
		.amdhsa_float_round_mode_32 0
		.amdhsa_float_round_mode_16_64 0
		.amdhsa_float_denorm_mode_32 3
		.amdhsa_float_denorm_mode_16_64 3
		.amdhsa_dx10_clamp 1
		.amdhsa_ieee_mode 1
		.amdhsa_fp16_overflow 0
		.amdhsa_tg_split 0
		.amdhsa_exception_fp_ieee_invalid_op 0
		.amdhsa_exception_fp_denorm_src 0
		.amdhsa_exception_fp_ieee_div_zero 0
		.amdhsa_exception_fp_ieee_overflow 0
		.amdhsa_exception_fp_ieee_underflow 0
		.amdhsa_exception_fp_ieee_inexact 0
		.amdhsa_exception_int_div_zero 0
	.end_amdhsa_kernel

amdhsa.kernels:
  - .agpr_count:     0
    .args:
      - .offset:         0
        .size:           136
        .value_kind:     by_value
      - .offset:         136
        .size:           4
        .value_kind:     hidden_block_count_x
      - .offset:         140
        .size:           4
        .value_kind:     hidden_block_count_y
      - .offset:         144
        .size:           4
        .value_kind:     hidden_block_count_z
      - .offset:         148
        .size:           2
        .value_kind:     hidden_group_size_x
      - .offset:         150
        .size:           2
        .value_kind:     hidden_group_size_y
      - .offset:         152
        .size:           2
        .value_kind:     hidden_group_size_z
      - .offset:         154
        .size:           2
        .value_kind:     hidden_remainder_x
      - .offset:         156
        .size:           2
        .value_kind:     hidden_remainder_y
      - .offset:         158
        .size:           2
        .value_kind:     hidden_remainder_z
      - .offset:         176
        .size:           8
        .value_kind:     hidden_global_offset_x
      - .offset:         184
        .size:           8
        .value_kind:     hidden_global_offset_y
      - .offset:         192
        .size:           8
        .value_kind:     hidden_global_offset_z
      - .offset:         200
        .size:           2
        .value_kind:     hidden_grid_dims
      - .offset:         224
        .size:           8
        .value_kind:     hidden_multigrid_sync_arg
    .group_segment_fixed_size: 139792
    .kernarg_segment_align: 8
    .kernarg_segment_size: 392
    .language:       OpenCL C
    .language_version:
      - 2
      - 0
    .max_flat_workgroup_size: 512
    .name:           _Z14fwd_megakernel6Params
    .private_segment_fixed_size: 0
    .sgpr_count:     106
    .sgpr_spill_count: 146
    .symbol:         _Z14fwd_megakernel6Params.kd
    .uniform_work_group_size: 1
    .uses_dynamic_stack: false
    .vgpr_count:     256
    .vgpr_spill_count: 0
    .wavefront_size: 64
